# v45 + GEMM epilogues: per-row loads (MLP-up rstd source, residual vectors) issued in groups into free registers with counted waits instead of one vmcnt(0) per load
# speedup vs baseline: 1.0293x; 1.0180x over previous
; #define PG8_STAGE(bufoff, gbase, voff) do { _Pragma("unroll") for (int _i = 0; _i < 2; ++_i) \
;         __builtin_amdgcn_global_load_lds((const unsigned*)((const char*)(gbase) + (voff)[_i]), (LAS unsigned*)(lds + (bufoff) + ldsw + _i * 8192), 16, 0, 0); } while (0)
; #define PG8_LDA(dst, b, h) do { _Pragma("unroll") for (int m = 0; m < 4; ++m) _Pragma("unroll") for (int k = 0; k < 2; ++k) dst[m][k] = *(const LAS bf16x8*)(lds + PG8_SA(b, h) + aoff + m * 2048 + k * 1024); } while (0)
; #define PG8_LDB(dst, b, h) do { _Pragma("unroll") for (int n = 0; n < 2; ++n) _Pragma("unroll") for (int k = 0; k < 2; ++k) dst[n][k] = *(const LAS bf16x8*)(lds + PG8_SB(b, h) + boff + n * 2048 + k * 1024); } while (0)
; #define PG8_MMA(ai, bj, At, Bt) do { __builtin_amdgcn_s_setprio(1); _Pragma("unroll") for (int m = 0; m < 4; ++m) _Pragma("unroll") for (int n = 0; n < 2; ++n) _Pragma("unroll") for (int k = 0; k < 2; ++k) \
;         acc[ai][bj][m][n] = __builtin_amdgcn_mfma_f32_16x16x32_bf16(Bt[n][k], At[m][k], acc[ai][bj][m][n], 0, 0, 0); __builtin_amdgcn_s_setprio(0); } while (0)
; #define PG8_WAIT_L(n) asm volatile("s_waitcnt lgkmcnt(" #n ")" ::: "memory")
; #define PG8_BAR __builtin_amdgcn_s_barrier()
; #define PG8_SCHED __builtin_amdgcn_sched_barrier(0)
; template <class Epi>
; __device__ __forceinline__ void gemm_phase(LAS unsigned char* lds, const Gemm g, const StaticOrder& S, const Epi& E) {
;     ...
;         for (int t = 0; t < nt; t += 2) {
;             const bool last = (t == nt - 2);
;             const char* a1 = cA + (size_t)(t + 1) * kstep;
;             const char* a2 = last ? nA : cA + (size_t)(t + 2) * kstep; const char* b2 = last ? nB : cB + (size_t)(t + 2) * kstep;
;             const char* a3 = a2 + kstep; const char* b3 = b2 + kstep;
;             PG8_LDB(B0, 0, 0); PG8_SCHED; PG8_LDA(At, 0, 0); PG8_STAGE(PG8_SA(1, 1), a1 + hstep, voffA);
;             PG8_WAIT_L(8); PG8_BAR; PG8_WAIT_L(0); PG8_MMA(0, 0, At, B0); PG8_BAR; PG8_SCHED;
;             PG8_LDB(B1, 0, 1); PG8_STAGE(PG8_SB(0, 0), b2, voffB);
;             PG8_BAR; PG8_WAIT_L(0); PG8_MMA(0, 1, At, B1); PG8_BAR;
;             PG8_LDA(At, 0, 1); PG8_STAGE(PG8_SA(0, 0), a2, voffA);
;             PG8_BAR; PG8_WAIT_L(0); PG8_MMA(1, 0, At, B0); PG8_BAR; PG8_SCHED;
.LBB0_770:
	ds_read_b128 v[128:131], v161
	ds_read_b128 v[132:135], v161 offset:1024
	ds_read_b128 v[148:151], v161 offset:2048
	ds_read_b128 v[152:155], v161 offset:3072
	s_add_u32 s26, s24, 0xfff80080
	s_addc_u32 s27, s25, -1
	s_cmp_eq_u32 s47, 28
	s_cselect_b32 s29, s9, s27
	s_cselect_b32 s28, s15, s26
	s_cselect_b32 s27, s13, s46
	s_cselect_b32 s26, s23, s45
	v_lshl_add_u64 v[156:157], s[24:25], 0, v[140:141]
	s_add_i32 m0, s33, 0xc000
	ds_read_b128 v[164:167], v162
	ds_read_b128 v[168:171], v162 offset:1024
	ds_read_b128 v[180:183], v162 offset:2048
	ds_read_b128 v[184:187], v162 offset:3072
	ds_read_b128 v[188:191], v162 offset:4096
	ds_read_b128 v[192:195], v162 offset:5120
	ds_read_b128 v[196:199], v162 offset:6144
	ds_read_b128 v[200:203], v162 offset:7168
	global_load_lds_dwordx4 v[156:157], off
	v_lshl_add_u64 v[156:157], s[24:25], 0, v[142:143]
	s_add_i32 m0, s33, 0xe000
	s_nop 0
	global_load_lds_dwordx4 v[156:157], off
	s_waitcnt lgkmcnt(8)
	s_barrier
	s_waitcnt lgkmcnt(0)
	s_setprio 1
	s_waitcnt lgkmcnt(0)
	v_mfma_f32_16x16x32_bf16 v[124:127], v[128:131], v[164:167], v[124:127]
	v_mfma_f32_16x16x32_bf16 v[120:123], v[148:151], v[164:167], v[120:123]
	v_mfma_f32_16x16x32_bf16 v[108:111], v[128:131], v[180:183], v[108:111]
	v_mfma_f32_16x16x32_bf16 v[104:107], v[148:151], v[180:183], v[104:107]
	v_mfma_f32_16x16x32_bf16 v[92:95], v[128:131], v[188:191], v[92:95]
	v_mfma_f32_16x16x32_bf16 v[88:91], v[148:151], v[188:191], v[88:91]
	v_mfma_f32_16x16x32_bf16 v[76:79], v[128:131], v[196:199], v[76:79]
	v_mfma_f32_16x16x32_bf16 v[72:75], v[148:151], v[196:199], v[72:75]
	v_mfma_f32_16x16x32_bf16 v[124:127], v[132:135], v[168:171], v[124:127]
	v_mfma_f32_16x16x32_bf16 v[120:123], v[152:155], v[168:171], v[120:123]
	v_mfma_f32_16x16x32_bf16 v[108:111], v[132:135], v[184:187], v[108:111]
	v_mfma_f32_16x16x32_bf16 v[104:107], v[152:155], v[184:187], v[104:107]
	v_mfma_f32_16x16x32_bf16 v[92:95], v[132:135], v[192:195], v[92:95]
	v_mfma_f32_16x16x32_bf16 v[88:91], v[152:155], v[192:195], v[88:91]
	v_mfma_f32_16x16x32_bf16 v[76:79], v[132:135], v[200:203], v[76:79]
	v_mfma_f32_16x16x32_bf16 v[72:75], v[152:155], v[200:203], v[72:75]
	s_setprio 0
	s_barrier
	s_add_i32 s48, s43, s3
	v_lshl_add_u64 v[156:157], s[26:27], 0, v[136:137]
	s_mov_b32 m0, s48
	ds_read_b128 v[204:207], v163
	ds_read_b128 v[208:211], v163 offset:1024
	ds_read_b128 v[212:215], v163 offset:2048
	ds_read_b128 v[216:219], v163 offset:3072
	global_load_lds_dwordx4 v[156:157], off
	v_lshl_add_u64 v[172:173], s[26:27], 0, v[138:139]
	s_add_i32 m0, s48, 0x2000
	s_nop 0
	global_load_lds_dwordx4 v[172:173], off
	s_barrier
	s_waitcnt lgkmcnt(0)
	s_setprio 1
	s_waitcnt lgkmcnt(0)
	v_mfma_f32_16x16x32_bf16 v[116:119], v[204:207], v[164:167], v[116:119]
	v_mfma_f32_16x16x32_bf16 v[112:115], v[212:215], v[164:167], v[112:115]
	v_mfma_f32_16x16x32_bf16 v[100:103], v[204:207], v[180:183], v[100:103]
	v_mfma_f32_16x16x32_bf16 v[96:99], v[212:215], v[180:183], v[96:99]
	v_mfma_f32_16x16x32_bf16 v[84:87], v[204:207], v[188:191], v[84:87]
	v_mfma_f32_16x16x32_bf16 v[80:83], v[212:215], v[188:191], v[80:83]
	v_mfma_f32_16x16x32_bf16 v[68:71], v[204:207], v[196:199], v[68:71]
	v_mfma_f32_16x16x32_bf16 v[64:67], v[212:215], v[196:199], v[64:67]
	v_mfma_f32_16x16x32_bf16 v[116:119], v[208:211], v[168:171], v[116:119]
	v_mfma_f32_16x16x32_bf16 v[112:115], v[216:219], v[168:171], v[112:115]
	v_mfma_f32_16x16x32_bf16 v[100:103], v[208:211], v[184:187], v[100:103]
	v_mfma_f32_16x16x32_bf16 v[96:99], v[216:219], v[184:187], v[96:99]
	v_mfma_f32_16x16x32_bf16 v[84:87], v[208:211], v[192:195], v[84:87]
	v_mfma_f32_16x16x32_bf16 v[80:83], v[216:219], v[192:195], v[80:83]
	v_mfma_f32_16x16x32_bf16 v[68:71], v[208:211], v[200:203], v[68:71]
	v_mfma_f32_16x16x32_bf16 v[64:67], v[216:219], v[200:203], v[64:67]
	s_setprio 0
	s_mov_b32 m0, s33
	v_lshl_add_u64 v[176:177], s[28:29], 0, v[136:137]
	s_barrier
	ds_read_b128 v[164:167], v162 offset:16384
	ds_read_b128 v[168:171], v162 offset:17408
	ds_read_b128 v[180:183], v162 offset:18432
	ds_read_b128 v[184:187], v162 offset:19456
	ds_read_b128 v[188:191], v162 offset:20480
	ds_read_b128 v[192:195], v162 offset:21504
	ds_read_b128 v[196:199], v162 offset:22528
	ds_read_b128 v[200:203], v162 offset:23552
	global_load_lds_dwordx4 v[176:177], off
	v_lshl_add_u64 v[220:221], s[28:29], 0, v[138:139]
	s_mov_b32 m0, s34
	s_nop 0
	global_load_lds_dwordx4 v[220:221], off
	s_barrier
	s_waitcnt lgkmcnt(0)
	s_setprio 1
	s_waitcnt lgkmcnt(0)
	v_mfma_f32_16x16x32_bf16 v[60:63], v[128:131], v[164:167], v[60:63]
	v_mfma_f32_16x16x32_bf16 v[56:59], v[148:151], v[164:167], v[56:59]
	v_mfma_f32_16x16x32_bf16 v[44:47], v[128:131], v[180:183], v[44:47]
	v_mfma_f32_16x16x32_bf16 v[40:43], v[148:151], v[180:183], v[40:43]
	v_mfma_f32_16x16x32_bf16 v[28:31], v[128:131], v[188:191], v[28:31]
	v_mfma_f32_16x16x32_bf16 v[24:27], v[148:151], v[188:191], v[24:27]
	v_mfma_f32_16x16x32_bf16 v[12:15], v[128:131], v[196:199], v[12:15]
	v_mfma_f32_16x16x32_bf16 v[8:11], v[148:151], v[196:199], v[8:11]
	v_mfma_f32_16x16x32_bf16 v[60:63], v[132:135], v[168:171], v[60:63]
	v_mfma_f32_16x16x32_bf16 v[56:59], v[152:155], v[168:171], v[56:59]
	v_mfma_f32_16x16x32_bf16 v[44:47], v[132:135], v[184:187], v[44:47]
	v_mfma_f32_16x16x32_bf16 v[40:43], v[152:155], v[184:187], v[40:43]
	v_mfma_f32_16x16x32_bf16 v[28:31], v[132:135], v[192:195], v[28:31]
	v_mfma_f32_16x16x32_bf16 v[24:27], v[152:155], v[192:195], v[24:27]
	v_mfma_f32_16x16x32_bf16 v[12:15], v[132:135], v[200:203], v[12:15]
	v_mfma_f32_16x16x32_bf16 v[8:11], v[152:155], v[200:203], v[8:11]
	s_setprio 0
	s_barrier
; #define PG8_STAGE(bufoff, gbase, voff) do { _Pragma("unroll") for (int _i = 0; _i < 2; ++_i) \
;         __builtin_amdgcn_global_load_lds((const unsigned*)((const char*)(gbase) + (voff)[_i]), (LAS unsigned*)(lds + (bufoff) + ldsw + _i * 8192), 16, 0, 0); } while (0)
; #define PG8_LDA(dst, b, h) do { _Pragma("unroll") for (int m = 0; m < 4; ++m) _Pragma("unroll") for (int k = 0; k < 2; ++k) dst[m][k] = *(const LAS bf16x8*)(lds + PG8_SA(b, h) + aoff + m * 2048 + k * 1024); } while (0)
; #define PG8_LDB(dst, b, h) do { _Pragma("unroll") for (int n = 0; n < 2; ++n) _Pragma("unroll") for (int k = 0; k < 2; ++k) dst[n][k] = *(const LAS bf16x8*)(lds + PG8_SB(b, h) + boff + n * 2048 + k * 1024); } while (0)
; #define PG8_MMA(ai, bj, At, Bt) do { __builtin_amdgcn_s_setprio(1); _Pragma("unroll") for (int m = 0; m < 4; ++m) _Pragma("unroll") for (int n = 0; n < 2; ++n) _Pragma("unroll") for (int k = 0; k < 2; ++k) \
;         acc[ai][bj][m][n] = __builtin_amdgcn_mfma_f32_16x16x32_bf16(Bt[n][k], At[m][k], acc[ai][bj][m][n], 0, 0, 0); __builtin_amdgcn_s_setprio(0); } while (0)
; #define PG8_WAIT_V(n) asm volatile("s_waitcnt vmcnt(" #n ")" ::: "memory")
; #define PG8_WAIT_L(n) asm volatile("s_waitcnt lgkmcnt(" #n ")" ::: "memory")
; #define PG8_BAR __builtin_amdgcn_s_barrier()
; #define PG8_SCHED __builtin_amdgcn_sched_barrier(0)
; template <class Epi>
; __device__ __forceinline__ void gemm_phase(LAS unsigned char* lds, const Gemm g, const StaticOrder& S, const Epi& E) {
;     ...
;             PG8_STAGE(PG8_SB(0, 1), b2 + hstep, voffB);
;             PG8_WAIT_V(6); PG8_BAR; PG8_MMA(1, 1, At, B1); PG8_BAR;
;             PG8_LDB(B0, 1, 0); PG8_SCHED; PG8_LDA(At, 1, 0); PG8_STAGE(PG8_SA(0, 1), a2 + hstep, voffA);
;             PG8_WAIT_L(8); PG8_BAR; PG8_WAIT_L(0); PG8_MMA(0, 0, At, B0); PG8_BAR; PG8_SCHED;
;             PG8_LDB(B1, 1, 1); PG8_STAGE(PG8_SB(1, 0), b3, voffB);
;             PG8_BAR; PG8_WAIT_L(0); PG8_MMA(0, 1, At, B1); PG8_BAR;
;             PG8_LDA(At, 1, 1); PG8_STAGE(PG8_SA(1, 0), a3, voffA);
;             PG8_BAR; PG8_WAIT_L(0); PG8_MMA(1, 0, At, B0); PG8_BAR; PG8_SCHED;
	s_add_u32 s48, s26, 0x80000
	s_addc_u32 s49, s27, 0
	s_add_i32 s50, s44, s3
	v_lshl_add_u64 v[128:129], s[48:49], 0, v[136:137]
	s_mov_b32 m0, s50
	s_nop 0
	global_load_lds_dwordx4 v[128:129], off
	v_lshl_add_u64 v[128:129], s[48:49], 0, v[138:139]
	s_add_i32 m0, s50, 0x2000
	s_nop 0
	global_load_lds_dwordx4 v[128:129], off
	s_waitcnt vmcnt(6)
	s_barrier
	s_setprio 1
	v_mfma_f32_16x16x32_bf16 v[52:55], v[204:207], v[164:167], v[52:55]
	v_mfma_f32_16x16x32_bf16 v[48:51], v[212:215], v[164:167], v[48:51]
	v_mfma_f32_16x16x32_bf16 v[36:39], v[204:207], v[180:183], v[36:39]
	v_mfma_f32_16x16x32_bf16 v[32:35], v[212:215], v[180:183], v[32:35]
	v_mfma_f32_16x16x32_bf16 v[20:23], v[204:207], v[188:191], v[20:23]
	v_mfma_f32_16x16x32_bf16 v[16:19], v[212:215], v[188:191], v[16:19]
	v_mfma_f32_16x16x32_bf16 v[4:7], v[204:207], v[196:199], v[4:7]
	v_mfma_f32_16x16x32_bf16 v[0:3], v[212:215], v[196:199], v[0:3]
	v_mfma_f32_16x16x32_bf16 v[52:55], v[208:211], v[168:171], v[52:55]
	v_mfma_f32_16x16x32_bf16 v[48:51], v[216:219], v[168:171], v[48:51]
	v_mfma_f32_16x16x32_bf16 v[36:39], v[208:211], v[184:187], v[36:39]
	v_mfma_f32_16x16x32_bf16 v[32:35], v[216:219], v[184:187], v[32:35]
	v_mfma_f32_16x16x32_bf16 v[20:23], v[208:211], v[192:195], v[20:23]
	v_mfma_f32_16x16x32_bf16 v[16:19], v[216:219], v[192:195], v[16:19]
	v_mfma_f32_16x16x32_bf16 v[4:7], v[208:211], v[200:203], v[4:7]
	v_mfma_f32_16x16x32_bf16 v[0:3], v[216:219], v[200:203], v[0:3]
	s_setprio 0
	s_add_i32 s48, 0, 0x18000
	v_add_u32_e32 v152, s48, v159
	s_barrier
	ds_read_b128 v[128:131], v152
	ds_read_b128 v[132:135], v152 offset:1024
	ds_read_b128 v[148:151], v152 offset:2048
	ds_read_b128 v[152:155], v152 offset:3072
	s_add_u32 s28, s28, 0x80000
	s_addc_u32 s29, s29, 0
	s_mov_b32 m0, s35
	v_lshl_add_u64 v[204:205], s[28:29], 0, v[136:137]
	ds_read_b128 v[164:167], v162 offset:32768
	ds_read_b128 v[168:171], v162 offset:33792
	ds_read_b128 v[180:183], v162 offset:34816
	ds_read_b128 v[184:187], v162 offset:35840
	ds_read_b128 v[188:191], v162 offset:36864
	ds_read_b128 v[192:195], v162 offset:37888
	ds_read_b128 v[196:199], v162 offset:38912
	ds_read_b128 v[200:203], v162 offset:39936
	global_load_lds_dwordx4 v[204:205], off
	v_lshl_add_u64 v[204:205], s[28:29], 0, v[138:139]
	s_mov_b32 m0, s36
	s_nop 0
	global_load_lds_dwordx4 v[204:205], off
	s_waitcnt lgkmcnt(8)
	s_barrier
	s_waitcnt lgkmcnt(0)
	s_setprio 1
	s_waitcnt lgkmcnt(0)
	v_mfma_f32_16x16x32_bf16 v[124:127], v[128:131], v[164:167], v[124:127]
	v_mfma_f32_16x16x32_bf16 v[120:123], v[148:151], v[164:167], v[120:123]
	v_mfma_f32_16x16x32_bf16 v[108:111], v[128:131], v[180:183], v[108:111]
	v_mfma_f32_16x16x32_bf16 v[104:107], v[148:151], v[180:183], v[104:107]
	v_mfma_f32_16x16x32_bf16 v[92:95], v[128:131], v[188:191], v[92:95]
	v_mfma_f32_16x16x32_bf16 v[88:91], v[148:151], v[188:191], v[88:91]
	v_mfma_f32_16x16x32_bf16 v[76:79], v[128:131], v[196:199], v[76:79]
	v_mfma_f32_16x16x32_bf16 v[72:75], v[148:151], v[196:199], v[72:75]
	v_mfma_f32_16x16x32_bf16 v[124:127], v[132:135], v[168:171], v[124:127]
	v_mfma_f32_16x16x32_bf16 v[120:123], v[152:155], v[168:171], v[120:123]
	v_mfma_f32_16x16x32_bf16 v[108:111], v[132:135], v[184:187], v[108:111]
	v_mfma_f32_16x16x32_bf16 v[104:107], v[152:155], v[184:187], v[104:107]
	v_mfma_f32_16x16x32_bf16 v[92:95], v[132:135], v[192:195], v[92:95]
	v_mfma_f32_16x16x32_bf16 v[88:91], v[152:155], v[192:195], v[88:91]
	v_mfma_f32_16x16x32_bf16 v[76:79], v[132:135], v[200:203], v[76:79]
	v_mfma_f32_16x16x32_bf16 v[72:75], v[152:155], v[200:203], v[72:75]
	s_setprio 0
	s_barrier
	s_add_i32 s28, 0, 0x1c000
	s_add_i32 s29, s48, s3
	v_add_u32_e32 v174, s28, v159
	v_lshl_add_u64 v[156:157], v[156:157], 0, s[0:1]
	s_mov_b32 m0, s29
	ds_read_b128 v[204:207], v174
	ds_read_b128 v[208:211], v174 offset:1024
	ds_read_b128 v[212:215], v174 offset:2048
	ds_read_b128 v[216:219], v174 offset:3072
	global_load_lds_dwordx4 v[156:157], off
	v_lshl_add_u64 v[156:157], v[172:173], 0, s[0:1]
	s_add_i32 m0, s29, 0x2000
	s_nop 0
	global_load_lds_dwordx4 v[156:157], off
	s_barrier
	s_waitcnt lgkmcnt(0)
	s_setprio 1
	s_waitcnt lgkmcnt(0)
	v_mfma_f32_16x16x32_bf16 v[116:119], v[204:207], v[164:167], v[116:119]
	v_mfma_f32_16x16x32_bf16 v[112:115], v[212:215], v[164:167], v[112:115]
	v_mfma_f32_16x16x32_bf16 v[100:103], v[204:207], v[180:183], v[100:103]
	v_mfma_f32_16x16x32_bf16 v[96:99], v[212:215], v[180:183], v[96:99]
	v_mfma_f32_16x16x32_bf16 v[84:87], v[204:207], v[188:191], v[84:87]
	v_mfma_f32_16x16x32_bf16 v[80:83], v[212:215], v[188:191], v[80:83]
	v_mfma_f32_16x16x32_bf16 v[68:71], v[204:207], v[196:199], v[68:71]
	v_mfma_f32_16x16x32_bf16 v[64:67], v[212:215], v[196:199], v[64:67]
	v_mfma_f32_16x16x32_bf16 v[116:119], v[208:211], v[168:171], v[116:119]
	v_mfma_f32_16x16x32_bf16 v[112:115], v[216:219], v[168:171], v[112:115]
	v_mfma_f32_16x16x32_bf16 v[100:103], v[208:211], v[184:187], v[100:103]
	v_mfma_f32_16x16x32_bf16 v[96:99], v[216:219], v[184:187], v[96:99]
	v_mfma_f32_16x16x32_bf16 v[84:87], v[208:211], v[192:195], v[84:87]
	v_mfma_f32_16x16x32_bf16 v[80:83], v[216:219], v[192:195], v[80:83]
	v_mfma_f32_16x16x32_bf16 v[68:71], v[208:211], v[200:203], v[68:71]
	v_mfma_f32_16x16x32_bf16 v[64:67], v[216:219], v[200:203], v[64:67]
	s_setprio 0
	s_mov_b32 m0, s38
	v_lshl_add_u64 v[156:157], v[176:177], 0, s[0:1]
	s_barrier
	ds_read_b128 v[164:167], v162 offset:49152
	ds_read_b128 v[168:171], v162 offset:50176
	ds_read_b128 v[180:183], v162 offset:51200
	ds_read_b128 v[184:187], v162 offset:52224
	ds_read_b128 v[188:191], v162 offset:53248
	ds_read_b128 v[192:195], v162 offset:54272
	ds_read_b128 v[196:199], v162 offset:55296
	ds_read_b128 v[200:203], v162 offset:56320
	global_load_lds_dwordx4 v[156:157], off
	v_lshl_add_u64 v[156:157], v[220:221], 0, s[0:1]
	s_mov_b32 m0, s39
	s_nop 0
	global_load_lds_dwordx4 v[156:157], off
	s_barrier
; DI unsigned pk2(float a, float b) { f32x2 v = {a, b}; hbf2 r = __builtin_convertvector(v, hbf2); return __builtin_bit_cast(unsigned, r); }
; #define PG8_STAGE(bufoff, gbase, voff) do { _Pragma("unroll") for (int _i = 0; _i < 2; ++_i) \
;         __builtin_amdgcn_global_load_lds((const unsigned*)((const char*)(gbase) + (voff)[_i]), (LAS unsigned*)(lds + (bufoff) + ldsw + _i * 8192), 16, 0, 0); } while (0)
; #define PG8_MMA(ai, bj, At, Bt) do { __builtin_amdgcn_s_setprio(1); _Pragma("unroll") for (int m = 0; m < 4; ++m) _Pragma("unroll") for (int n = 0; n < 2; ++n) _Pragma("unroll") for (int k = 0; k < 2; ++k) \
;         acc[ai][bj][m][n] = __builtin_amdgcn_mfma_f32_16x16x32_bf16(Bt[n][k], At[m][k], acc[ai][bj][m][n], 0, 0, 0); __builtin_amdgcn_s_setprio(0); } while (0)
; template <class Epi>
; __device__ __forceinline__ void gemm_phase(LAS unsigned char* lds, const Gemm g, const StaticOrder& S, const Epi& E) {
;     ...
;             PG8_STAGE(PG8_SB(1, 1), b3 + hstep, voffB);
;             PG8_WAIT_V(6); PG8_BAR; PG8_MMA(1, 1, At, B1); PG8_BAR;
;         }
;     DI void operator()(const f32x4 (&acc)[2][2][4][2], const Unit& u, int wr, int wc, int fr, int fq) const {
;         const int row0 = u.pm * 256 + wr * 64 + fr, col0 = u.pn * 256 + wc * 32 + 4 * fq;
; #pragma unroll
;         for (int ai = 0; ai < 2; ++ai)
; #pragma unroll
;             for (int m = 0; m < 4; ++m) {
;                 const int r = row0 + ai * 128 + m * 16;
;                 const float* rp;
;                 if (MODE == 0) rp = x + (size_t)r * 1024;
;                 else rp = h + (size_t)r * 1024;
;                 float sq = 0.f;
; #pragma unroll
;                 for (int bj = 0; bj < 2; ++bj)
; #pragma unroll
;                     for (int n = 0; n < 2; ++n) {
;                         const int c = col0 + bj * 128 + n * 16;
;                         f32x4 rv = rp ? *(const f32x4*)(rp + c) : (f32x4){0.f, 0.f, 0.f, 0.f};
;                         f32x4 v = acc[ai][bj][m][n] + rv;
;                         *(f32x4*)(h + (size_t)r * 1024 + c) = v;
;                         if (WRITE_HB) {
;                             u32x2 w; w.x = pk2(v[0], v[1]); w.y = pk2(v[2], v[3]);
;                             *(u32x2*)(hb + (size_t)r * 1024 + c) = w;
;                         }
;                         sq += v[0] * v[0] + v[1] * v[1] + v[2] * v[2] + v[3] * v[3];
	s_waitcnt lgkmcnt(0)
	s_setprio 1
	s_waitcnt lgkmcnt(0)
	v_mfma_f32_16x16x32_bf16 v[60:63], v[128:131], v[164:167], v[60:63]
	v_mfma_f32_16x16x32_bf16 v[56:59], v[148:151], v[164:167], v[56:59]
	v_mfma_f32_16x16x32_bf16 v[44:47], v[128:131], v[180:183], v[44:47]
	v_mfma_f32_16x16x32_bf16 v[40:43], v[148:151], v[180:183], v[40:43]
	v_mfma_f32_16x16x32_bf16 v[28:31], v[128:131], v[188:191], v[28:31]
	v_mfma_f32_16x16x32_bf16 v[24:27], v[148:151], v[188:191], v[24:27]
	v_mfma_f32_16x16x32_bf16 v[12:15], v[128:131], v[196:199], v[12:15]
	v_mfma_f32_16x16x32_bf16 v[8:11], v[148:151], v[196:199], v[8:11]
	v_mfma_f32_16x16x32_bf16 v[60:63], v[132:135], v[168:171], v[60:63]
	v_mfma_f32_16x16x32_bf16 v[56:59], v[152:155], v[168:171], v[56:59]
	v_mfma_f32_16x16x32_bf16 v[44:47], v[132:135], v[184:187], v[44:47]
	v_mfma_f32_16x16x32_bf16 v[40:43], v[152:155], v[184:187], v[40:43]
	v_mfma_f32_16x16x32_bf16 v[28:31], v[132:135], v[192:195], v[28:31]
	v_mfma_f32_16x16x32_bf16 v[24:27], v[152:155], v[192:195], v[24:27]
	v_mfma_f32_16x16x32_bf16 v[12:15], v[132:135], v[200:203], v[12:15]
	v_mfma_f32_16x16x32_bf16 v[8:11], v[152:155], v[200:203], v[8:11]
	s_setprio 0
	s_barrier
	s_add_u32 s26, s26, 0x80080
	s_addc_u32 s27, s27, 0
	s_add_i32 s28, s28, s3
	v_lshl_add_u64 v[128:129], s[26:27], 0, v[136:137]
	s_mov_b32 m0, s28
	s_nop 0
	global_load_lds_dwordx4 v[128:129], off
	v_lshl_add_u64 v[128:129], s[26:27], 0, v[138:139]
	s_add_i32 m0, s28, 0x2000
	s_nop 0
	global_load_lds_dwordx4 v[128:129], off
	s_waitcnt vmcnt(6)
	s_barrier
	s_setprio 1
	v_mfma_f32_16x16x32_bf16 v[52:55], v[204:207], v[164:167], v[52:55]
	v_mfma_f32_16x16x32_bf16 v[48:51], v[212:215], v[164:167], v[48:51]
	v_mfma_f32_16x16x32_bf16 v[36:39], v[204:207], v[180:183], v[36:39]
	v_mfma_f32_16x16x32_bf16 v[32:35], v[212:215], v[180:183], v[32:35]
	v_mfma_f32_16x16x32_bf16 v[20:23], v[204:207], v[188:191], v[20:23]
	v_mfma_f32_16x16x32_bf16 v[16:19], v[212:215], v[188:191], v[16:19]
	v_mfma_f32_16x16x32_bf16 v[4:7], v[204:207], v[196:199], v[4:7]
	v_mfma_f32_16x16x32_bf16 v[0:3], v[212:215], v[196:199], v[0:3]
	v_mfma_f32_16x16x32_bf16 v[52:55], v[208:211], v[168:171], v[52:55]
	v_mfma_f32_16x16x32_bf16 v[48:51], v[216:219], v[168:171], v[48:51]
	v_mfma_f32_16x16x32_bf16 v[36:39], v[208:211], v[184:187], v[36:39]
	v_mfma_f32_16x16x32_bf16 v[32:35], v[216:219], v[184:187], v[32:35]
	v_mfma_f32_16x16x32_bf16 v[20:23], v[208:211], v[192:195], v[20:23]
	v_mfma_f32_16x16x32_bf16 v[16:19], v[216:219], v[192:195], v[16:19]
	v_mfma_f32_16x16x32_bf16 v[4:7], v[208:211], v[200:203], v[4:7]
	v_mfma_f32_16x16x32_bf16 v[0:3], v[216:219], v[200:203], v[0:3]
	s_setprio 0
	s_add_i32 s47, s47, 2
	s_add_u32 s24, s24, 0x100
	s_addc_u32 s25, s25, 0
	s_add_u32 s45, s45, 0x100
	s_addc_u32 s46, s46, 0
	s_cmp_gt_u32 s47, 29
	s_barrier
	s_cbranch_scc0 .LBB0_770
	v_lshl_add_u32 v150, s8, 8, v158
	v_ashrrev_i32_e32 v151, 31, v150
	v_lshl_or_b32 v148, s22, 8, v160
	v_lshlrev_b64 v[128:129], 12, v[150:151]
	v_lshl_add_u64 v[130:131], s[56:57], 0, v[128:129]
	v_ashrrev_i32_e32 v149, 31, v148
	v_cndmask_b32_e64 v129, 0, 1, s[10:11]
	v_mov_b32_e32 v128, 0
	v_cmp_ne_u32_e64 s[8:9], 1, v129
	s_andn2_b64 vcc, exec, s[10:11]
	v_lshl_add_u64 v[156:157], v[148:149], 2, v[130:131]
	v_mov_b32_e32 v130, 0
	v_mov_b32_e32 v131, 0
	v_mov_b32_e32 v132, 0
	v_mov_b32_e32 v133, 0
	s_cbranch_vccnz .LBB0_773
	global_load_dwordx4 v[180:183], v[156:157], off
	global_load_dwordx4 v[184:187], v[156:157], off offset:64
	global_load_dwordx4 v[188:191], v[156:157], off offset:512
	global_load_dwordx4 v[192:195], v[156:157], off offset:576
.LBB0_773:
	v_lshlrev_b64 v[134:135], 10, v[150:151]
	s_waitcnt vmcnt(3)
	v_pk_add_f32 v[126:127], v[126:127], v[182:183]
	v_pk_add_f32 v[124:125], v[124:125], v[180:181]
	v_lshl_add_u64 v[130:131], v[134:135], 2, s[66:67]
	v_lshl_add_u64 v[132:133], v[134:135], 1, s[68:69]
	v_lshl_add_u64 v[152:153], v[148:149], 2, v[130:131]
	v_cvt_pk_bf16_f32 v130, v124, v125
	v_cvt_pk_bf16_f32 v131, v126, v127
	v_lshl_add_u64 v[154:155], v[148:149], 1, v[132:133]
	global_store_dwordx4 v[152:153], v[124:127], off
	global_store_dwordx2 v[154:155], v[130:131], off
	s_and_b64 vcc, exec, s[8:9]
	v_mov_b32_e32 v129, 0
	v_mov_b32_e32 v130, 0
	v_mov_b32_e32 v131, 0
	s_cbranch_vccnz .LBB0_775
	s_nop 0
.LBB0_775:
	s_waitcnt vmcnt(4)
	v_pk_add_f32 v[130:131], v[122:123], v[186:187]
	v_pk_add_f32 v[128:129], v[120:121], v[184:185]
	v_cvt_pk_bf16_f32 v121, v130, v131
	v_cvt_pk_bf16_f32 v120, v128, v129
	global_store_dwordx4 v[152:153], v[128:131], off offset:64
	global_store_dwordx2 v[154:155], v[120:121], off offset:32
	v_mov_b32_e32 v120, 0
	s_and_b64 vcc, exec, s[8:9]
	v_mov_b32_e32 v132, 0
	v_mov_b32_e32 v133, 0
	v_mov_b32_e32 v134, 0
	v_mov_b32_e32 v135, 0
	s_cbranch_vccnz .LBB0_777
	s_nop 0
.LBB0_777:
	s_waitcnt vmcnt(5)
	v_pk_add_f32 v[118:119], v[118:119], v[190:191]
	v_pk_add_f32 v[116:117], v[116:117], v[188:189]
	v_cvt_pk_bf16_f32 v123, v118, v119
	v_cvt_pk_bf16_f32 v122, v116, v117
	global_store_dwordx4 v[152:153], v[116:119], off offset:512
	global_store_dwordx2 v[154:155], v[122:123], off offset:256
	s_and_b64 vcc, exec, s[8:9]
	v_mov_b32_e32 v121, 0
	v_mov_b32_e32 v122, 0
	v_mov_b32_e32 v123, 0
	s_cbranch_vccnz .LBB0_779
	s_nop 0
; DI unsigned pk2(float a, float b) { f32x2 v = {a, b}; hbf2 r = __builtin_convertvector(v, hbf2); return __builtin_bit_cast(unsigned, r); }
; DI float sum_x16_x32(float x) { return sum_x32(sum_x16(x)); }
;     DI void operator()(const f32x4 (&acc)[2][2][4][2], const Unit& u, int wr, int wc, int fr, int fq) const {
;     ...
;             for (int m = 0; m < 4; ++m) {
;                 const int r = row0 + ai * 128 + m * 16;
;                 const float* rp;
;                 if (MODE == 0) rp = x + (size_t)r * 1024;
;                 else rp = h + (size_t)r * 1024;
;                 float sq = 0.f;
; #pragma unroll
;                 for (int bj = 0; bj < 2; ++bj)
; #pragma unroll
;                     for (int n = 0; n < 2; ++n) {
;                         const int c = col0 + bj * 128 + n * 16;
;                         f32x4 rv = rp ? *(const f32x4*)(rp + c) : (f32x4){0.f, 0.f, 0.f, 0.f};
;                         f32x4 v = acc[ai][bj][m][n] + rv;
;                         *(f32x4*)(h + (size_t)r * 1024 + c) = v;
;                         if (WRITE_HB) {
;                             u32x2 w; w.x = pk2(v[0], v[1]); w.y = pk2(v[2], v[3]);
;                             *(u32x2*)(hb + (size_t)r * 1024 + c) = w;
;                         }
;                         sq += v[0] * v[0] + v[1] * v[1] + v[2] * v[2] + v[3] * v[3];
;                     }
;                 sq = sum_x16_x32(sq);
;                 if (fq == 0) atomicAdd(ss + r, sq);
.LBB0_779:
	v_mul_f32_e32 v125, v125, v125
	v_fmac_f32_e32 v125, v124, v124
	v_mul_f32_e32 v124, v129, v129
	v_fmac_f32_e32 v124, v128, v128
	v_mul_f32_e32 v117, v117, v117
	s_waitcnt vmcnt(6)
	v_pk_add_f32 v[114:115], v[114:115], v[194:195]
	v_pk_add_f32 v[112:113], v[112:113], v[192:193]
	v_fmac_f32_e32 v125, v126, v126
	v_fmac_f32_e32 v124, v130, v130
	v_fmac_f32_e32 v117, v116, v116
	global_store_dwordx4 v[152:153], v[112:115], off offset:576
	v_cvt_pk_bf16_f32 v116, v112, v113
	v_fmac_f32_e32 v125, v127, v127
	v_mul_f32_e32 v113, v113, v113
	v_fmac_f32_e32 v124, v131, v131
	v_fmac_f32_e32 v117, v118, v118
	v_fmac_f32_e32 v113, v112, v112
	v_add_f32_e32 v124, v125, v124
	v_fmac_f32_e32 v117, v119, v119
	v_fmac_f32_e32 v113, v114, v114
	v_add_f32_e32 v118, v124, v117
	v_fmac_f32_e32 v113, v115, v115
	v_add_f32_e32 v112, v118, v113
	v_mov_b32_e32 v113, v112
	s_nop 1
	v_permlane16_swap_b32_e32 v112, v113
	v_add_f32_e32 v112, v112, v113
	v_mov_b32_e32 v113, v112
	v_cvt_pk_bf16_f32 v117, v114, v115
	s_nop 0
	v_permlane32_swap_b32_e32 v112, v113
	global_store_dwordx2 v[154:155], v[116:117], off offset:288
	s_and_saveexec_b64 s[22:23], s[4:5]
	s_cbranch_execz .LBB0_781
	v_lshl_add_u64 v[114:115], v[150:151], 2, s[94:95]
	v_add_f32_e32 v112, v112, v113
	global_atomic_add_f32 v[114:115], v112, off
.LBB0_781:
	s_or_b64 exec, exec, s[22:23]
	v_or_b32_e32 v120, 16, v150
	v_ashrrev_i32_e32 v121, 31, v120
	v_lshlrev_b64 v[112:113], 12, v[120:121]
	v_lshl_add_u64 v[114:115], s[56:57], 0, v[112:113]
	v_mov_b32_e32 v112, 0
	s_and_b64 vcc, exec, s[8:9]
	v_lshl_add_u64 v[126:127], v[148:149], 2, v[114:115]
	v_mov_b32_e32 v114, 0
	v_mov_b32_e32 v115, 0
	v_mov_b32_e32 v116, 0
	v_mov_b32_e32 v117, 0
	s_cbranch_vccnz .LBB0_783
	global_load_dwordx4 v[180:183], v[126:127], off
	global_load_dwordx4 v[184:187], v[126:127], off offset:64
	global_load_dwordx4 v[188:191], v[126:127], off offset:512
	global_load_dwordx4 v[192:195], v[126:127], off offset:576
.LBB0_783:
	v_lshlrev_b64 v[118:119], 10, v[120:121]
	s_waitcnt vmcnt(3)
	v_pk_add_f32 v[110:111], v[110:111], v[182:183]
	v_pk_add_f32 v[108:109], v[108:109], v[180:181]
	v_lshl_add_u64 v[114:115], v[118:119], 2, s[66:67]
	v_lshl_add_u64 v[116:117], v[118:119], 1, s[68:69]
	v_lshl_add_u64 v[122:123], v[148:149], 2, v[114:115]
	v_cvt_pk_bf16_f32 v114, v108, v109
	v_cvt_pk_bf16_f32 v115, v110, v111
	v_lshl_add_u64 v[124:125], v[148:149], 1, v[116:117]
	global_store_dwordx4 v[122:123], v[108:111], off
	global_store_dwordx2 v[124:125], v[114:115], off
	s_and_b64 vcc, exec, s[8:9]
	v_mov_b32_e32 v113, 0
	v_mov_b32_e32 v114, 0
	v_mov_b32_e32 v115, 0
	s_cbranch_vccnz .LBB0_785
	s_nop 0
.LBB0_785:
	s_waitcnt vmcnt(4)
	v_pk_add_f32 v[114:115], v[106:107], v[186:187]
	v_pk_add_f32 v[112:113], v[104:105], v[184:185]
	v_cvt_pk_bf16_f32 v105, v114, v115
	v_cvt_pk_bf16_f32 v104, v112, v113
	global_store_dwordx4 v[122:123], v[112:115], off offset:64
	global_store_dwordx2 v[124:125], v[104:105], off offset:32
	v_mov_b32_e32 v104, 0
	s_and_b64 vcc, exec, s[8:9]
	v_mov_b32_e32 v116, 0
	v_mov_b32_e32 v117, 0
	v_mov_b32_e32 v118, 0
	v_mov_b32_e32 v119, 0
	s_cbranch_vccnz .LBB0_787
	s_nop 0
.LBB0_787:
	s_waitcnt vmcnt(5)
	v_pk_add_f32 v[102:103], v[102:103], v[190:191]
	v_pk_add_f32 v[100:101], v[100:101], v[188:189]
	v_cvt_pk_bf16_f32 v107, v102, v103
	v_cvt_pk_bf16_f32 v106, v100, v101
	global_store_dwordx4 v[122:123], v[100:103], off offset:512
	global_store_dwordx2 v[124:125], v[106:107], off offset:256
	s_and_b64 vcc, exec, s[8:9]
	v_mov_b32_e32 v105, 0
	v_mov_b32_e32 v106, 0
	v_mov_b32_e32 v107, 0
	s_cbranch_vccnz .LBB0_789
	s_nop 0
.LBB0_789:
	v_mul_f32_e32 v109, v109, v109
	v_fmac_f32_e32 v109, v108, v108
	v_mul_f32_e32 v108, v113, v113
	v_fmac_f32_e32 v108, v112, v112
	v_mul_f32_e32 v101, v101, v101
	s_waitcnt vmcnt(6)
	v_pk_add_f32 v[98:99], v[98:99], v[194:195]
	v_pk_add_f32 v[96:97], v[96:97], v[192:193]
	v_fmac_f32_e32 v109, v110, v110
	v_fmac_f32_e32 v108, v114, v114
	v_fmac_f32_e32 v101, v100, v100
	global_store_dwordx4 v[122:123], v[96:99], off offset:576
	v_cvt_pk_bf16_f32 v100, v96, v97
	v_fmac_f32_e32 v109, v111, v111
	v_mul_f32_e32 v97, v97, v97
	v_fmac_f32_e32 v108, v115, v115
	v_fmac_f32_e32 v101, v102, v102
	v_fmac_f32_e32 v97, v96, v96
	v_add_f32_e32 v108, v109, v108
	v_fmac_f32_e32 v101, v103, v103
	v_fmac_f32_e32 v97, v98, v98
	v_add_f32_e32 v102, v108, v101
	v_fmac_f32_e32 v97, v99, v99
	v_add_f32_e32 v96, v102, v97
	v_mov_b32_e32 v97, v96
	s_nop 1
	v_permlane16_swap_b32_e32 v96, v97
	v_add_f32_e32 v96, v96, v97
	v_mov_b32_e32 v97, v96
	v_cvt_pk_bf16_f32 v101, v98, v99
	s_nop 0
	v_permlane32_swap_b32_e32 v96, v97
	global_store_dwordx2 v[124:125], v[100:101], off offset:288
	s_and_saveexec_b64 s[22:23], s[4:5]
	s_cbranch_execz .LBB0_791
	v_lshl_add_u64 v[98:99], v[120:121], 2, s[94:95]
	v_add_f32_e32 v96, v96, v97
	global_atomic_add_f32 v[98:99], v96, off
.LBB0_791:
	s_or_b64 exec, exec, s[22:23]
	v_or_b32_e32 v104, 32, v150
	v_ashrrev_i32_e32 v105, 31, v104
	v_lshlrev_b64 v[96:97], 12, v[104:105]
	v_lshl_add_u64 v[98:99], s[56:57], 0, v[96:97]
	v_mov_b32_e32 v96, 0
	s_and_b64 vcc, exec, s[8:9]
	v_lshl_add_u64 v[110:111], v[148:149], 2, v[98:99]
	v_mov_b32_e32 v98, 0
	v_mov_b32_e32 v99, 0
	v_mov_b32_e32 v100, 0
	v_mov_b32_e32 v101, 0
	s_cbranch_vccnz .LBB0_793
	global_load_dwordx4 v[180:183], v[110:111], off
	global_load_dwordx4 v[184:187], v[110:111], off offset:64
	global_load_dwordx4 v[188:191], v[110:111], off offset:512
	global_load_dwordx4 v[192:195], v[110:111], off offset:576
; DI unsigned pk2(float a, float b) { f32x2 v = {a, b}; hbf2 r = __builtin_convertvector(v, hbf2); return __builtin_bit_cast(unsigned, r); }
; DI float sum_x16_x32(float x) { return sum_x32(sum_x16(x)); }
;     DI void operator()(const f32x4 (&acc)[2][2][4][2], const Unit& u, int wr, int wc, int fr, int fq) const {
;     ...
;             for (int m = 0; m < 4; ++m) {
;                 const int r = row0 + ai * 128 + m * 16;
;                 const float* rp;
;                 if (MODE == 0) rp = x + (size_t)r * 1024;
;                 else rp = h + (size_t)r * 1024;
;                 float sq = 0.f;
; #pragma unroll
;                 for (int bj = 0; bj < 2; ++bj)
; #pragma unroll
;                     for (int n = 0; n < 2; ++n) {
;                         const int c = col0 + bj * 128 + n * 16;
;                         f32x4 rv = rp ? *(const f32x4*)(rp + c) : (f32x4){0.f, 0.f, 0.f, 0.f};
;                         f32x4 v = acc[ai][bj][m][n] + rv;
;                         *(f32x4*)(h + (size_t)r * 1024 + c) = v;
;                         if (WRITE_HB) {
;                             u32x2 w; w.x = pk2(v[0], v[1]); w.y = pk2(v[2], v[3]);
;                             *(u32x2*)(hb + (size_t)r * 1024 + c) = w;
;                         }
;                         sq += v[0] * v[0] + v[1] * v[1] + v[2] * v[2] + v[3] * v[3];
;                     }
;                 sq = sum_x16_x32(sq);
;                 if (fq == 0) atomicAdd(ss + r, sq);
.LBB0_793:
	v_lshlrev_b64 v[102:103], 10, v[104:105]
	s_waitcnt vmcnt(3)
	v_pk_add_f32 v[94:95], v[94:95], v[182:183]
	v_pk_add_f32 v[92:93], v[92:93], v[180:181]
	v_lshl_add_u64 v[98:99], v[102:103], 2, s[66:67]
	v_lshl_add_u64 v[100:101], v[102:103], 1, s[68:69]
	v_lshl_add_u64 v[106:107], v[148:149], 2, v[98:99]
	v_cvt_pk_bf16_f32 v98, v92, v93
	v_cvt_pk_bf16_f32 v99, v94, v95
	v_lshl_add_u64 v[108:109], v[148:149], 1, v[100:101]
	global_store_dwordx4 v[106:107], v[92:95], off
	global_store_dwordx2 v[108:109], v[98:99], off
	s_and_b64 vcc, exec, s[8:9]
	v_mov_b32_e32 v97, 0
	v_mov_b32_e32 v98, 0
	v_mov_b32_e32 v99, 0
	s_cbranch_vccnz .LBB0_795
	s_nop 0
.LBB0_795:
	s_waitcnt vmcnt(4)
	v_pk_add_f32 v[98:99], v[90:91], v[186:187]
	v_pk_add_f32 v[96:97], v[88:89], v[184:185]
	v_cvt_pk_bf16_f32 v89, v98, v99
	v_cvt_pk_bf16_f32 v88, v96, v97
	global_store_dwordx4 v[106:107], v[96:99], off offset:64
	global_store_dwordx2 v[108:109], v[88:89], off offset:32
	v_mov_b32_e32 v88, 0
	s_and_b64 vcc, exec, s[8:9]
	v_mov_b32_e32 v100, 0
	v_mov_b32_e32 v101, 0
	v_mov_b32_e32 v102, 0
	v_mov_b32_e32 v103, 0
	s_cbranch_vccnz .LBB0_797
	s_nop 0
.LBB0_797:
	s_waitcnt vmcnt(5)
	v_pk_add_f32 v[86:87], v[86:87], v[190:191]
	v_pk_add_f32 v[84:85], v[84:85], v[188:189]
	v_cvt_pk_bf16_f32 v91, v86, v87
	v_cvt_pk_bf16_f32 v90, v84, v85
	global_store_dwordx4 v[106:107], v[84:87], off offset:512
	global_store_dwordx2 v[108:109], v[90:91], off offset:256
	s_and_b64 vcc, exec, s[8:9]
	v_mov_b32_e32 v89, 0
	v_mov_b32_e32 v90, 0
	v_mov_b32_e32 v91, 0
	s_cbranch_vccnz .LBB0_799
	s_nop 0
.LBB0_799:
	v_mul_f32_e32 v93, v93, v93
	v_fmac_f32_e32 v93, v92, v92
	v_mul_f32_e32 v92, v97, v97
	v_fmac_f32_e32 v92, v96, v96
	v_mul_f32_e32 v85, v85, v85
	s_waitcnt vmcnt(6)
	v_pk_add_f32 v[82:83], v[82:83], v[194:195]
	v_pk_add_f32 v[80:81], v[80:81], v[192:193]
	v_fmac_f32_e32 v93, v94, v94
	v_fmac_f32_e32 v92, v98, v98
	v_fmac_f32_e32 v85, v84, v84
	global_store_dwordx4 v[106:107], v[80:83], off offset:576
	v_cvt_pk_bf16_f32 v84, v80, v81
	v_fmac_f32_e32 v93, v95, v95
	v_mul_f32_e32 v81, v81, v81
	v_fmac_f32_e32 v92, v99, v99
	v_fmac_f32_e32 v85, v86, v86
	v_fmac_f32_e32 v81, v80, v80
	v_add_f32_e32 v92, v93, v92
	v_fmac_f32_e32 v85, v87, v87
	v_fmac_f32_e32 v81, v82, v82
	v_add_f32_e32 v86, v92, v85
	v_fmac_f32_e32 v81, v83, v83
	v_add_f32_e32 v80, v86, v81
	v_mov_b32_e32 v81, v80
	s_nop 1
	v_permlane16_swap_b32_e32 v80, v81
	v_add_f32_e32 v80, v80, v81
	v_mov_b32_e32 v81, v80
	v_cvt_pk_bf16_f32 v85, v82, v83
	s_nop 0
	v_permlane32_swap_b32_e32 v80, v81
	global_store_dwordx2 v[108:109], v[84:85], off offset:288
	s_and_saveexec_b64 s[22:23], s[4:5]
	s_cbranch_execz .LBB0_801
	v_lshl_add_u64 v[82:83], v[104:105], 2, s[94:95]
	v_add_f32_e32 v80, v80, v81
	global_atomic_add_f32 v[82:83], v80, off
.LBB0_801:
	s_or_b64 exec, exec, s[22:23]
	v_or_b32_e32 v88, 48, v150
	v_ashrrev_i32_e32 v89, 31, v88
	v_lshlrev_b64 v[80:81], 12, v[88:89]
	v_lshl_add_u64 v[82:83], s[56:57], 0, v[80:81]
	v_mov_b32_e32 v80, 0
	s_and_b64 vcc, exec, s[8:9]
	v_lshl_add_u64 v[94:95], v[148:149], 2, v[82:83]
	v_mov_b32_e32 v82, 0
	v_mov_b32_e32 v83, 0
	v_mov_b32_e32 v84, 0
	v_mov_b32_e32 v85, 0
	s_cbranch_vccnz .LBB0_803
	global_load_dwordx4 v[180:183], v[94:95], off
	global_load_dwordx4 v[184:187], v[94:95], off offset:64
	global_load_dwordx4 v[188:191], v[94:95], off offset:512
	global_load_dwordx4 v[192:195], v[94:95], off offset:576
.LBB0_803:
	v_lshlrev_b64 v[86:87], 10, v[88:89]
	s_waitcnt vmcnt(3)
	v_pk_add_f32 v[78:79], v[78:79], v[182:183]
	v_pk_add_f32 v[76:77], v[76:77], v[180:181]
	v_lshl_add_u64 v[82:83], v[86:87], 2, s[66:67]
	v_lshl_add_u64 v[84:85], v[86:87], 1, s[68:69]
	v_lshl_add_u64 v[90:91], v[148:149], 2, v[82:83]
	v_cvt_pk_bf16_f32 v82, v76, v77
	v_cvt_pk_bf16_f32 v83, v78, v79
	v_lshl_add_u64 v[92:93], v[148:149], 1, v[84:85]
	global_store_dwordx4 v[90:91], v[76:79], off
	global_store_dwordx2 v[92:93], v[82:83], off
	s_and_b64 vcc, exec, s[8:9]
	v_mov_b32_e32 v81, 0
	v_mov_b32_e32 v82, 0
	v_mov_b32_e32 v83, 0
	s_cbranch_vccnz .LBB0_805
	s_nop 0
.LBB0_805:
	s_waitcnt vmcnt(4)
	v_pk_add_f32 v[82:83], v[74:75], v[186:187]
	v_pk_add_f32 v[80:81], v[72:73], v[184:185]
	v_cvt_pk_bf16_f32 v73, v82, v83
	v_cvt_pk_bf16_f32 v72, v80, v81
	global_store_dwordx4 v[90:91], v[80:83], off offset:64
	global_store_dwordx2 v[92:93], v[72:73], off offset:32
	v_mov_b32_e32 v72, 0
	s_and_b64 vcc, exec, s[8:9]
	v_mov_b32_e32 v84, 0
	v_mov_b32_e32 v85, 0
	v_mov_b32_e32 v86, 0
	v_mov_b32_e32 v87, 0
	s_cbranch_vccnz .LBB0_807
	s_nop 0
.LBB0_807:
	s_waitcnt vmcnt(5)
	v_pk_add_f32 v[70:71], v[70:71], v[190:191]
	v_pk_add_f32 v[68:69], v[68:69], v[188:189]
	v_cvt_pk_bf16_f32 v75, v70, v71
	v_cvt_pk_bf16_f32 v74, v68, v69
	global_store_dwordx4 v[90:91], v[68:71], off offset:512
	global_store_dwordx2 v[92:93], v[74:75], off offset:256
	s_and_b64 vcc, exec, s[8:9]
	v_mov_b32_e32 v73, 0
	v_mov_b32_e32 v74, 0
	v_mov_b32_e32 v75, 0
	s_cbranch_vccnz .LBB0_809
	s_nop 0
.LBB0_809:
	v_mul_f32_e32 v77, v77, v77
	v_fmac_f32_e32 v77, v76, v76
	v_mul_f32_e32 v76, v81, v81
	v_fmac_f32_e32 v76, v80, v80
	v_mul_f32_e32 v69, v69, v69
	s_waitcnt vmcnt(6)
	v_pk_add_f32 v[66:67], v[66:67], v[194:195]
	v_pk_add_f32 v[64:65], v[64:65], v[192:193]
	v_fmac_f32_e32 v77, v78, v78
	v_fmac_f32_e32 v76, v82, v82
	v_fmac_f32_e32 v69, v68, v68
	global_store_dwordx4 v[90:91], v[64:67], off offset:576
	v_cvt_pk_bf16_f32 v68, v64, v65
	v_fmac_f32_e32 v77, v79, v79
	v_mul_f32_e32 v65, v65, v65
	v_fmac_f32_e32 v76, v83, v83
	v_fmac_f32_e32 v69, v70, v70
	v_fmac_f32_e32 v65, v64, v64
	v_add_f32_e32 v76, v77, v76
	v_fmac_f32_e32 v69, v71, v71
	v_fmac_f32_e32 v65, v66, v66
	v_add_f32_e32 v70, v76, v69
	v_fmac_f32_e32 v65, v67, v67
	v_add_f32_e32 v64, v70, v65
	v_mov_b32_e32 v65, v64
	s_nop 1
	v_permlane16_swap_b32_e32 v64, v65
	v_add_f32_e32 v64, v64, v65
	v_mov_b32_e32 v65, v64
	v_cvt_pk_bf16_f32 v69, v66, v67
	s_nop 0
	v_permlane32_swap_b32_e32 v64, v65
	global_store_dwordx2 v[92:93], v[68:69], off offset:288
	s_and_saveexec_b64 s[22:23], s[4:5]
	s_cbranch_execz .LBB0_811
	v_lshl_add_u64 v[66:67], v[88:89], 2, s[94:95]
	v_add_f32_e32 v64, v64, v65
	global_atomic_add_f32 v[66:67], v64, off
; DI unsigned pk2(float a, float b) { f32x2 v = {a, b}; hbf2 r = __builtin_convertvector(v, hbf2); return __builtin_bit_cast(unsigned, r); }
; DI float sum_x16_x32(float x) { return sum_x32(sum_x16(x)); }
;     DI void operator()(const f32x4 (&acc)[2][2][4][2], const Unit& u, int wr, int wc, int fr, int fq) const {
;     ...
;             for (int m = 0; m < 4; ++m) {
;                 const int r = row0 + ai * 128 + m * 16;
;                 const float* rp;
;                 if (MODE == 0) rp = x + (size_t)r * 1024;
;                 else rp = h + (size_t)r * 1024;
;                 float sq = 0.f;
; #pragma unroll
;                 for (int bj = 0; bj < 2; ++bj)
; #pragma unroll
;                     for (int n = 0; n < 2; ++n) {
;                         const int c = col0 + bj * 128 + n * 16;
;                         f32x4 rv = rp ? *(const f32x4*)(rp + c) : (f32x4){0.f, 0.f, 0.f, 0.f};
;                         f32x4 v = acc[ai][bj][m][n] + rv;
;                         *(f32x4*)(h + (size_t)r * 1024 + c) = v;
;                         if (WRITE_HB) {
;                             u32x2 w; w.x = pk2(v[0], v[1]); w.y = pk2(v[2], v[3]);
;                             *(u32x2*)(hb + (size_t)r * 1024 + c) = w;
;                         }
;                         sq += v[0] * v[0] + v[1] * v[1] + v[2] * v[2] + v[3] * v[3];
;                     }
;                 sq = sum_x16_x32(sq);
;                 if (fq == 0) atomicAdd(ss + r, sq);
.LBB0_811:
	s_or_b64 exec, exec, s[22:23]
	v_add_u32_e32 v72, 0x80, v150
	v_ashrrev_i32_e32 v73, 31, v72
	v_lshlrev_b64 v[64:65], 12, v[72:73]
	v_lshl_add_u64 v[66:67], s[56:57], 0, v[64:65]
	v_mov_b32_e32 v64, 0
	s_and_b64 vcc, exec, s[8:9]
	v_lshl_add_u64 v[78:79], v[148:149], 2, v[66:67]
	v_mov_b32_e32 v66, 0
	v_mov_b32_e32 v67, 0
	v_mov_b32_e32 v68, 0
	v_mov_b32_e32 v69, 0
	s_cbranch_vccnz .LBB0_813
	global_load_dwordx4 v[180:183], v[78:79], off
	global_load_dwordx4 v[184:187], v[78:79], off offset:64
	global_load_dwordx4 v[188:191], v[78:79], off offset:512
	global_load_dwordx4 v[192:195], v[78:79], off offset:576
.LBB0_813:
	v_lshlrev_b64 v[70:71], 10, v[72:73]
	s_waitcnt vmcnt(3)
	v_pk_add_f32 v[62:63], v[62:63], v[182:183]
	v_pk_add_f32 v[60:61], v[60:61], v[180:181]
	v_lshl_add_u64 v[66:67], v[70:71], 2, s[66:67]
	v_lshl_add_u64 v[68:69], v[70:71], 1, s[68:69]
	v_lshl_add_u64 v[74:75], v[148:149], 2, v[66:67]
	v_cvt_pk_bf16_f32 v66, v60, v61
	v_cvt_pk_bf16_f32 v67, v62, v63
	v_lshl_add_u64 v[76:77], v[148:149], 1, v[68:69]
	global_store_dwordx4 v[74:75], v[60:63], off
	global_store_dwordx2 v[76:77], v[66:67], off
	s_and_b64 vcc, exec, s[8:9]
	v_mov_b32_e32 v65, 0
	v_mov_b32_e32 v66, 0
	v_mov_b32_e32 v67, 0
	s_cbranch_vccnz .LBB0_815
	s_nop 0
.LBB0_815:
	s_waitcnt vmcnt(4)
	v_pk_add_f32 v[66:67], v[58:59], v[186:187]
	v_pk_add_f32 v[64:65], v[56:57], v[184:185]
	v_cvt_pk_bf16_f32 v57, v66, v67
	v_cvt_pk_bf16_f32 v56, v64, v65
	global_store_dwordx4 v[74:75], v[64:67], off offset:64
	global_store_dwordx2 v[76:77], v[56:57], off offset:32
	v_mov_b32_e32 v56, 0
	s_and_b64 vcc, exec, s[8:9]
	v_mov_b32_e32 v68, 0
	v_mov_b32_e32 v69, 0
	v_mov_b32_e32 v70, 0
	v_mov_b32_e32 v71, 0
	s_cbranch_vccnz .LBB0_817
	s_nop 0
.LBB0_817:
	s_waitcnt vmcnt(5)
	v_pk_add_f32 v[54:55], v[54:55], v[190:191]
	v_pk_add_f32 v[52:53], v[52:53], v[188:189]
	v_cvt_pk_bf16_f32 v59, v54, v55
	v_cvt_pk_bf16_f32 v58, v52, v53
	global_store_dwordx4 v[74:75], v[52:55], off offset:512
	global_store_dwordx2 v[76:77], v[58:59], off offset:256
	s_and_b64 vcc, exec, s[8:9]
	v_mov_b32_e32 v57, 0
	v_mov_b32_e32 v58, 0
	v_mov_b32_e32 v59, 0
	s_cbranch_vccnz .LBB0_819
	s_nop 0
.LBB0_819:
	v_mul_f32_e32 v61, v61, v61
	v_fmac_f32_e32 v61, v60, v60
	v_mul_f32_e32 v60, v65, v65
	v_fmac_f32_e32 v60, v64, v64
	v_mul_f32_e32 v53, v53, v53
	s_waitcnt vmcnt(6)
	v_pk_add_f32 v[50:51], v[50:51], v[194:195]
	v_pk_add_f32 v[48:49], v[48:49], v[192:193]
	v_fmac_f32_e32 v61, v62, v62
	v_fmac_f32_e32 v60, v66, v66
	v_fmac_f32_e32 v53, v52, v52
	global_store_dwordx4 v[74:75], v[48:51], off offset:576
	v_cvt_pk_bf16_f32 v52, v48, v49
	v_fmac_f32_e32 v61, v63, v63
	v_mul_f32_e32 v49, v49, v49
	v_fmac_f32_e32 v60, v67, v67
	v_fmac_f32_e32 v53, v54, v54
	v_fmac_f32_e32 v49, v48, v48
	v_add_f32_e32 v60, v61, v60
	v_fmac_f32_e32 v53, v55, v55
	v_fmac_f32_e32 v49, v50, v50
	v_add_f32_e32 v54, v60, v53
	v_fmac_f32_e32 v49, v51, v51
	v_add_f32_e32 v48, v54, v49
	v_mov_b32_e32 v49, v48
	s_nop 1
	v_permlane16_swap_b32_e32 v48, v49
	v_add_f32_e32 v48, v48, v49
	v_mov_b32_e32 v49, v48
	v_cvt_pk_bf16_f32 v53, v50, v51
	s_nop 0
	v_permlane32_swap_b32_e32 v48, v49
	global_store_dwordx2 v[76:77], v[52:53], off offset:288
	s_and_saveexec_b64 s[22:23], s[4:5]
	s_cbranch_execz .LBB0_821
	v_lshl_add_u64 v[50:51], v[72:73], 2, s[94:95]
	v_add_f32_e32 v48, v48, v49
	global_atomic_add_f32 v[50:51], v48, off
.LBB0_821:
	s_or_b64 exec, exec, s[22:23]
	v_add_u32_e32 v56, 0x90, v150
	v_ashrrev_i32_e32 v57, 31, v56
	v_lshlrev_b64 v[48:49], 12, v[56:57]
	v_lshl_add_u64 v[50:51], s[56:57], 0, v[48:49]
	v_mov_b32_e32 v48, 0
	s_and_b64 vcc, exec, s[8:9]
	v_lshl_add_u64 v[62:63], v[148:149], 2, v[50:51]
	v_mov_b32_e32 v50, 0
	v_mov_b32_e32 v51, 0
	v_mov_b32_e32 v52, 0
	v_mov_b32_e32 v53, 0
	s_cbranch_vccnz .LBB0_823
	global_load_dwordx4 v[180:183], v[62:63], off
	global_load_dwordx4 v[184:187], v[62:63], off offset:64
	global_load_dwordx4 v[188:191], v[62:63], off offset:512
	global_load_dwordx4 v[192:195], v[62:63], off offset:576
.LBB0_823:
	v_lshlrev_b64 v[54:55], 10, v[56:57]
	s_waitcnt vmcnt(3)
	v_pk_add_f32 v[46:47], v[46:47], v[182:183]
	v_pk_add_f32 v[44:45], v[44:45], v[180:181]
	v_lshl_add_u64 v[50:51], v[54:55], 2, s[66:67]
	v_lshl_add_u64 v[52:53], v[54:55], 1, s[68:69]
	v_lshl_add_u64 v[58:59], v[148:149], 2, v[50:51]
	v_cvt_pk_bf16_f32 v50, v44, v45
	v_cvt_pk_bf16_f32 v51, v46, v47
	v_lshl_add_u64 v[60:61], v[148:149], 1, v[52:53]
	global_store_dwordx4 v[58:59], v[44:47], off
	global_store_dwordx2 v[60:61], v[50:51], off
	s_and_b64 vcc, exec, s[8:9]
	v_mov_b32_e32 v49, 0
	v_mov_b32_e32 v50, 0
	v_mov_b32_e32 v51, 0
	s_cbranch_vccnz .LBB0_825
	s_nop 0
.LBB0_825:
	s_waitcnt vmcnt(4)
	v_pk_add_f32 v[50:51], v[42:43], v[186:187]
	v_pk_add_f32 v[48:49], v[40:41], v[184:185]
	v_cvt_pk_bf16_f32 v41, v50, v51
	v_cvt_pk_bf16_f32 v40, v48, v49
	global_store_dwordx4 v[58:59], v[48:51], off offset:64
	global_store_dwordx2 v[60:61], v[40:41], off offset:32
	v_mov_b32_e32 v40, 0
	s_and_b64 vcc, exec, s[8:9]
	v_mov_b32_e32 v52, 0
	v_mov_b32_e32 v53, 0
	v_mov_b32_e32 v54, 0
	v_mov_b32_e32 v55, 0
	s_cbranch_vccnz .LBB0_827
	s_nop 0
.LBB0_827:
	s_waitcnt vmcnt(5)
	v_pk_add_f32 v[38:39], v[38:39], v[190:191]
	v_pk_add_f32 v[36:37], v[36:37], v[188:189]
	v_cvt_pk_bf16_f32 v43, v38, v39
	v_cvt_pk_bf16_f32 v42, v36, v37
	global_store_dwordx4 v[58:59], v[36:39], off offset:512
	global_store_dwordx2 v[60:61], v[42:43], off offset:256
	s_and_b64 vcc, exec, s[8:9]
	v_mov_b32_e32 v41, 0
	v_mov_b32_e32 v42, 0
	v_mov_b32_e32 v43, 0
	s_cbranch_vccnz .LBB0_829
	s_nop 0
; DI unsigned pk2(float a, float b) { f32x2 v = {a, b}; hbf2 r = __builtin_convertvector(v, hbf2); return __builtin_bit_cast(unsigned, r); }
; DI float sum_x16_x32(float x) { return sum_x32(sum_x16(x)); }
;     DI void operator()(const f32x4 (&acc)[2][2][4][2], const Unit& u, int wr, int wc, int fr, int fq) const {
;     ...
;             for (int m = 0; m < 4; ++m) {
;                 const int r = row0 + ai * 128 + m * 16;
;                 const float* rp;
;                 if (MODE == 0) rp = x + (size_t)r * 1024;
;                 else rp = h + (size_t)r * 1024;
;                 float sq = 0.f;
; #pragma unroll
;                 for (int bj = 0; bj < 2; ++bj)
; #pragma unroll
;                     for (int n = 0; n < 2; ++n) {
;                         const int c = col0 + bj * 128 + n * 16;
;                         f32x4 rv = rp ? *(const f32x4*)(rp + c) : (f32x4){0.f, 0.f, 0.f, 0.f};
;                         f32x4 v = acc[ai][bj][m][n] + rv;
;                         *(f32x4*)(h + (size_t)r * 1024 + c) = v;
;                         if (WRITE_HB) {
;                             u32x2 w; w.x = pk2(v[0], v[1]); w.y = pk2(v[2], v[3]);
;                             *(u32x2*)(hb + (size_t)r * 1024 + c) = w;
;                         }
;                         sq += v[0] * v[0] + v[1] * v[1] + v[2] * v[2] + v[3] * v[3];
;                     }
;                 sq = sum_x16_x32(sq);
;                 if (fq == 0) atomicAdd(ss + r, sq);
.LBB0_829:
	v_mul_f32_e32 v45, v45, v45
	v_fmac_f32_e32 v45, v44, v44
	v_mul_f32_e32 v44, v49, v49
	v_fmac_f32_e32 v44, v48, v48
	v_mul_f32_e32 v37, v37, v37
	s_waitcnt vmcnt(6)
	v_pk_add_f32 v[34:35], v[34:35], v[194:195]
	v_pk_add_f32 v[32:33], v[32:33], v[192:193]
	v_fmac_f32_e32 v45, v46, v46
	v_fmac_f32_e32 v44, v50, v50
	v_fmac_f32_e32 v37, v36, v36
	global_store_dwordx4 v[58:59], v[32:35], off offset:576
	v_cvt_pk_bf16_f32 v36, v32, v33
	v_fmac_f32_e32 v45, v47, v47
	v_mul_f32_e32 v33, v33, v33
	v_fmac_f32_e32 v44, v51, v51
	v_fmac_f32_e32 v37, v38, v38
	v_fmac_f32_e32 v33, v32, v32
	v_add_f32_e32 v44, v45, v44
	v_fmac_f32_e32 v37, v39, v39
	v_fmac_f32_e32 v33, v34, v34
	v_add_f32_e32 v38, v44, v37
	v_fmac_f32_e32 v33, v35, v35
	v_add_f32_e32 v32, v38, v33
	v_mov_b32_e32 v33, v32
	s_nop 1
	v_permlane16_swap_b32_e32 v32, v33
	v_add_f32_e32 v32, v32, v33
	v_mov_b32_e32 v33, v32
	v_cvt_pk_bf16_f32 v37, v34, v35
	s_nop 0
	v_permlane32_swap_b32_e32 v32, v33
	global_store_dwordx2 v[60:61], v[36:37], off offset:288
	s_and_saveexec_b64 s[22:23], s[4:5]
	s_cbranch_execz .LBB0_831
	v_lshl_add_u64 v[34:35], v[56:57], 2, s[94:95]
	v_add_f32_e32 v32, v32, v33
	global_atomic_add_f32 v[34:35], v32, off
.LBB0_831:
	s_or_b64 exec, exec, s[22:23]
	v_add_u32_e32 v40, 0xa0, v150
	v_ashrrev_i32_e32 v41, 31, v40
	v_lshlrev_b64 v[32:33], 12, v[40:41]
	v_lshl_add_u64 v[34:35], s[56:57], 0, v[32:33]
	v_mov_b32_e32 v32, 0
	s_and_b64 vcc, exec, s[8:9]
	v_lshl_add_u64 v[46:47], v[148:149], 2, v[34:35]
	v_mov_b32_e32 v34, 0
	v_mov_b32_e32 v35, 0
	v_mov_b32_e32 v36, 0
	v_mov_b32_e32 v37, 0
	s_cbranch_vccnz .LBB0_833
	global_load_dwordx4 v[180:183], v[46:47], off
	global_load_dwordx4 v[184:187], v[46:47], off offset:64
	global_load_dwordx4 v[188:191], v[46:47], off offset:512
	global_load_dwordx4 v[192:195], v[46:47], off offset:576
.LBB0_833:
	v_lshlrev_b64 v[38:39], 10, v[40:41]
	s_waitcnt vmcnt(3)
	v_pk_add_f32 v[30:31], v[30:31], v[182:183]
	v_pk_add_f32 v[28:29], v[28:29], v[180:181]
	v_lshl_add_u64 v[34:35], v[38:39], 2, s[66:67]
	v_lshl_add_u64 v[36:37], v[38:39], 1, s[68:69]
	v_lshl_add_u64 v[42:43], v[148:149], 2, v[34:35]
	v_cvt_pk_bf16_f32 v34, v28, v29
	v_cvt_pk_bf16_f32 v35, v30, v31
	v_lshl_add_u64 v[44:45], v[148:149], 1, v[36:37]
	global_store_dwordx4 v[42:43], v[28:31], off
	global_store_dwordx2 v[44:45], v[34:35], off
	s_and_b64 vcc, exec, s[8:9]
	v_mov_b32_e32 v33, 0
	v_mov_b32_e32 v34, 0
	v_mov_b32_e32 v35, 0
	s_cbranch_vccnz .LBB0_835
	s_nop 0
.LBB0_835:
	s_waitcnt vmcnt(4)
	v_pk_add_f32 v[34:35], v[26:27], v[186:187]
	v_pk_add_f32 v[32:33], v[24:25], v[184:185]
	v_cvt_pk_bf16_f32 v25, v34, v35
	v_cvt_pk_bf16_f32 v24, v32, v33
	global_store_dwordx4 v[42:43], v[32:35], off offset:64
	global_store_dwordx2 v[44:45], v[24:25], off offset:32
	v_mov_b32_e32 v24, 0
	s_and_b64 vcc, exec, s[8:9]
	v_mov_b32_e32 v36, 0
	v_mov_b32_e32 v37, 0
	v_mov_b32_e32 v38, 0
	v_mov_b32_e32 v39, 0
	s_cbranch_vccnz .LBB0_837
	s_nop 0
.LBB0_837:
	s_waitcnt vmcnt(5)
	v_pk_add_f32 v[22:23], v[22:23], v[190:191]
	v_pk_add_f32 v[20:21], v[20:21], v[188:189]
	v_cvt_pk_bf16_f32 v27, v22, v23
	v_cvt_pk_bf16_f32 v26, v20, v21
	global_store_dwordx4 v[42:43], v[20:23], off offset:512
	global_store_dwordx2 v[44:45], v[26:27], off offset:256
	s_and_b64 vcc, exec, s[8:9]
	v_mov_b32_e32 v25, 0
	v_mov_b32_e32 v26, 0
	v_mov_b32_e32 v27, 0
	s_cbranch_vccnz .LBB0_839
	s_nop 0
; DI unsigned pk2(float a, float b) { f32x2 v = {a, b}; hbf2 r = __builtin_convertvector(v, hbf2); return __builtin_bit_cast(unsigned, r); }
; DI float sum_x16_x32(float x) { return sum_x32(sum_x16(x)); }
;     DI void operator()(const f32x4 (&acc)[2][2][4][2], const Unit& u, int wr, int wc, int fr, int fq) const {
;     ...
;             for (int m = 0; m < 4; ++m) {
;                 const int r = row0 + ai * 128 + m * 16;
;                 const float* rp;
;                 if (MODE == 0) rp = x + (size_t)r * 1024;
;                 else rp = h + (size_t)r * 1024;
;                 float sq = 0.f;
; #pragma unroll
;                 for (int bj = 0; bj < 2; ++bj)
; #pragma unroll
;                     for (int n = 0; n < 2; ++n) {
;                         const int c = col0 + bj * 128 + n * 16;
;                         f32x4 rv = rp ? *(const f32x4*)(rp + c) : (f32x4){0.f, 0.f, 0.f, 0.f};
;                         f32x4 v = acc[ai][bj][m][n] + rv;
;                         *(f32x4*)(h + (size_t)r * 1024 + c) = v;
;                         if (WRITE_HB) {
;                             u32x2 w; w.x = pk2(v[0], v[1]); w.y = pk2(v[2], v[3]);
;                             *(u32x2*)(hb + (size_t)r * 1024 + c) = w;
;                         }
;                         sq += v[0] * v[0] + v[1] * v[1] + v[2] * v[2] + v[3] * v[3];
;                     }
;                 sq = sum_x16_x32(sq);
;                 if (fq == 0) atomicAdd(ss + r, sq);
.LBB0_839:
	v_mul_f32_e32 v29, v29, v29
	v_fmac_f32_e32 v29, v28, v28
	v_mul_f32_e32 v28, v33, v33
	v_fmac_f32_e32 v28, v32, v32
	v_mul_f32_e32 v21, v21, v21
	s_waitcnt vmcnt(6)
	v_pk_add_f32 v[18:19], v[18:19], v[194:195]
	v_pk_add_f32 v[16:17], v[16:17], v[192:193]
	v_fmac_f32_e32 v29, v30, v30
	v_fmac_f32_e32 v28, v34, v34
	v_fmac_f32_e32 v21, v20, v20
	global_store_dwordx4 v[42:43], v[16:19], off offset:576
	v_cvt_pk_bf16_f32 v20, v16, v17
	v_fmac_f32_e32 v29, v31, v31
	v_mul_f32_e32 v17, v17, v17
	v_fmac_f32_e32 v28, v35, v35
	v_fmac_f32_e32 v21, v22, v22
	v_fmac_f32_e32 v17, v16, v16
	v_add_f32_e32 v28, v29, v28
	v_fmac_f32_e32 v21, v23, v23
	v_fmac_f32_e32 v17, v18, v18
	v_add_f32_e32 v22, v28, v21
	v_fmac_f32_e32 v17, v19, v19
	v_add_f32_e32 v16, v22, v17
	v_mov_b32_e32 v17, v16
	s_nop 1
	v_permlane16_swap_b32_e32 v16, v17
	v_add_f32_e32 v16, v16, v17
	v_mov_b32_e32 v17, v16
	v_cvt_pk_bf16_f32 v21, v18, v19
	s_nop 0
	v_permlane32_swap_b32_e32 v16, v17
	global_store_dwordx2 v[44:45], v[20:21], off offset:288
	s_and_saveexec_b64 s[22:23], s[4:5]
	s_cbranch_execz .LBB0_841
	v_lshl_add_u64 v[18:19], v[40:41], 2, s[94:95]
	v_add_f32_e32 v16, v16, v17
	global_atomic_add_f32 v[18:19], v16, off
.LBB0_841:
	s_or_b64 exec, exec, s[22:23]
	v_add_u32_e32 v24, 0xb0, v150
	v_ashrrev_i32_e32 v25, 31, v24
	v_lshlrev_b64 v[16:17], 12, v[24:25]
	v_lshl_add_u64 v[18:19], s[56:57], 0, v[16:17]
	v_mov_b32_e32 v16, 0
	s_and_b64 vcc, exec, s[8:9]
	v_lshl_add_u64 v[30:31], v[148:149], 2, v[18:19]
	v_mov_b32_e32 v18, 0
	v_mov_b32_e32 v19, 0
	v_mov_b32_e32 v20, 0
	v_mov_b32_e32 v21, 0
	s_cbranch_vccnz .LBB0_843
	global_load_dwordx4 v[180:183], v[30:31], off
	global_load_dwordx4 v[184:187], v[30:31], off offset:64
	global_load_dwordx4 v[188:191], v[30:31], off offset:512
	global_load_dwordx4 v[192:195], v[30:31], off offset:576
.LBB0_843:
	v_lshlrev_b64 v[22:23], 10, v[24:25]
	s_waitcnt vmcnt(3)
	v_pk_add_f32 v[14:15], v[14:15], v[182:183]
	v_pk_add_f32 v[12:13], v[12:13], v[180:181]
	v_lshl_add_u64 v[18:19], v[22:23], 2, s[66:67]
	v_lshl_add_u64 v[20:21], v[22:23], 1, s[68:69]
	v_lshl_add_u64 v[26:27], v[148:149], 2, v[18:19]
	v_cvt_pk_bf16_f32 v18, v12, v13
	v_cvt_pk_bf16_f32 v19, v14, v15
	v_lshl_add_u64 v[28:29], v[148:149], 1, v[20:21]
	global_store_dwordx4 v[26:27], v[12:15], off
	global_store_dwordx2 v[28:29], v[18:19], off
	s_and_b64 vcc, exec, s[8:9]
	v_mov_b32_e32 v17, 0
	v_mov_b32_e32 v18, 0
	v_mov_b32_e32 v19, 0
	s_cbranch_vccnz .LBB0_845
	s_nop 0
.LBB0_845:
	s_waitcnt vmcnt(4)
	v_pk_add_f32 v[18:19], v[10:11], v[186:187]
	v_pk_add_f32 v[16:17], v[8:9], v[184:185]
	v_cvt_pk_bf16_f32 v9, v18, v19
	v_cvt_pk_bf16_f32 v8, v16, v17
	global_store_dwordx4 v[26:27], v[16:19], off offset:64
	global_store_dwordx2 v[28:29], v[8:9], off offset:32
	v_mov_b32_e32 v8, 0
	s_and_b64 vcc, exec, s[8:9]
	v_mov_b32_e32 v20, 0
	v_mov_b32_e32 v21, 0
	v_mov_b32_e32 v22, 0
	v_mov_b32_e32 v23, 0
	s_cbranch_vccnz .LBB0_847
	s_nop 0
.LBB0_847:
	s_waitcnt vmcnt(5)
	v_pk_add_f32 v[6:7], v[6:7], v[190:191]
	v_pk_add_f32 v[4:5], v[4:5], v[188:189]
	v_cvt_pk_bf16_f32 v11, v6, v7
	v_cvt_pk_bf16_f32 v10, v4, v5
	global_store_dwordx4 v[26:27], v[4:7], off offset:512
	global_store_dwordx2 v[28:29], v[10:11], off offset:256
	s_and_b64 vcc, exec, s[8:9]
	v_mov_b32_e32 v9, 0
	v_mov_b32_e32 v10, 0
	v_mov_b32_e32 v11, 0
	s_cbranch_vccnz .LBB0_849
	s_nop 0
.LBB0_849:
	v_mul_f32_e32 v13, v13, v13
	v_fmac_f32_e32 v13, v12, v12
	v_mul_f32_e32 v12, v17, v17
	v_fmac_f32_e32 v12, v16, v16
	v_mul_f32_e32 v5, v5, v5
	s_waitcnt vmcnt(6)
	v_pk_add_f32 v[2:3], v[2:3], v[194:195]
	v_pk_add_f32 v[0:1], v[0:1], v[192:193]
	v_fmac_f32_e32 v13, v14, v14
	v_fmac_f32_e32 v12, v18, v18
	v_fmac_f32_e32 v5, v4, v4
	global_store_dwordx4 v[26:27], v[0:3], off offset:576
	v_cvt_pk_bf16_f32 v4, v0, v1
	v_fmac_f32_e32 v13, v15, v15
	v_mul_f32_e32 v1, v1, v1
	v_fmac_f32_e32 v12, v19, v19
	v_fmac_f32_e32 v5, v6, v6
	v_fmac_f32_e32 v1, v0, v0
	v_add_f32_e32 v12, v13, v12
	v_fmac_f32_e32 v5, v7, v7
	v_fmac_f32_e32 v1, v2, v2
	v_add_f32_e32 v6, v12, v5
	v_fmac_f32_e32 v1, v3, v3
	v_add_f32_e32 v0, v6, v1
	v_mov_b32_e32 v1, v0
	s_nop 1
	v_permlane16_swap_b32_e32 v0, v1
	v_add_f32_e32 v0, v0, v1
	v_mov_b32_e32 v1, v0
	v_cvt_pk_bf16_f32 v5, v2, v3
	s_nop 0
	v_permlane32_swap_b32_e32 v0, v1
	global_store_dwordx2 v[28:29], v[4:5], off offset:288
	s_and_saveexec_b64 s[8:9], s[4:5]
	s_cbranch_execz .LBB0_762
	v_lshl_add_u64 v[2:3], v[24:25], 2, s[94:95]
	v_add_f32_e32 v0, v0, v1
	global_atomic_add_f32 v[2:3], v0, off
	s_branch .LBB0_762

; #define PG8_STAGE(bufoff, gbase, voff) do { _Pragma("unroll") for (int _i = 0; _i < 2; ++_i) \
;         __builtin_amdgcn_global_load_lds((const unsigned*)((const char*)(gbase) + (voff)[_i]), (LAS unsigned*)(lds + (bufoff) + ldsw + _i * 8192), 16, 0, 0); } while (0)
; #define PG8_LDA(dst, b, h) do { _Pragma("unroll") for (int m = 0; m < 4; ++m) _Pragma("unroll") for (int k = 0; k < 2; ++k) dst[m][k] = *(const LAS bf16x8*)(lds + PG8_SA(b, h) + aoff + m * 2048 + k * 1024); } while (0)
; #define PG8_LDB(dst, b, h) do { _Pragma("unroll") for (int n = 0; n < 2; ++n) _Pragma("unroll") for (int k = 0; k < 2; ++k) dst[n][k] = *(const LAS bf16x8*)(lds + PG8_SB(b, h) + boff + n * 2048 + k * 1024); } while (0)
; #define PG8_MMA(ai, bj, At, Bt) do { __builtin_amdgcn_s_setprio(1); _Pragma("unroll") for (int m = 0; m < 4; ++m) _Pragma("unroll") for (int n = 0; n < 2; ++n) _Pragma("unroll") for (int k = 0; k < 2; ++k) \
;         acc[ai][bj][m][n] = __builtin_amdgcn_mfma_f32_16x16x32_bf16(Bt[n][k], At[m][k], acc[ai][bj][m][n], 0, 0, 0); __builtin_amdgcn_s_setprio(0); } while (0)
; #define PG8_WAIT_L(n) asm volatile("s_waitcnt lgkmcnt(" #n ")" ::: "memory")
; #define PG8_BAR __builtin_amdgcn_s_barrier()
; #define PG8_SCHED __builtin_amdgcn_sched_barrier(0)
; template <class Epi>
; __device__ __forceinline__ void gemm_phase(LAS unsigned char* lds, const Gemm g, const StaticOrder& S, const Epi& E) {
;     ...
;         for (int t = 0; t < nt; t += 2) {
;             const bool last = (t == nt - 2);
;             const char* a1 = cA + (size_t)(t + 1) * kstep;
;             const char* a2 = last ? nA : cA + (size_t)(t + 2) * kstep; const char* b2 = last ? nB : cB + (size_t)(t + 2) * kstep;
;             const char* a3 = a2 + kstep; const char* b3 = b2 + kstep;
;             PG8_LDB(B0, 0, 0); PG8_SCHED; PG8_LDA(At, 0, 0); PG8_STAGE(PG8_SA(1, 1), a1 + hstep, voffA);
;             PG8_WAIT_L(8); PG8_BAR; PG8_WAIT_L(0); PG8_MMA(0, 0, At, B0); PG8_BAR; PG8_SCHED;
;             PG8_LDB(B1, 0, 1); PG8_STAGE(PG8_SB(0, 0), b2, voffB);
;             PG8_BAR; PG8_WAIT_L(0); PG8_MMA(0, 1, At, B1); PG8_BAR;
;             PG8_LDA(At, 0, 1); PG8_STAGE(PG8_SA(0, 0), a2, voffA);
;             PG8_BAR; PG8_WAIT_L(0); PG8_MMA(1, 0, At, B0); PG8_BAR; PG8_SCHED;
.LBB0_926:
	ds_read_b128 v[144:147], v155
	ds_read_b128 v[148:151], v155 offset:1024
	ds_read_b128 v[160:163], v155 offset:2048
	ds_read_b128 v[164:167], v155 offset:3072
	s_add_u32 s28, s0, 0xfffc0080
	s_addc_u32 s29, s1, -1
	s_cmp_eq_u32 s70, 12
	s_cselect_b32 s31, s21, s29
	s_cselect_b32 s30, s60, s28
	s_cselect_b32 s29, s19, s63
	s_cselect_b32 s28, s61, s62
	v_lshl_add_u64 v[172:173], s[0:1], 0, v[136:137]
	s_add_i32 m0, s27, 0xc000
	ds_read_b128 v[168:171], v156
	ds_read_b128 v[180:183], v156 offset:1024
	ds_read_b128 v[184:187], v156 offset:2048
	ds_read_b128 v[188:191], v156 offset:3072
	ds_read_b128 v[192:195], v156 offset:4096
	ds_read_b128 v[196:199], v156 offset:5120
	ds_read_b128 v[200:203], v156 offset:6144
	ds_read_b128 v[204:207], v156 offset:7168
	global_load_lds_dwordx4 v[172:173], off
	v_lshl_add_u64 v[172:173], s[0:1], 0, v[138:139]
	s_add_i32 m0, s27, 0xe000
	s_nop 0
	global_load_lds_dwordx4 v[172:173], off
	s_waitcnt lgkmcnt(8)
	s_barrier
	s_waitcnt lgkmcnt(0)
	s_setprio 1
	s_waitcnt lgkmcnt(0)
	v_mfma_f32_16x16x32_bf16 v[124:127], v[144:147], v[168:171], v[124:127]
	v_mfma_f32_16x16x32_bf16 v[120:123], v[160:163], v[168:171], v[120:123]
	v_mfma_f32_16x16x32_bf16 v[108:111], v[144:147], v[184:187], v[108:111]
	v_mfma_f32_16x16x32_bf16 v[104:107], v[160:163], v[184:187], v[104:107]
	v_mfma_f32_16x16x32_bf16 v[92:95], v[144:147], v[192:195], v[92:95]
	v_mfma_f32_16x16x32_bf16 v[88:91], v[160:163], v[192:195], v[88:91]
	v_mfma_f32_16x16x32_bf16 v[76:79], v[144:147], v[200:203], v[76:79]
	v_mfma_f32_16x16x32_bf16 v[72:75], v[160:163], v[200:203], v[72:75]
	v_mfma_f32_16x16x32_bf16 v[124:127], v[148:151], v[180:183], v[124:127]
	v_mfma_f32_16x16x32_bf16 v[120:123], v[164:167], v[180:183], v[120:123]
	v_mfma_f32_16x16x32_bf16 v[108:111], v[148:151], v[188:191], v[108:111]
	v_mfma_f32_16x16x32_bf16 v[104:107], v[164:167], v[188:191], v[104:107]
	v_mfma_f32_16x16x32_bf16 v[92:95], v[148:151], v[196:199], v[92:95]
	v_mfma_f32_16x16x32_bf16 v[88:91], v[164:167], v[196:199], v[88:91]
	v_mfma_f32_16x16x32_bf16 v[76:79], v[148:151], v[204:207], v[76:79]
	v_mfma_f32_16x16x32_bf16 v[72:75], v[164:167], v[204:207], v[72:75]
	s_setprio 0
	s_barrier
	s_add_i32 s71, s48, s33
	v_lshl_add_u64 v[172:173], s[28:29], 0, v[130:131]
	s_mov_b32 m0, s71
	ds_read_b128 v[208:211], v157
	ds_read_b128 v[212:215], v157 offset:1024
	ds_read_b128 v[216:219], v157 offset:2048
	ds_read_b128 v[220:223], v157 offset:3072
	global_load_lds_dwordx4 v[172:173], off
	v_lshl_add_u64 v[176:177], s[28:29], 0, v[134:135]
	s_add_i32 m0, s71, 0x2000
	s_nop 0
	global_load_lds_dwordx4 v[176:177], off
	s_barrier
	s_waitcnt lgkmcnt(0)
	s_setprio 1
	s_waitcnt lgkmcnt(0)
	v_mfma_f32_16x16x32_bf16 v[116:119], v[208:211], v[168:171], v[116:119]
	v_mfma_f32_16x16x32_bf16 v[112:115], v[216:219], v[168:171], v[112:115]
	v_mfma_f32_16x16x32_bf16 v[100:103], v[208:211], v[184:187], v[100:103]
	v_mfma_f32_16x16x32_bf16 v[96:99], v[216:219], v[184:187], v[96:99]
	v_mfma_f32_16x16x32_bf16 v[84:87], v[208:211], v[192:195], v[84:87]
	v_mfma_f32_16x16x32_bf16 v[80:83], v[216:219], v[192:195], v[80:83]
	v_mfma_f32_16x16x32_bf16 v[68:71], v[208:211], v[200:203], v[68:71]
	v_mfma_f32_16x16x32_bf16 v[64:67], v[216:219], v[200:203], v[64:67]
	v_mfma_f32_16x16x32_bf16 v[116:119], v[212:215], v[180:183], v[116:119]
	v_mfma_f32_16x16x32_bf16 v[112:115], v[220:223], v[180:183], v[112:115]
	v_mfma_f32_16x16x32_bf16 v[100:103], v[212:215], v[188:191], v[100:103]
	v_mfma_f32_16x16x32_bf16 v[96:99], v[220:223], v[188:191], v[96:99]
	v_mfma_f32_16x16x32_bf16 v[84:87], v[212:215], v[196:199], v[84:87]
	v_mfma_f32_16x16x32_bf16 v[80:83], v[220:223], v[196:199], v[80:83]
	v_mfma_f32_16x16x32_bf16 v[68:71], v[212:215], v[204:207], v[68:71]
	v_mfma_f32_16x16x32_bf16 v[64:67], v[220:223], v[204:207], v[64:67]
	s_setprio 0
	s_mov_b32 m0, s27
	v_lshl_add_u64 v[224:225], s[30:31], 0, v[128:129]
	s_barrier
	ds_read_b128 v[168:171], v156 offset:16384
	ds_read_b128 v[180:183], v156 offset:17408
	ds_read_b128 v[184:187], v156 offset:18432
	ds_read_b128 v[188:191], v156 offset:19456
	ds_read_b128 v[192:195], v156 offset:20480
	ds_read_b128 v[196:199], v156 offset:21504
	ds_read_b128 v[200:203], v156 offset:22528
	ds_read_b128 v[204:207], v156 offset:23552
	global_load_lds_dwordx4 v[224:225], off
	v_lshl_add_u64 v[226:227], s[30:31], 0, v[132:133]
	s_mov_b32 m0, s38
	s_nop 0
	global_load_lds_dwordx4 v[226:227], off
	s_barrier
	s_waitcnt lgkmcnt(0)
	s_setprio 1
	s_waitcnt lgkmcnt(0)
	v_mfma_f32_16x16x32_bf16 v[60:63], v[144:147], v[168:171], v[60:63]
	v_mfma_f32_16x16x32_bf16 v[56:59], v[160:163], v[168:171], v[56:59]
	v_mfma_f32_16x16x32_bf16 v[44:47], v[144:147], v[184:187], v[44:47]
	v_mfma_f32_16x16x32_bf16 v[40:43], v[160:163], v[184:187], v[40:43]
	v_mfma_f32_16x16x32_bf16 v[28:31], v[144:147], v[192:195], v[28:31]
	v_mfma_f32_16x16x32_bf16 v[24:27], v[160:163], v[192:195], v[24:27]
	v_mfma_f32_16x16x32_bf16 v[12:15], v[144:147], v[200:203], v[12:15]
	v_mfma_f32_16x16x32_bf16 v[8:11], v[160:163], v[200:203], v[8:11]
	v_mfma_f32_16x16x32_bf16 v[60:63], v[148:151], v[180:183], v[60:63]
	v_mfma_f32_16x16x32_bf16 v[56:59], v[164:167], v[180:183], v[56:59]
	v_mfma_f32_16x16x32_bf16 v[44:47], v[148:151], v[188:191], v[44:47]
	v_mfma_f32_16x16x32_bf16 v[40:43], v[164:167], v[188:191], v[40:43]
	v_mfma_f32_16x16x32_bf16 v[28:31], v[148:151], v[196:199], v[28:31]
	v_mfma_f32_16x16x32_bf16 v[24:27], v[164:167], v[196:199], v[24:27]
	v_mfma_f32_16x16x32_bf16 v[12:15], v[148:151], v[204:207], v[12:15]
	v_mfma_f32_16x16x32_bf16 v[8:11], v[164:167], v[204:207], v[8:11]
	s_setprio 0
	s_barrier
; #define PG8_STAGE(bufoff, gbase, voff) do { _Pragma("unroll") for (int _i = 0; _i < 2; ++_i) \
;         __builtin_amdgcn_global_load_lds((const unsigned*)((const char*)(gbase) + (voff)[_i]), (LAS unsigned*)(lds + (bufoff) + ldsw + _i * 8192), 16, 0, 0); } while (0)
; #define PG8_LDA(dst, b, h) do { _Pragma("unroll") for (int m = 0; m < 4; ++m) _Pragma("unroll") for (int k = 0; k < 2; ++k) dst[m][k] = *(const LAS bf16x8*)(lds + PG8_SA(b, h) + aoff + m * 2048 + k * 1024); } while (0)
; #define PG8_LDB(dst, b, h) do { _Pragma("unroll") for (int n = 0; n < 2; ++n) _Pragma("unroll") for (int k = 0; k < 2; ++k) dst[n][k] = *(const LAS bf16x8*)(lds + PG8_SB(b, h) + boff + n * 2048 + k * 1024); } while (0)
; #define PG8_MMA(ai, bj, At, Bt) do { __builtin_amdgcn_s_setprio(1); _Pragma("unroll") for (int m = 0; m < 4; ++m) _Pragma("unroll") for (int n = 0; n < 2; ++n) _Pragma("unroll") for (int k = 0; k < 2; ++k) \
;         acc[ai][bj][m][n] = __builtin_amdgcn_mfma_f32_16x16x32_bf16(Bt[n][k], At[m][k], acc[ai][bj][m][n], 0, 0, 0); __builtin_amdgcn_s_setprio(0); } while (0)
; #define PG8_WAIT_V(n) asm volatile("s_waitcnt vmcnt(" #n ")" ::: "memory")
; #define PG8_WAIT_L(n) asm volatile("s_waitcnt lgkmcnt(" #n ")" ::: "memory")
; #define PG8_BAR __builtin_amdgcn_s_barrier()
; #define PG8_SCHED __builtin_amdgcn_sched_barrier(0)
; template <class Epi>
; __device__ __forceinline__ void gemm_phase(LAS unsigned char* lds, const Gemm g, const StaticOrder& S, const Epi& E) {
;     ...
;             PG8_STAGE(PG8_SB(0, 1), b2 + hstep, voffB);
;             PG8_WAIT_V(6); PG8_BAR; PG8_MMA(1, 1, At, B1); PG8_BAR;
;             PG8_LDB(B0, 1, 0); PG8_SCHED; PG8_LDA(At, 1, 0); PG8_STAGE(PG8_SA(0, 1), a2 + hstep, voffA);
;             PG8_WAIT_L(8); PG8_BAR; PG8_WAIT_L(0); PG8_MMA(0, 0, At, B0); PG8_BAR; PG8_SCHED;
;             PG8_LDB(B1, 1, 1); PG8_STAGE(PG8_SB(1, 0), b3, voffB);
;             PG8_BAR; PG8_WAIT_L(0); PG8_MMA(0, 1, At, B1); PG8_BAR;
;             PG8_LDA(At, 1, 1); PG8_STAGE(PG8_SA(1, 0), a3, voffA);
;             PG8_BAR; PG8_WAIT_L(0); PG8_MMA(1, 0, At, B0); PG8_BAR; PG8_SCHED;
	s_add_u32 s72, s28, 0x40000
	s_addc_u32 s73, s29, 0
	s_add_i32 s71, s49, s33
	v_lshl_add_u64 v[144:145], s[72:73], 0, v[130:131]
	s_mov_b32 m0, s71
	s_nop 0
	global_load_lds_dwordx4 v[144:145], off
	v_lshl_add_u64 v[144:145], s[72:73], 0, v[134:135]
	s_add_i32 m0, s71, 0x2000
	s_nop 0
	global_load_lds_dwordx4 v[144:145], off
	s_waitcnt vmcnt(6)
	s_barrier
	s_setprio 1
	v_mfma_f32_16x16x32_bf16 v[52:55], v[208:211], v[168:171], v[52:55]
	v_mfma_f32_16x16x32_bf16 v[48:51], v[216:219], v[168:171], v[48:51]
	v_mfma_f32_16x16x32_bf16 v[36:39], v[208:211], v[184:187], v[36:39]
	v_mfma_f32_16x16x32_bf16 v[32:35], v[216:219], v[184:187], v[32:35]
	v_mfma_f32_16x16x32_bf16 v[20:23], v[208:211], v[192:195], v[20:23]
	v_mfma_f32_16x16x32_bf16 v[16:19], v[216:219], v[192:195], v[16:19]
	v_mfma_f32_16x16x32_bf16 v[4:7], v[208:211], v[200:203], v[4:7]
	v_mfma_f32_16x16x32_bf16 v[0:3], v[216:219], v[200:203], v[0:3]
	v_mfma_f32_16x16x32_bf16 v[52:55], v[212:215], v[180:183], v[52:55]
	v_mfma_f32_16x16x32_bf16 v[48:51], v[220:223], v[180:183], v[48:51]
	v_mfma_f32_16x16x32_bf16 v[36:39], v[212:215], v[188:191], v[36:39]
	v_mfma_f32_16x16x32_bf16 v[32:35], v[220:223], v[188:191], v[32:35]
	v_mfma_f32_16x16x32_bf16 v[20:23], v[212:215], v[196:199], v[20:23]
	v_mfma_f32_16x16x32_bf16 v[16:19], v[220:223], v[196:199], v[16:19]
	v_mfma_f32_16x16x32_bf16 v[4:7], v[212:215], v[204:207], v[4:7]
	v_mfma_f32_16x16x32_bf16 v[0:3], v[220:223], v[204:207], v[0:3]
	s_setprio 0
	s_add_i32 s71, 0, 0x18000
	v_add_u32_e32 v159, s71, v153
	s_barrier
	ds_read_b128 v[144:147], v159
	ds_read_b128 v[148:151], v159 offset:1024
	ds_read_b128 v[160:163], v159 offset:2048
	ds_read_b128 v[164:167], v159 offset:3072
	s_add_u32 s30, s30, 0x40000
	s_addc_u32 s31, s31, 0
	s_mov_b32 m0, s39
	v_lshl_add_u64 v[208:209], s[30:31], 0, v[128:129]
	ds_read_b128 v[168:171], v156 offset:32768
	ds_read_b128 v[180:183], v156 offset:33792
	ds_read_b128 v[184:187], v156 offset:34816
	ds_read_b128 v[188:191], v156 offset:35840
	ds_read_b128 v[192:195], v156 offset:36864
	ds_read_b128 v[196:199], v156 offset:37888
	ds_read_b128 v[200:203], v156 offset:38912
	ds_read_b128 v[204:207], v156 offset:39936
	global_load_lds_dwordx4 v[208:209], off
	v_lshl_add_u64 v[208:209], s[30:31], 0, v[132:133]
	s_mov_b32 m0, s42
	s_nop 0
	global_load_lds_dwordx4 v[208:209], off
	s_waitcnt lgkmcnt(8)
	s_barrier
	s_waitcnt lgkmcnt(0)
	s_setprio 1
	s_waitcnt lgkmcnt(0)
	v_mfma_f32_16x16x32_bf16 v[124:127], v[144:147], v[168:171], v[124:127]
	v_mfma_f32_16x16x32_bf16 v[120:123], v[160:163], v[168:171], v[120:123]
	v_mfma_f32_16x16x32_bf16 v[108:111], v[144:147], v[184:187], v[108:111]
	v_mfma_f32_16x16x32_bf16 v[104:107], v[160:163], v[184:187], v[104:107]
	v_mfma_f32_16x16x32_bf16 v[92:95], v[144:147], v[192:195], v[92:95]
	v_mfma_f32_16x16x32_bf16 v[88:91], v[160:163], v[192:195], v[88:91]
	v_mfma_f32_16x16x32_bf16 v[76:79], v[144:147], v[200:203], v[76:79]
	v_mfma_f32_16x16x32_bf16 v[72:75], v[160:163], v[200:203], v[72:75]
	v_mfma_f32_16x16x32_bf16 v[124:127], v[148:151], v[180:183], v[124:127]
	v_mfma_f32_16x16x32_bf16 v[120:123], v[164:167], v[180:183], v[120:123]
	v_mfma_f32_16x16x32_bf16 v[108:111], v[148:151], v[188:191], v[108:111]
	v_mfma_f32_16x16x32_bf16 v[104:107], v[164:167], v[188:191], v[104:107]
	v_mfma_f32_16x16x32_bf16 v[92:95], v[148:151], v[196:199], v[92:95]
	v_mfma_f32_16x16x32_bf16 v[88:91], v[164:167], v[196:199], v[88:91]
	v_mfma_f32_16x16x32_bf16 v[76:79], v[148:151], v[204:207], v[76:79]
	v_mfma_f32_16x16x32_bf16 v[72:75], v[164:167], v[204:207], v[72:75]
	s_setprio 0
	s_barrier
	s_add_i32 s30, 0, 0x1c000
	s_add_i32 s31, s71, s33
	v_add_u32_e32 v159, s30, v153
	v_lshl_add_u64 v[172:173], v[172:173], 0, s[6:7]
	s_mov_b32 m0, s31
	ds_read_b128 v[208:211], v159
	ds_read_b128 v[212:215], v159 offset:1024
	ds_read_b128 v[216:219], v159 offset:2048
	ds_read_b128 v[220:223], v159 offset:3072
	global_load_lds_dwordx4 v[172:173], off
	v_lshl_add_u64 v[172:173], v[176:177], 0, s[6:7]
	s_add_i32 m0, s31, 0x2000
	s_nop 0
	global_load_lds_dwordx4 v[172:173], off
	s_barrier
	s_waitcnt lgkmcnt(0)
	s_setprio 1
	s_waitcnt lgkmcnt(0)
	v_mfma_f32_16x16x32_bf16 v[116:119], v[208:211], v[168:171], v[116:119]
	v_mfma_f32_16x16x32_bf16 v[112:115], v[216:219], v[168:171], v[112:115]
	v_mfma_f32_16x16x32_bf16 v[100:103], v[208:211], v[184:187], v[100:103]
	v_mfma_f32_16x16x32_bf16 v[96:99], v[216:219], v[184:187], v[96:99]
	v_mfma_f32_16x16x32_bf16 v[84:87], v[208:211], v[192:195], v[84:87]
	v_mfma_f32_16x16x32_bf16 v[80:83], v[216:219], v[192:195], v[80:83]
	v_mfma_f32_16x16x32_bf16 v[68:71], v[208:211], v[200:203], v[68:71]
	v_mfma_f32_16x16x32_bf16 v[64:67], v[216:219], v[200:203], v[64:67]
	v_mfma_f32_16x16x32_bf16 v[116:119], v[212:215], v[180:183], v[116:119]
	v_mfma_f32_16x16x32_bf16 v[112:115], v[220:223], v[180:183], v[112:115]
	v_mfma_f32_16x16x32_bf16 v[100:103], v[212:215], v[188:191], v[100:103]
	v_mfma_f32_16x16x32_bf16 v[96:99], v[220:223], v[188:191], v[96:99]
	v_mfma_f32_16x16x32_bf16 v[84:87], v[212:215], v[196:199], v[84:87]
	v_mfma_f32_16x16x32_bf16 v[80:83], v[220:223], v[196:199], v[80:83]
	v_mfma_f32_16x16x32_bf16 v[68:71], v[212:215], v[204:207], v[68:71]
	v_mfma_f32_16x16x32_bf16 v[64:67], v[220:223], v[204:207], v[64:67]
	s_setprio 0
	s_mov_b32 m0, s44
	v_lshl_add_u64 v[172:173], v[224:225], 0, s[6:7]
	s_barrier
	ds_read_b128 v[168:171], v156 offset:49152
	ds_read_b128 v[180:183], v156 offset:50176
	ds_read_b128 v[184:187], v156 offset:51200
	ds_read_b128 v[188:191], v156 offset:52224
	ds_read_b128 v[192:195], v156 offset:53248
	ds_read_b128 v[196:199], v156 offset:54272
	ds_read_b128 v[200:203], v156 offset:55296
	ds_read_b128 v[204:207], v156 offset:56320
	global_load_lds_dwordx4 v[172:173], off
	v_lshl_add_u64 v[172:173], v[226:227], 0, s[6:7]
	s_mov_b32 m0, s45
	s_nop 0
	global_load_lds_dwordx4 v[172:173], off
	s_barrier
; DI unsigned pk2(float a, float b) { f32x2 v = {a, b}; hbf2 r = __builtin_convertvector(v, hbf2); return __builtin_bit_cast(unsigned, r); }
; #define PG8_STAGE(bufoff, gbase, voff) do { _Pragma("unroll") for (int _i = 0; _i < 2; ++_i) \
;         __builtin_amdgcn_global_load_lds((const unsigned*)((const char*)(gbase) + (voff)[_i]), (LAS unsigned*)(lds + (bufoff) + ldsw + _i * 8192), 16, 0, 0); } while (0)
; #define PG8_MMA(ai, bj, At, Bt) do { __builtin_amdgcn_s_setprio(1); _Pragma("unroll") for (int m = 0; m < 4; ++m) _Pragma("unroll") for (int n = 0; n < 2; ++n) _Pragma("unroll") for (int k = 0; k < 2; ++k) \
;         acc[ai][bj][m][n] = __builtin_amdgcn_mfma_f32_16x16x32_bf16(Bt[n][k], At[m][k], acc[ai][bj][m][n], 0, 0, 0); __builtin_amdgcn_s_setprio(0); } while (0)
; #define PG8_WAIT_V(n) asm volatile("s_waitcnt vmcnt(" #n ")" ::: "memory")
; #define PG8_BAR __builtin_amdgcn_s_barrier()
; template <class Epi>
; __device__ __forceinline__ void gemm_phase(LAS unsigned char* lds, const Gemm g, const StaticOrder& S, const Epi& E) {
;     ...
;             PG8_STAGE(PG8_SB(1, 1), b3 + hstep, voffB);
;             PG8_WAIT_V(6); PG8_BAR; PG8_MMA(1, 1, At, B1); PG8_BAR;
;         }
;     DI void operator()(const f32x4 (&acc)[2][2][4][2], const Unit& u, int wr, int wc, int fr, int fq) const {
;         const int row0 = u.pm * 256 + wr * 64 + fr, col0 = u.pn * 256 + wc * 32 + 8 * fq;
; #pragma unroll
;         for (int ai = 0; ai < 2; ++ai)
; #pragma unroll
;             for (int m = 0; m < 4; ++m) {
;                 const int r = row0 + ai * 128 + m * 16;
;                 const float rstd = rsqrtf(ss[r] * (1.0f / 1024.0f) + EPS);
;                 bf16_t* rowp = HID + (size_t)r * 4096 + col0;
; #pragma unroll
;                 for (int bj = 0; bj < 2; ++bj) {
;                     f32x4 v0 = acc[ai][bj][m][0] * rstd, v1 = acc[ai][bj][m][1] * rstd;
; #pragma unroll
;                     for (int j = 0; j < 4; ++j) { float a = fmaxf(v0[j], 0.f), b = fmaxf(v1[j], 0.f); v0[j] = a * a; v1[j] = b * b; }
;                     u32x4 w; w.x = pk2(v0[0], v0[1]); w.y = pk2(v0[2], v0[3]); w.z = pk2(v1[0], v1[1]); w.w = pk2(v1[2], v1[3]);
;                     *(u32x4*)(rowp + bj * 128) = w;
;                 }
	s_waitcnt lgkmcnt(0)
	s_setprio 1
	s_waitcnt lgkmcnt(0)
	v_mfma_f32_16x16x32_bf16 v[60:63], v[144:147], v[168:171], v[60:63]
	v_mfma_f32_16x16x32_bf16 v[56:59], v[160:163], v[168:171], v[56:59]
	v_mfma_f32_16x16x32_bf16 v[44:47], v[144:147], v[184:187], v[44:47]
	v_mfma_f32_16x16x32_bf16 v[40:43], v[160:163], v[184:187], v[40:43]
	v_mfma_f32_16x16x32_bf16 v[28:31], v[144:147], v[192:195], v[28:31]
	v_mfma_f32_16x16x32_bf16 v[24:27], v[160:163], v[192:195], v[24:27]
	v_mfma_f32_16x16x32_bf16 v[12:15], v[144:147], v[200:203], v[12:15]
	v_mfma_f32_16x16x32_bf16 v[8:11], v[160:163], v[200:203], v[8:11]
	v_mfma_f32_16x16x32_bf16 v[60:63], v[148:151], v[180:183], v[60:63]
	v_mfma_f32_16x16x32_bf16 v[56:59], v[164:167], v[180:183], v[56:59]
	v_mfma_f32_16x16x32_bf16 v[44:47], v[148:151], v[188:191], v[44:47]
	v_mfma_f32_16x16x32_bf16 v[40:43], v[164:167], v[188:191], v[40:43]
	v_mfma_f32_16x16x32_bf16 v[28:31], v[148:151], v[196:199], v[28:31]
	v_mfma_f32_16x16x32_bf16 v[24:27], v[164:167], v[196:199], v[24:27]
	v_mfma_f32_16x16x32_bf16 v[12:15], v[148:151], v[204:207], v[12:15]
	v_mfma_f32_16x16x32_bf16 v[8:11], v[164:167], v[204:207], v[8:11]
	s_setprio 0
	s_barrier
	s_add_u32 s28, s28, 0x40080
	s_addc_u32 s29, s29, 0
	s_add_i32 s30, s30, s33
	v_lshl_add_u64 v[144:145], s[28:29], 0, v[130:131]
	s_mov_b32 m0, s30
	s_nop 0
	global_load_lds_dwordx4 v[144:145], off
	v_lshl_add_u64 v[144:145], s[28:29], 0, v[134:135]
	s_add_i32 m0, s30, 0x2000
	s_nop 0
	global_load_lds_dwordx4 v[144:145], off
	s_waitcnt vmcnt(6)
	s_barrier
	s_setprio 1
	v_mfma_f32_16x16x32_bf16 v[52:55], v[208:211], v[168:171], v[52:55]
	v_mfma_f32_16x16x32_bf16 v[48:51], v[216:219], v[168:171], v[48:51]
	v_mfma_f32_16x16x32_bf16 v[36:39], v[208:211], v[184:187], v[36:39]
	v_mfma_f32_16x16x32_bf16 v[32:35], v[216:219], v[184:187], v[32:35]
	v_mfma_f32_16x16x32_bf16 v[20:23], v[208:211], v[192:195], v[20:23]
	v_mfma_f32_16x16x32_bf16 v[16:19], v[216:219], v[192:195], v[16:19]
	v_mfma_f32_16x16x32_bf16 v[4:7], v[208:211], v[200:203], v[4:7]
	v_mfma_f32_16x16x32_bf16 v[0:3], v[216:219], v[200:203], v[0:3]
	v_mfma_f32_16x16x32_bf16 v[52:55], v[212:215], v[180:183], v[52:55]
	v_mfma_f32_16x16x32_bf16 v[48:51], v[220:223], v[180:183], v[48:51]
	v_mfma_f32_16x16x32_bf16 v[36:39], v[212:215], v[188:191], v[36:39]
	v_mfma_f32_16x16x32_bf16 v[32:35], v[220:223], v[188:191], v[32:35]
	v_mfma_f32_16x16x32_bf16 v[20:23], v[212:215], v[196:199], v[20:23]
	v_mfma_f32_16x16x32_bf16 v[16:19], v[220:223], v[196:199], v[16:19]
	v_mfma_f32_16x16x32_bf16 v[4:7], v[212:215], v[204:207], v[4:7]
	v_mfma_f32_16x16x32_bf16 v[0:3], v[220:223], v[204:207], v[0:3]
	s_setprio 0
	s_add_i32 s70, s70, 2
	s_add_u32 s0, s0, 0x100
	s_addc_u32 s1, s1, 0
	s_add_u32 s62, s62, 0x100
	s_addc_u32 s63, s63, 0
	s_cmp_gt_u32 s70, 13
	s_barrier
	s_cbranch_scc0 .LBB0_926
	v_lshl_add_u32 v148, s26, 8, v152
	v_ashrrev_i32_e32 v149, 31, v148
	v_lshl_add_u64 v[144:145], v[148:149], 2, s[94:95]
	global_load_dword v159, v[144:145], off
	global_load_dword v209, v[144:145], off offset:64
	global_load_dword v210, v[144:145], off offset:128
	global_load_dword v211, v[144:145], off offset:192
	global_load_dword v212, v[144:145], off offset:512
	global_load_dword v213, v[144:145], off offset:576
	global_load_dword v214, v[144:145], off offset:640
	global_load_dword v215, v[144:145], off offset:704
	v_lshl_or_b32 v146, s59, 8, v154
	v_ashrrev_i32_e32 v147, 31, v146
	v_lshlrev_b64 v[150:151], 1, v[146:147]
	v_lshlrev_b64 v[162:163], 13, v[148:149]
	v_or_b32_e32 v160, 16, v148
	v_ashrrev_i32_e32 v161, 31, v160
	s_mov_b32 s59, s18
	s_mov_b32 s26, s20
	s_mov_b64 s[28:29], s[24:25]
	s_mov_b64 s[30:31], s[22:23]
	s_waitcnt vmcnt(0)
	v_fmamk_f32 v146, v159, 0x3a800000, v158
	v_mul_f32_e32 v147, 0x4b800000, v146
	v_cmp_gt_f32_e32 vcc, s50, v146
	s_nop 1
	v_cndmask_b32_e32 v146, v146, v147, vcc
	v_rsq_f32_e32 v149, v146
	v_lshl_add_u64 v[146:147], s[34:35], 0, v[162:163]
	v_lshl_add_u64 v[146:147], v[146:147], 0, v[150:151]
	v_lshl_add_u64 v[162:163], v[160:161], 2, s[94:95]
	v_mul_f32_e32 v159, 0x45800000, v149
	v_cndmask_b32_e32 v164, v149, v159, vcc
	v_pk_mul_f32 v[126:127], v[126:127], v[164:165] op_sel_hi:[1,0]
	v_pk_mul_f32 v[124:125], v[124:125], v[164:165] op_sel_hi:[1,0]
	v_pk_mul_f32 v[122:123], v[122:123], v[164:165] op_sel_hi:[1,0]
	v_pk_mul_f32 v[120:121], v[120:121], v[164:165] op_sel_hi:[1,0]
	v_pk_mul_f32 v[118:119], v[118:119], v[164:165] op_sel_hi:[1,0]
	v_pk_mul_f32 v[116:117], v[116:117], v[164:165] op_sel_hi:[1,0]
	v_pk_mul_f32 v[114:115], v[114:115], v[164:165] op_sel_hi:[1,0]
	v_pk_mul_f32 v[112:113], v[112:113], v[164:165] op_sel_hi:[1,0]
	v_max_f32_e32 v124, 0, v124
	v_max_f32_e32 v120, 0, v120
	v_max_f32_e32 v125, 0, v125
	v_max_f32_e32 v121, 0, v121
	v_max_f32_e32 v126, 0, v126
	v_max_f32_e32 v122, 0, v122
	v_max_f32_e32 v127, 0, v127
	v_max_f32_e32 v123, 0, v123
	v_max_f32_e32 v116, 0, v116
	v_max_f32_e32 v112, 0, v112
	v_max_f32_e32 v117, 0, v117
	v_max_f32_e32 v113, 0, v113
	v_max_f32_e32 v118, 0, v118
	v_max_f32_e32 v114, 0, v114
	v_max_f32_e32 v119, 0, v119
	v_max_f32_e32 v115, 0, v115
	v_pk_mul_f32 v[124:125], v[124:125], v[124:125]
	v_pk_mul_f32 v[120:121], v[120:121], v[120:121]
	v_pk_mul_f32 v[126:127], v[126:127], v[126:127]
	v_pk_mul_f32 v[122:123], v[122:123], v[122:123]
	v_pk_mul_f32 v[116:117], v[116:117], v[116:117]
	v_pk_mul_f32 v[164:165], v[112:113], v[112:113]
	v_pk_mul_f32 v[118:119], v[118:119], v[118:119]
	v_pk_mul_f32 v[166:167], v[114:115], v[114:115]
	v_cvt_pk_bf16_f32 v112, v124, v125
	v_cvt_pk_bf16_f32 v113, v126, v127
	v_cvt_pk_bf16_f32 v114, v120, v121
	v_cvt_pk_bf16_f32 v115, v122, v123
; DI unsigned pk2(float a, float b) { f32x2 v = {a, b}; hbf2 r = __builtin_convertvector(v, hbf2); return __builtin_bit_cast(unsigned, r); }
;     DI void operator()(const f32x4 (&acc)[2][2][4][2], const Unit& u, int wr, int wc, int fr, int fq) const {
;     ...
;             for (int m = 0; m < 4; ++m) {
;                 const int r = row0 + ai * 128 + m * 16;
;                 const float rstd = rsqrtf(ss[r] * (1.0f / 1024.0f) + EPS);
;                 bf16_t* rowp = HID + (size_t)r * 4096 + col0;
; #pragma unroll
;                 for (int bj = 0; bj < 2; ++bj) {
;                     f32x4 v0 = acc[ai][bj][m][0] * rstd, v1 = acc[ai][bj][m][1] * rstd;
; #pragma unroll
;                     for (int j = 0; j < 4; ++j) { float a = fmaxf(v0[j], 0.f), b = fmaxf(v1[j], 0.f); v0[j] = a * a; v1[j] = b * b; }
;                     u32x4 w; w.x = pk2(v0[0], v0[1]); w.y = pk2(v0[2], v0[3]); w.z = pk2(v1[0], v1[1]); w.w = pk2(v1[2], v1[3]);
;                     *(u32x4*)(rowp + bj * 128) = w;
;                 }
	v_cvt_pk_bf16_f32 v116, v116, v117
	v_cvt_pk_bf16_f32 v117, v118, v119
	v_cvt_pk_bf16_f32 v118, v164, v165
	v_cvt_pk_bf16_f32 v119, v166, v167
	global_store_dwordx4 v[146:147], v[112:115], off
	global_store_dwordx4 v[146:147], v[116:119], off offset:256
	s_nop 0
	v_lshlrev_b64 v[114:115], 13, v[160:161]
	v_or_b32_e32 v112, 32, v148
	v_lshl_add_u64 v[114:115], s[34:35], 0, v[114:115]
	v_ashrrev_i32_e32 v113, 31, v112
	v_lshl_add_u64 v[114:115], v[114:115], 0, v[150:151]
	s_nop 1
	v_mov_b32_e32 v116, v209
	v_fmamk_f32 v116, v116, 0x3a800000, v158
	v_mul_f32_e32 v117, 0x4b800000, v116
	v_cmp_gt_f32_e32 vcc, s50, v116
	s_nop 1
	v_cndmask_b32_e32 v116, v116, v117, vcc
	v_rsq_f32_e32 v118, v116
	v_lshl_add_u64 v[116:117], v[112:113], 2, s[94:95]
	v_mul_f32_e32 v119, 0x45800000, v118
	v_cndmask_b32_e32 v118, v118, v119, vcc
	v_pk_mul_f32 v[110:111], v[110:111], v[118:119] op_sel_hi:[1,0]
	v_pk_mul_f32 v[108:109], v[108:109], v[118:119] op_sel_hi:[1,0]
	v_pk_mul_f32 v[106:107], v[106:107], v[118:119] op_sel_hi:[1,0]
	v_pk_mul_f32 v[104:105], v[104:105], v[118:119] op_sel_hi:[1,0]
	v_pk_mul_f32 v[102:103], v[102:103], v[118:119] op_sel_hi:[1,0]
	v_pk_mul_f32 v[100:101], v[100:101], v[118:119] op_sel_hi:[1,0]
	v_pk_mul_f32 v[98:99], v[98:99], v[118:119] op_sel_hi:[1,0]
	v_pk_mul_f32 v[96:97], v[96:97], v[118:119] op_sel_hi:[1,0]
	v_max_f32_e32 v108, 0, v108
	v_max_f32_e32 v104, 0, v104
	v_max_f32_e32 v109, 0, v109
	v_max_f32_e32 v105, 0, v105
	v_max_f32_e32 v110, 0, v110
	v_max_f32_e32 v106, 0, v106
	v_max_f32_e32 v111, 0, v111
	v_max_f32_e32 v107, 0, v107
	v_max_f32_e32 v100, 0, v100
	v_max_f32_e32 v96, 0, v96
	v_max_f32_e32 v101, 0, v101
	v_max_f32_e32 v97, 0, v97
	v_max_f32_e32 v102, 0, v102
	v_max_f32_e32 v98, 0, v98
	v_max_f32_e32 v103, 0, v103
	v_max_f32_e32 v99, 0, v99
	v_pk_mul_f32 v[108:109], v[108:109], v[108:109]
	v_pk_mul_f32 v[104:105], v[104:105], v[104:105]
	v_pk_mul_f32 v[110:111], v[110:111], v[110:111]
	v_pk_mul_f32 v[106:107], v[106:107], v[106:107]
	v_pk_mul_f32 v[100:101], v[100:101], v[100:101]
	v_pk_mul_f32 v[118:119], v[96:97], v[96:97]
	v_pk_mul_f32 v[102:103], v[102:103], v[102:103]
	v_pk_mul_f32 v[120:121], v[98:99], v[98:99]
	v_cvt_pk_bf16_f32 v96, v108, v109
	v_cvt_pk_bf16_f32 v97, v110, v111
	v_cvt_pk_bf16_f32 v98, v104, v105
	v_cvt_pk_bf16_f32 v99, v106, v107
	v_cvt_pk_bf16_f32 v100, v100, v101
	v_cvt_pk_bf16_f32 v101, v102, v103
	v_cvt_pk_bf16_f32 v102, v118, v119
	v_cvt_pk_bf16_f32 v103, v120, v121
	global_store_dwordx4 v[114:115], v[96:99], off
	global_store_dwordx4 v[114:115], v[100:103], off offset:256
	s_nop 0
	v_lshlrev_b64 v[98:99], 13, v[112:113]
	v_or_b32_e32 v96, 48, v148
	v_lshl_add_u64 v[98:99], s[34:35], 0, v[98:99]
	v_ashrrev_i32_e32 v97, 31, v96
	v_lshl_add_u64 v[98:99], v[98:99], 0, v[150:151]
	s_nop 1
	v_mov_b32_e32 v100, v210
	v_fmamk_f32 v100, v100, 0x3a800000, v158
	v_mul_f32_e32 v101, 0x4b800000, v100
	v_cmp_gt_f32_e32 vcc, s50, v100
	s_nop 1
	v_cndmask_b32_e32 v100, v100, v101, vcc
	v_rsq_f32_e32 v102, v100
	v_lshl_add_u64 v[100:101], v[96:97], 2, s[94:95]
	v_mul_f32_e32 v103, 0x45800000, v102
	v_cndmask_b32_e32 v102, v102, v103, vcc
	v_pk_mul_f32 v[94:95], v[94:95], v[102:103] op_sel_hi:[1,0]
	v_pk_mul_f32 v[92:93], v[92:93], v[102:103] op_sel_hi:[1,0]
	v_pk_mul_f32 v[90:91], v[90:91], v[102:103] op_sel_hi:[1,0]
	v_pk_mul_f32 v[88:89], v[88:89], v[102:103] op_sel_hi:[1,0]
	v_pk_mul_f32 v[86:87], v[86:87], v[102:103] op_sel_hi:[1,0]
	v_pk_mul_f32 v[84:85], v[84:85], v[102:103] op_sel_hi:[1,0]
	v_pk_mul_f32 v[82:83], v[82:83], v[102:103] op_sel_hi:[1,0]
	v_pk_mul_f32 v[80:81], v[80:81], v[102:103] op_sel_hi:[1,0]
	v_max_f32_e32 v92, 0, v92
	v_max_f32_e32 v88, 0, v88
	v_max_f32_e32 v93, 0, v93
	v_max_f32_e32 v89, 0, v89
	v_max_f32_e32 v94, 0, v94
	v_max_f32_e32 v90, 0, v90
	v_max_f32_e32 v95, 0, v95
	v_max_f32_e32 v91, 0, v91
	v_max_f32_e32 v84, 0, v84
	v_max_f32_e32 v80, 0, v80
	v_max_f32_e32 v85, 0, v85
	v_max_f32_e32 v81, 0, v81
	v_max_f32_e32 v86, 0, v86
	v_max_f32_e32 v82, 0, v82
	v_max_f32_e32 v87, 0, v87
	v_max_f32_e32 v83, 0, v83
	v_pk_mul_f32 v[92:93], v[92:93], v[92:93]
	v_pk_mul_f32 v[88:89], v[88:89], v[88:89]
	v_pk_mul_f32 v[94:95], v[94:95], v[94:95]
	v_pk_mul_f32 v[90:91], v[90:91], v[90:91]
	v_pk_mul_f32 v[84:85], v[84:85], v[84:85]
	v_pk_mul_f32 v[102:103], v[80:81], v[80:81]
	v_pk_mul_f32 v[86:87], v[86:87], v[86:87]
	v_pk_mul_f32 v[104:105], v[82:83], v[82:83]
	v_cvt_pk_bf16_f32 v80, v92, v93
	v_cvt_pk_bf16_f32 v81, v94, v95
	v_cvt_pk_bf16_f32 v82, v88, v89
	v_cvt_pk_bf16_f32 v83, v90, v91
	v_cvt_pk_bf16_f32 v84, v84, v85
	v_cvt_pk_bf16_f32 v85, v86, v87
	v_cvt_pk_bf16_f32 v86, v102, v103
	v_cvt_pk_bf16_f32 v87, v104, v105
	global_store_dwordx4 v[98:99], v[80:83], off
	global_store_dwordx4 v[98:99], v[84:87], off offset:256
	s_nop 0
	s_nop 1
	v_mov_b32_e32 v80, v211
	v_fmamk_f32 v80, v80, 0x3a800000, v158
	v_mul_f32_e32 v81, 0x4b800000, v80
	v_cmp_gt_f32_e32 vcc, s50, v80
	s_nop 1
	v_cndmask_b32_e32 v80, v80, v81, vcc
	v_rsq_f32_e32 v82, v80
	v_lshlrev_b64 v[80:81], 13, v[96:97]
	v_lshl_add_u64 v[80:81], s[34:35], 0, v[80:81]
	v_lshl_add_u64 v[80:81], v[80:81], 0, v[150:151]
	v_mul_f32_e32 v83, 0x45800000, v82
	v_cndmask_b32_e32 v82, v82, v83, vcc
	v_pk_mul_f32 v[78:79], v[78:79], v[82:83] op_sel_hi:[1,0]
	v_pk_mul_f32 v[76:77], v[76:77], v[82:83] op_sel_hi:[1,0]
	v_pk_mul_f32 v[74:75], v[74:75], v[82:83] op_sel_hi:[1,0]
	v_pk_mul_f32 v[72:73], v[72:73], v[82:83] op_sel_hi:[1,0]
	v_pk_mul_f32 v[70:71], v[70:71], v[82:83] op_sel_hi:[1,0]
	v_pk_mul_f32 v[68:69], v[68:69], v[82:83] op_sel_hi:[1,0]
	v_pk_mul_f32 v[66:67], v[66:67], v[82:83] op_sel_hi:[1,0]
; DI unsigned pk2(float a, float b) { f32x2 v = {a, b}; hbf2 r = __builtin_convertvector(v, hbf2); return __builtin_bit_cast(unsigned, r); }
;     DI void operator()(const f32x4 (&acc)[2][2][4][2], const Unit& u, int wr, int wc, int fr, int fq) const {
;     ...
;             for (int m = 0; m < 4; ++m) {
;                 const int r = row0 + ai * 128 + m * 16;
;                 const float rstd = rsqrtf(ss[r] * (1.0f / 1024.0f) + EPS);
;                 bf16_t* rowp = HID + (size_t)r * 4096 + col0;
; #pragma unroll
;                 for (int bj = 0; bj < 2; ++bj) {
;                     f32x4 v0 = acc[ai][bj][m][0] * rstd, v1 = acc[ai][bj][m][1] * rstd;
; #pragma unroll
;                     for (int j = 0; j < 4; ++j) { float a = fmaxf(v0[j], 0.f), b = fmaxf(v1[j], 0.f); v0[j] = a * a; v1[j] = b * b; }
;                     u32x4 w; w.x = pk2(v0[0], v0[1]); w.y = pk2(v0[2], v0[3]); w.z = pk2(v1[0], v1[1]); w.w = pk2(v1[2], v1[3]);
;                     *(u32x4*)(rowp + bj * 128) = w;
;                 }
	v_pk_mul_f32 v[64:65], v[64:65], v[82:83] op_sel_hi:[1,0]
	v_max_f32_e32 v76, 0, v76
	v_max_f32_e32 v72, 0, v72
	v_max_f32_e32 v77, 0, v77
	v_max_f32_e32 v73, 0, v73
	v_max_f32_e32 v78, 0, v78
	v_max_f32_e32 v74, 0, v74
	v_max_f32_e32 v79, 0, v79
	v_max_f32_e32 v75, 0, v75
	v_max_f32_e32 v68, 0, v68
	v_max_f32_e32 v64, 0, v64
	v_max_f32_e32 v69, 0, v69
	v_max_f32_e32 v65, 0, v65
	v_max_f32_e32 v70, 0, v70
	v_max_f32_e32 v66, 0, v66
	v_max_f32_e32 v71, 0, v71
	v_max_f32_e32 v67, 0, v67
	v_pk_mul_f32 v[76:77], v[76:77], v[76:77]
	v_pk_mul_f32 v[72:73], v[72:73], v[72:73]
	v_pk_mul_f32 v[78:79], v[78:79], v[78:79]
	v_pk_mul_f32 v[74:75], v[74:75], v[74:75]
	v_pk_mul_f32 v[68:69], v[68:69], v[68:69]
	v_pk_mul_f32 v[82:83], v[64:65], v[64:65]
	v_pk_mul_f32 v[70:71], v[70:71], v[70:71]
	v_pk_mul_f32 v[84:85], v[66:67], v[66:67]
	v_cvt_pk_bf16_f32 v64, v76, v77
	v_cvt_pk_bf16_f32 v65, v78, v79
	v_cvt_pk_bf16_f32 v66, v72, v73
	v_cvt_pk_bf16_f32 v67, v74, v75
	v_cvt_pk_bf16_f32 v68, v68, v69
	v_cvt_pk_bf16_f32 v69, v70, v71
	v_cvt_pk_bf16_f32 v70, v82, v83
	v_cvt_pk_bf16_f32 v71, v84, v85
	global_store_dwordx4 v[80:81], v[64:67], off
	global_store_dwordx4 v[80:81], v[68:71], off offset:256
	s_nop 0
	v_lshl_add_u64 v[64:65], v[146:147], 0, s[8:9]
	s_nop 1
	v_mov_b32_e32 v66, v212
	v_fmamk_f32 v66, v66, 0x3a800000, v158
	v_mul_f32_e32 v67, 0x4b800000, v66
	v_cmp_gt_f32_e32 vcc, s50, v66
	s_nop 1
	v_cndmask_b32_e32 v66, v66, v67, vcc
	v_rsq_f32_e32 v68, v66
	v_add_co_u32_e64 v66, s[0:1], s51, v146
	v_mul_f32_e32 v69, 0x45800000, v68
	v_cndmask_b32_e32 v68, v68, v69, vcc
	v_pk_mul_f32 v[62:63], v[62:63], v[68:69] op_sel_hi:[1,0]
	v_pk_mul_f32 v[60:61], v[60:61], v[68:69] op_sel_hi:[1,0]
	v_pk_mul_f32 v[58:59], v[58:59], v[68:69] op_sel_hi:[1,0]
	v_pk_mul_f32 v[56:57], v[56:57], v[68:69] op_sel_hi:[1,0]
	v_pk_mul_f32 v[54:55], v[54:55], v[68:69] op_sel_hi:[1,0]
	v_pk_mul_f32 v[52:53], v[52:53], v[68:69] op_sel_hi:[1,0]
	v_pk_mul_f32 v[50:51], v[50:51], v[68:69] op_sel_hi:[1,0]
	v_pk_mul_f32 v[48:49], v[48:49], v[68:69] op_sel_hi:[1,0]
	v_max_f32_e32 v60, 0, v60
	v_max_f32_e32 v56, 0, v56
	v_max_f32_e32 v61, 0, v61
	v_max_f32_e32 v57, 0, v57
	v_max_f32_e32 v62, 0, v62
	v_max_f32_e32 v58, 0, v58
	v_max_f32_e32 v63, 0, v63
	v_max_f32_e32 v59, 0, v59
	v_max_f32_e32 v52, 0, v52
	v_max_f32_e32 v48, 0, v48
	v_max_f32_e32 v53, 0, v53
	v_max_f32_e32 v49, 0, v49
	v_max_f32_e32 v54, 0, v54
	v_max_f32_e32 v50, 0, v50
	v_max_f32_e32 v55, 0, v55
	v_max_f32_e32 v51, 0, v51
	v_pk_mul_f32 v[60:61], v[60:61], v[60:61]
	v_pk_mul_f32 v[56:57], v[56:57], v[56:57]
	v_pk_mul_f32 v[62:63], v[62:63], v[62:63]
	v_pk_mul_f32 v[58:59], v[58:59], v[58:59]
	v_addc_co_u32_e64 v67, s[0:1], 0, v147, s[0:1]
	v_pk_mul_f32 v[52:53], v[52:53], v[52:53]
	v_pk_mul_f32 v[68:69], v[48:49], v[48:49]
	v_pk_mul_f32 v[54:55], v[54:55], v[54:55]
	v_pk_mul_f32 v[70:71], v[50:51], v[50:51]
	v_cvt_pk_bf16_f32 v48, v60, v61
	v_cvt_pk_bf16_f32 v49, v62, v63
	v_cvt_pk_bf16_f32 v50, v56, v57
	v_cvt_pk_bf16_f32 v51, v58, v59
	v_cvt_pk_bf16_f32 v52, v52, v53
	v_cvt_pk_bf16_f32 v53, v54, v55
	v_cvt_pk_bf16_f32 v54, v68, v69
	v_cvt_pk_bf16_f32 v55, v70, v71
	global_store_dwordx4 v[66:67], v[48:51], off
	global_store_dwordx4 v[64:65], v[52:55], off offset:256
	s_nop 0
	v_lshl_add_u64 v[48:49], v[146:147], 0, s[10:11]
	s_nop 1
	v_mov_b32_e32 v50, v213
	v_fmamk_f32 v50, v50, 0x3a800000, v158
	v_mul_f32_e32 v51, 0x4b800000, v50
	v_cmp_gt_f32_e32 vcc, s50, v50
	s_nop 1
	v_cndmask_b32_e32 v50, v50, v51, vcc
	v_rsq_f32_e32 v52, v50
	v_add_co_u32_e64 v50, s[0:1], s56, v146
	v_mul_f32_e32 v53, 0x45800000, v52
	v_cndmask_b32_e32 v52, v52, v53, vcc
	v_pk_mul_f32 v[46:47], v[46:47], v[52:53] op_sel_hi:[1,0]
	v_pk_mul_f32 v[44:45], v[44:45], v[52:53] op_sel_hi:[1,0]
	v_pk_mul_f32 v[42:43], v[42:43], v[52:53] op_sel_hi:[1,0]
	v_pk_mul_f32 v[40:41], v[40:41], v[52:53] op_sel_hi:[1,0]
	v_pk_mul_f32 v[38:39], v[38:39], v[52:53] op_sel_hi:[1,0]
	v_pk_mul_f32 v[36:37], v[36:37], v[52:53] op_sel_hi:[1,0]
	v_pk_mul_f32 v[34:35], v[34:35], v[52:53] op_sel_hi:[1,0]
	v_pk_mul_f32 v[32:33], v[32:33], v[52:53] op_sel_hi:[1,0]
	v_max_f32_e32 v44, 0, v44
	v_max_f32_e32 v40, 0, v40
	v_max_f32_e32 v45, 0, v45
	v_max_f32_e32 v41, 0, v41
	v_max_f32_e32 v46, 0, v46
	v_max_f32_e32 v42, 0, v42
	v_max_f32_e32 v47, 0, v47
	v_max_f32_e32 v43, 0, v43
	v_max_f32_e32 v36, 0, v36
	v_max_f32_e32 v32, 0, v32
	v_max_f32_e32 v37, 0, v37
	v_max_f32_e32 v33, 0, v33
	v_max_f32_e32 v38, 0, v38
	v_max_f32_e32 v34, 0, v34
	v_max_f32_e32 v39, 0, v39
	v_max_f32_e32 v35, 0, v35
	v_pk_mul_f32 v[44:45], v[44:45], v[44:45]
	v_pk_mul_f32 v[40:41], v[40:41], v[40:41]
	v_pk_mul_f32 v[46:47], v[46:47], v[46:47]
	v_pk_mul_f32 v[42:43], v[42:43], v[42:43]
; DI unsigned pk2(float a, float b) { f32x2 v = {a, b}; hbf2 r = __builtin_convertvector(v, hbf2); return __builtin_bit_cast(unsigned, r); }
;     DI void operator()(const f32x4 (&acc)[2][2][4][2], const Unit& u, int wr, int wc, int fr, int fq) const {
;     ...
;             for (int m = 0; m < 4; ++m) {
;                 const int r = row0 + ai * 128 + m * 16;
;                 const float rstd = rsqrtf(ss[r] * (1.0f / 1024.0f) + EPS);
;                 bf16_t* rowp = HID + (size_t)r * 4096 + col0;
; #pragma unroll
;                 for (int bj = 0; bj < 2; ++bj) {
;                     f32x4 v0 = acc[ai][bj][m][0] * rstd, v1 = acc[ai][bj][m][1] * rstd;
; #pragma unroll
;                     for (int j = 0; j < 4; ++j) { float a = fmaxf(v0[j], 0.f), b = fmaxf(v1[j], 0.f); v0[j] = a * a; v1[j] = b * b; }
;                     u32x4 w; w.x = pk2(v0[0], v0[1]); w.y = pk2(v0[2], v0[3]); w.z = pk2(v1[0], v1[1]); w.w = pk2(v1[2], v1[3]);
;                     *(u32x4*)(rowp + bj * 128) = w;
;                 }
	v_addc_co_u32_e64 v51, s[0:1], 0, v147, s[0:1]
	v_pk_mul_f32 v[36:37], v[36:37], v[36:37]
	v_pk_mul_f32 v[52:53], v[32:33], v[32:33]
	v_pk_mul_f32 v[38:39], v[38:39], v[38:39]
	v_pk_mul_f32 v[54:55], v[34:35], v[34:35]
	v_cvt_pk_bf16_f32 v32, v44, v45
	v_cvt_pk_bf16_f32 v33, v46, v47
	v_cvt_pk_bf16_f32 v34, v40, v41
	v_cvt_pk_bf16_f32 v35, v42, v43
	v_cvt_pk_bf16_f32 v36, v36, v37
	v_cvt_pk_bf16_f32 v37, v38, v39
	v_cvt_pk_bf16_f32 v38, v52, v53
	v_cvt_pk_bf16_f32 v39, v54, v55
	global_store_dwordx4 v[50:51], v[32:35], off
	global_store_dwordx4 v[48:49], v[36:39], off offset:256
	s_nop 0
	v_lshl_add_u64 v[32:33], v[146:147], 0, s[12:13]
	s_nop 1
	v_mov_b32_e32 v34, v214
	v_fmamk_f32 v34, v34, 0x3a800000, v158
	v_mul_f32_e32 v35, 0x4b800000, v34
	v_cmp_gt_f32_e32 vcc, s50, v34
	s_nop 1
	v_cndmask_b32_e32 v34, v34, v35, vcc
	v_rsq_f32_e32 v36, v34
	v_add_co_u32_e64 v34, s[0:1], s57, v146
	v_mul_f32_e32 v37, 0x45800000, v36
	v_cndmask_b32_e32 v36, v36, v37, vcc
	v_pk_mul_f32 v[30:31], v[30:31], v[36:37] op_sel_hi:[1,0]
	v_pk_mul_f32 v[28:29], v[28:29], v[36:37] op_sel_hi:[1,0]
	v_pk_mul_f32 v[26:27], v[26:27], v[36:37] op_sel_hi:[1,0]
	v_pk_mul_f32 v[24:25], v[24:25], v[36:37] op_sel_hi:[1,0]
	v_pk_mul_f32 v[22:23], v[22:23], v[36:37] op_sel_hi:[1,0]
	v_pk_mul_f32 v[20:21], v[20:21], v[36:37] op_sel_hi:[1,0]
	v_pk_mul_f32 v[18:19], v[18:19], v[36:37] op_sel_hi:[1,0]
	v_pk_mul_f32 v[16:17], v[16:17], v[36:37] op_sel_hi:[1,0]
	v_max_f32_e32 v28, 0, v28
	v_max_f32_e32 v24, 0, v24
	v_max_f32_e32 v29, 0, v29
	v_max_f32_e32 v25, 0, v25
	v_max_f32_e32 v30, 0, v30
	v_max_f32_e32 v26, 0, v26
	v_max_f32_e32 v31, 0, v31
	v_max_f32_e32 v27, 0, v27
	v_max_f32_e32 v20, 0, v20
	v_max_f32_e32 v16, 0, v16
	v_max_f32_e32 v21, 0, v21
	v_max_f32_e32 v17, 0, v17
	v_max_f32_e32 v22, 0, v22
	v_max_f32_e32 v18, 0, v18
	v_max_f32_e32 v23, 0, v23
	v_max_f32_e32 v19, 0, v19
	v_pk_mul_f32 v[28:29], v[28:29], v[28:29]
	v_pk_mul_f32 v[24:25], v[24:25], v[24:25]
	v_pk_mul_f32 v[30:31], v[30:31], v[30:31]
	v_pk_mul_f32 v[26:27], v[26:27], v[26:27]
	v_addc_co_u32_e64 v35, s[0:1], 0, v147, s[0:1]
	v_pk_mul_f32 v[20:21], v[20:21], v[20:21]
	v_pk_mul_f32 v[36:37], v[16:17], v[16:17]
	v_pk_mul_f32 v[22:23], v[22:23], v[22:23]
	v_pk_mul_f32 v[38:39], v[18:19], v[18:19]
	v_cvt_pk_bf16_f32 v16, v28, v29
	v_cvt_pk_bf16_f32 v17, v30, v31
	v_cvt_pk_bf16_f32 v18, v24, v25
	v_cvt_pk_bf16_f32 v19, v26, v27
	v_cvt_pk_bf16_f32 v20, v20, v21
	v_cvt_pk_bf16_f32 v21, v22, v23
	v_cvt_pk_bf16_f32 v22, v36, v37
	v_cvt_pk_bf16_f32 v23, v38, v39
	global_store_dwordx4 v[34:35], v[16:19], off
	global_store_dwordx4 v[32:33], v[20:23], off offset:256
	s_nop 0
	s_and_b64 vcc, exec, s[4:5]
	v_lshl_add_u64 v[16:17], v[146:147], 0, s[14:15]
	s_nop 1
	v_mov_b32_e32 v18, v215
	v_fmamk_f32 v18, v18, 0x3a800000, v158
	v_mul_f32_e32 v19, 0x4b800000, v18
	v_cmp_gt_f32_e64 s[0:1], s50, v18
	s_nop 1
	v_cndmask_b32_e64 v18, v18, v19, s[0:1]
	v_rsq_f32_e32 v20, v18
	v_add_co_u32_e64 v18, s[4:5], s58, v146
	v_mul_f32_e32 v21, 0x45800000, v20
	v_cndmask_b32_e64 v20, v20, v21, s[0:1]
	v_pk_mul_f32 v[14:15], v[14:15], v[20:21] op_sel_hi:[1,0]
	v_pk_mul_f32 v[12:13], v[12:13], v[20:21] op_sel_hi:[1,0]
	v_pk_mul_f32 v[10:11], v[10:11], v[20:21] op_sel_hi:[1,0]
	v_pk_mul_f32 v[8:9], v[8:9], v[20:21] op_sel_hi:[1,0]
	v_pk_mul_f32 v[6:7], v[6:7], v[20:21] op_sel_hi:[1,0]
	v_pk_mul_f32 v[4:5], v[4:5], v[20:21] op_sel_hi:[1,0]
	v_pk_mul_f32 v[2:3], v[2:3], v[20:21] op_sel_hi:[1,0]
	v_pk_mul_f32 v[0:1], v[0:1], v[20:21] op_sel_hi:[1,0]
	v_max_f32_e32 v12, 0, v12
	v_max_f32_e32 v8, 0, v8
	v_max_f32_e32 v13, 0, v13
	v_max_f32_e32 v9, 0, v9
	v_max_f32_e32 v14, 0, v14
	v_max_f32_e32 v10, 0, v10
	v_max_f32_e32 v15, 0, v15
	v_max_f32_e32 v11, 0, v11
	v_max_f32_e32 v4, 0, v4
	v_max_f32_e32 v0, 0, v0
	v_max_f32_e32 v5, 0, v5
	v_max_f32_e32 v1, 0, v1
	v_max_f32_e32 v6, 0, v6
	v_max_f32_e32 v2, 0, v2
	v_max_f32_e32 v7, 0, v7
	v_max_f32_e32 v3, 0, v3
	v_pk_mul_f32 v[12:13], v[12:13], v[12:13]
	v_pk_mul_f32 v[8:9], v[8:9], v[8:9]
	v_pk_mul_f32 v[14:15], v[14:15], v[14:15]
	v_pk_mul_f32 v[10:11], v[10:11], v[10:11]
	v_addc_co_u32_e64 v19, s[4:5], 0, v147, s[4:5]
	v_pk_mul_f32 v[4:5], v[4:5], v[4:5]
	v_pk_mul_f32 v[20:21], v[0:1], v[0:1]
	v_pk_mul_f32 v[6:7], v[6:7], v[6:7]
	v_pk_mul_f32 v[22:23], v[2:3], v[2:3]
	v_cvt_pk_bf16_f32 v0, v12, v13
	v_cvt_pk_bf16_f32 v1, v14, v15
	v_cvt_pk_bf16_f32 v2, v8, v9
	v_cvt_pk_bf16_f32 v3, v10, v11
	v_cvt_pk_bf16_f32 v4, v4, v5
	v_cvt_pk_bf16_f32 v5, v6, v7
	v_cvt_pk_bf16_f32 v6, v20, v21
	v_cvt_pk_bf16_f32 v7, v22, v23
	global_store_dwordx4 v[18:19], v[0:3], off
	global_store_dwordx4 v[16:17], v[4:7], off offset:256
	s_cbranch_vccz .LBB0_919
	s_waitcnt vmcnt(0)
	s_cmpk_gt_u32 s2, 0xff
	s_cbranch_scc1 .LBB0_930
	s_barrier

; #define PG8_STAGE(bufoff, gbase, voff) do { _Pragma("unroll") for (int _i = 0; _i < 2; ++_i) \
;         __builtin_amdgcn_global_load_lds((const unsigned*)((const char*)(gbase) + (voff)[_i]), (LAS unsigned*)(lds + (bufoff) + ldsw + _i * 8192), 16, 0, 0); } while (0)
; #define PG8_LDA(dst, b, h) do { _Pragma("unroll") for (int m = 0; m < 4; ++m) _Pragma("unroll") for (int k = 0; k < 2; ++k) dst[m][k] = *(const LAS bf16x8*)(lds + PG8_SA(b, h) + aoff + m * 2048 + k * 1024); } while (0)
; #define PG8_LDB(dst, b, h) do { _Pragma("unroll") for (int n = 0; n < 2; ++n) _Pragma("unroll") for (int k = 0; k < 2; ++k) dst[n][k] = *(const LAS bf16x8*)(lds + PG8_SB(b, h) + boff + n * 2048 + k * 1024); } while (0)
; #define PG8_MMA(ai, bj, At, Bt) do { __builtin_amdgcn_s_setprio(1); _Pragma("unroll") for (int m = 0; m < 4; ++m) _Pragma("unroll") for (int n = 0; n < 2; ++n) _Pragma("unroll") for (int k = 0; k < 2; ++k) \
;         acc[ai][bj][m][n] = __builtin_amdgcn_mfma_f32_16x16x32_bf16(Bt[n][k], At[m][k], acc[ai][bj][m][n], 0, 0, 0); __builtin_amdgcn_s_setprio(0); } while (0)
; #define PG8_WAIT_L(n) asm volatile("s_waitcnt lgkmcnt(" #n ")" ::: "memory")
; #define PG8_BAR __builtin_amdgcn_s_barrier()
; #define PG8_SCHED __builtin_amdgcn_sched_barrier(0)
; template <class Epi>
; __device__ __forceinline__ void gemm_phase(LAS unsigned char* lds, const Gemm g, const StaticOrder& S, const Epi& E) {
;     ...
;         for (int t = 0; t < nt; t += 2) {
;             const bool last = (t == nt - 2);
;             const char* a1 = cA + (size_t)(t + 1) * kstep;
;             const char* a2 = last ? nA : cA + (size_t)(t + 2) * kstep; const char* b2 = last ? nB : cB + (size_t)(t + 2) * kstep;
;             const char* a3 = a2 + kstep; const char* b3 = b2 + kstep;
;             PG8_LDB(B0, 0, 0); PG8_SCHED; PG8_LDA(At, 0, 0); PG8_STAGE(PG8_SA(1, 1), a1 + hstep, voffA);
;             PG8_WAIT_L(8); PG8_BAR; PG8_WAIT_L(0); PG8_MMA(0, 0, At, B0); PG8_BAR; PG8_SCHED;
;             PG8_LDB(B1, 0, 1); PG8_STAGE(PG8_SB(0, 0), b2, voffB);
;             PG8_BAR; PG8_WAIT_L(0); PG8_MMA(0, 1, At, B1); PG8_BAR;
;             PG8_LDA(At, 0, 1); PG8_STAGE(PG8_SA(0, 0), a2, voffA);
;             PG8_BAR; PG8_WAIT_L(0); PG8_MMA(1, 0, At, B0); PG8_BAR; PG8_SCHED;
.LBB0_1008:
	ds_read_b128 v[140:143], v147
	ds_read_b128 v[150:153], v147 offset:1024
	ds_read_b128 v[154:157], v147 offset:2048
	ds_read_b128 v[158:161], v147 offset:3072
	s_add_u32 s24, s22, 0x100
	s_addc_u32 s25, s23, 0
	s_cmp_eq_u32 s57, 60
	s_cselect_b32 s29, s11, s25
	s_cselect_b32 s28, s19, s24
	s_cselect_b32 s27, s9, s56
	s_cselect_b32 s26, s50, s51
	v_lshl_add_u64 v[176:177], s[22:23], 0, v[132:133]
	s_add_i32 m0, s21, 0xc000
	ds_read_b128 v[162:165], v148
	ds_read_b128 v[166:169], v148 offset:1024
	ds_read_b128 v[170:173], v148 offset:2048
	ds_read_b128 v[180:183], v148 offset:3072
	ds_read_b128 v[184:187], v148 offset:4096
	ds_read_b128 v[188:191], v148 offset:5120
	ds_read_b128 v[192:195], v148 offset:6144
	ds_read_b128 v[196:199], v148 offset:7168
	global_load_lds_dwordx4 v[176:177], off
	v_lshl_add_u64 v[176:177], s[22:23], 0, v[134:135]
	s_add_i32 m0, s21, 0xe000
	s_nop 0
	global_load_lds_dwordx4 v[176:177], off
	s_waitcnt lgkmcnt(8)
	s_barrier
	s_waitcnt lgkmcnt(0)
	s_setprio 1
	s_waitcnt lgkmcnt(0)
	v_mfma_f32_16x16x32_bf16 v[124:127], v[140:143], v[162:165], v[124:127]
	v_mfma_f32_16x16x32_bf16 v[120:123], v[154:157], v[162:165], v[120:123]
	v_mfma_f32_16x16x32_bf16 v[108:111], v[140:143], v[170:173], v[108:111]
	v_mfma_f32_16x16x32_bf16 v[104:107], v[154:157], v[170:173], v[104:107]
	v_mfma_f32_16x16x32_bf16 v[92:95], v[140:143], v[184:187], v[92:95]
	v_mfma_f32_16x16x32_bf16 v[88:91], v[154:157], v[184:187], v[88:91]
	v_mfma_f32_16x16x32_bf16 v[76:79], v[140:143], v[192:195], v[76:79]
	v_mfma_f32_16x16x32_bf16 v[72:75], v[154:157], v[192:195], v[72:75]
	v_mfma_f32_16x16x32_bf16 v[124:127], v[150:153], v[166:169], v[124:127]
	v_mfma_f32_16x16x32_bf16 v[120:123], v[158:161], v[166:169], v[120:123]
	v_mfma_f32_16x16x32_bf16 v[108:111], v[150:153], v[180:183], v[108:111]
	v_mfma_f32_16x16x32_bf16 v[104:107], v[158:161], v[180:183], v[104:107]
	v_mfma_f32_16x16x32_bf16 v[92:95], v[150:153], v[188:191], v[92:95]
	v_mfma_f32_16x16x32_bf16 v[88:91], v[158:161], v[188:191], v[88:91]
	v_mfma_f32_16x16x32_bf16 v[76:79], v[150:153], v[196:199], v[76:79]
	v_mfma_f32_16x16x32_bf16 v[72:75], v[158:161], v[196:199], v[72:75]
	s_setprio 0
	s_barrier
	s_add_i32 s22, s48, s3
	v_lshl_add_u64 v[176:177], s[26:27], 0, v[128:129]
	s_mov_b32 m0, s22
	ds_read_b128 v[200:203], v149
	ds_read_b128 v[204:207], v149 offset:1024
	ds_read_b128 v[208:211], v149 offset:2048
	ds_read_b128 v[212:215], v149 offset:3072
	global_load_lds_dwordx4 v[176:177], off
	v_lshl_add_u64 v[216:217], s[26:27], 0, v[130:131]
	s_add_i32 m0, s22, 0x2000
	s_nop 0
	global_load_lds_dwordx4 v[216:217], off
	s_barrier
	s_waitcnt lgkmcnt(0)
	s_setprio 1
	s_waitcnt lgkmcnt(0)
	v_mfma_f32_16x16x32_bf16 v[116:119], v[200:203], v[162:165], v[116:119]
	v_mfma_f32_16x16x32_bf16 v[112:115], v[208:211], v[162:165], v[112:115]
	v_mfma_f32_16x16x32_bf16 v[100:103], v[200:203], v[170:173], v[100:103]
	v_mfma_f32_16x16x32_bf16 v[96:99], v[208:211], v[170:173], v[96:99]
	v_mfma_f32_16x16x32_bf16 v[84:87], v[200:203], v[184:187], v[84:87]
	v_mfma_f32_16x16x32_bf16 v[80:83], v[208:211], v[184:187], v[80:83]
	v_mfma_f32_16x16x32_bf16 v[68:71], v[200:203], v[192:195], v[68:71]
	v_mfma_f32_16x16x32_bf16 v[64:67], v[208:211], v[192:195], v[64:67]
	v_mfma_f32_16x16x32_bf16 v[116:119], v[204:207], v[166:169], v[116:119]
	v_mfma_f32_16x16x32_bf16 v[112:115], v[212:215], v[166:169], v[112:115]
	v_mfma_f32_16x16x32_bf16 v[100:103], v[204:207], v[180:183], v[100:103]
	v_mfma_f32_16x16x32_bf16 v[96:99], v[212:215], v[180:183], v[96:99]
	v_mfma_f32_16x16x32_bf16 v[84:87], v[204:207], v[188:191], v[84:87]
	v_mfma_f32_16x16x32_bf16 v[80:83], v[212:215], v[188:191], v[80:83]
	v_mfma_f32_16x16x32_bf16 v[68:71], v[204:207], v[196:199], v[68:71]
	v_mfma_f32_16x16x32_bf16 v[64:67], v[212:215], v[196:199], v[64:67]
	s_setprio 0
	s_mov_b32 m0, s21
	v_lshl_add_u64 v[218:219], s[28:29], 0, v[128:129]
	s_barrier
	ds_read_b128 v[162:165], v148 offset:16384
	ds_read_b128 v[166:169], v148 offset:17408
	ds_read_b128 v[170:173], v148 offset:18432
	ds_read_b128 v[180:183], v148 offset:19456
	ds_read_b128 v[184:187], v148 offset:20480
	ds_read_b128 v[188:191], v148 offset:21504
	ds_read_b128 v[192:195], v148 offset:22528
	ds_read_b128 v[196:199], v148 offset:23552
	global_load_lds_dwordx4 v[218:219], off
	v_lshl_add_u64 v[220:221], s[28:29], 0, v[130:131]
	s_mov_b32 m0, s33
	s_nop 0
	global_load_lds_dwordx4 v[220:221], off
	s_barrier
	s_waitcnt lgkmcnt(0)
	s_setprio 1
	s_waitcnt lgkmcnt(0)
	v_mfma_f32_16x16x32_bf16 v[60:63], v[140:143], v[162:165], v[60:63]
	v_mfma_f32_16x16x32_bf16 v[56:59], v[154:157], v[162:165], v[56:59]
	v_mfma_f32_16x16x32_bf16 v[44:47], v[140:143], v[170:173], v[44:47]
	v_mfma_f32_16x16x32_bf16 v[40:43], v[154:157], v[170:173], v[40:43]
	v_mfma_f32_16x16x32_bf16 v[28:31], v[140:143], v[184:187], v[28:31]
	v_mfma_f32_16x16x32_bf16 v[24:27], v[154:157], v[184:187], v[24:27]
	v_mfma_f32_16x16x32_bf16 v[12:15], v[140:143], v[192:195], v[12:15]
	v_mfma_f32_16x16x32_bf16 v[8:11], v[154:157], v[192:195], v[8:11]
	v_mfma_f32_16x16x32_bf16 v[60:63], v[150:153], v[166:169], v[60:63]
	v_mfma_f32_16x16x32_bf16 v[56:59], v[158:161], v[166:169], v[56:59]
	v_mfma_f32_16x16x32_bf16 v[44:47], v[150:153], v[180:183], v[44:47]
	v_mfma_f32_16x16x32_bf16 v[40:43], v[158:161], v[180:183], v[40:43]
	v_mfma_f32_16x16x32_bf16 v[28:31], v[150:153], v[188:191], v[28:31]
	v_mfma_f32_16x16x32_bf16 v[24:27], v[158:161], v[188:191], v[24:27]
	v_mfma_f32_16x16x32_bf16 v[12:15], v[150:153], v[196:199], v[12:15]
	v_mfma_f32_16x16x32_bf16 v[8:11], v[158:161], v[196:199], v[8:11]
	s_setprio 0
	s_barrier
; #define PG8_STAGE(bufoff, gbase, voff) do { _Pragma("unroll") for (int _i = 0; _i < 2; ++_i) \
;         __builtin_amdgcn_global_load_lds((const unsigned*)((const char*)(gbase) + (voff)[_i]), (LAS unsigned*)(lds + (bufoff) + ldsw + _i * 8192), 16, 0, 0); } while (0)
; #define PG8_LDA(dst, b, h) do { _Pragma("unroll") for (int m = 0; m < 4; ++m) _Pragma("unroll") for (int k = 0; k < 2; ++k) dst[m][k] = *(const LAS bf16x8*)(lds + PG8_SA(b, h) + aoff + m * 2048 + k * 1024); } while (0)
; #define PG8_LDB(dst, b, h) do { _Pragma("unroll") for (int n = 0; n < 2; ++n) _Pragma("unroll") for (int k = 0; k < 2; ++k) dst[n][k] = *(const LAS bf16x8*)(lds + PG8_SB(b, h) + boff + n * 2048 + k * 1024); } while (0)
; #define PG8_MMA(ai, bj, At, Bt) do { __builtin_amdgcn_s_setprio(1); _Pragma("unroll") for (int m = 0; m < 4; ++m) _Pragma("unroll") for (int n = 0; n < 2; ++n) _Pragma("unroll") for (int k = 0; k < 2; ++k) \
;         acc[ai][bj][m][n] = __builtin_amdgcn_mfma_f32_16x16x32_bf16(Bt[n][k], At[m][k], acc[ai][bj][m][n], 0, 0, 0); __builtin_amdgcn_s_setprio(0); } while (0)
; #define PG8_WAIT_V(n) asm volatile("s_waitcnt vmcnt(" #n ")" ::: "memory")
; #define PG8_WAIT_L(n) asm volatile("s_waitcnt lgkmcnt(" #n ")" ::: "memory")
; #define PG8_BAR __builtin_amdgcn_s_barrier()
; #define PG8_SCHED __builtin_amdgcn_sched_barrier(0)
; template <class Epi>
; __device__ __forceinline__ void gemm_phase(LAS unsigned char* lds, const Gemm g, const StaticOrder& S, const Epi& E) {
;     ...
;             PG8_STAGE(PG8_SB(0, 1), b2 + hstep, voffB);
;             PG8_WAIT_V(6); PG8_BAR; PG8_MMA(1, 1, At, B1); PG8_BAR;
;             PG8_LDB(B0, 1, 0); PG8_SCHED; PG8_LDA(At, 1, 0); PG8_STAGE(PG8_SA(0, 1), a2 + hstep, voffA);
;             PG8_WAIT_L(8); PG8_BAR; PG8_WAIT_L(0); PG8_MMA(0, 0, At, B0); PG8_BAR; PG8_SCHED;
;             PG8_LDB(B1, 1, 1); PG8_STAGE(PG8_SB(1, 0), b3, voffB);
;             PG8_BAR; PG8_WAIT_L(0); PG8_MMA(0, 1, At, B1); PG8_BAR;
;             PG8_LDA(At, 1, 1); PG8_STAGE(PG8_SA(1, 0), a3, voffA);
;             PG8_BAR; PG8_WAIT_L(0); PG8_MMA(1, 0, At, B0); PG8_BAR; PG8_SCHED;
	s_add_u32 s22, s26, 0x100000
	s_addc_u32 s23, s27, 0
	s_add_i32 s58, s49, s3
	v_lshl_add_u64 v[140:141], s[22:23], 0, v[128:129]
	s_mov_b32 m0, s58
	s_nop 0
	global_load_lds_dwordx4 v[140:141], off
	v_lshl_add_u64 v[140:141], s[22:23], 0, v[130:131]
	s_add_i32 m0, s58, 0x2000
	s_nop 0
	global_load_lds_dwordx4 v[140:141], off
	s_waitcnt vmcnt(6)
	s_barrier
	s_setprio 1
	v_mfma_f32_16x16x32_bf16 v[52:55], v[200:203], v[162:165], v[52:55]
	v_mfma_f32_16x16x32_bf16 v[48:51], v[208:211], v[162:165], v[48:51]
	v_mfma_f32_16x16x32_bf16 v[36:39], v[200:203], v[170:173], v[36:39]
	v_mfma_f32_16x16x32_bf16 v[32:35], v[208:211], v[170:173], v[32:35]
	v_mfma_f32_16x16x32_bf16 v[20:23], v[200:203], v[184:187], v[20:23]
	v_mfma_f32_16x16x32_bf16 v[16:19], v[208:211], v[184:187], v[16:19]
	v_mfma_f32_16x16x32_bf16 v[4:7], v[200:203], v[192:195], v[4:7]
	v_mfma_f32_16x16x32_bf16 v[0:3], v[208:211], v[192:195], v[0:3]
	v_mfma_f32_16x16x32_bf16 v[52:55], v[204:207], v[166:169], v[52:55]
	v_mfma_f32_16x16x32_bf16 v[48:51], v[212:215], v[166:169], v[48:51]
	v_mfma_f32_16x16x32_bf16 v[36:39], v[204:207], v[180:183], v[36:39]
	v_mfma_f32_16x16x32_bf16 v[32:35], v[212:215], v[180:183], v[32:35]
	v_mfma_f32_16x16x32_bf16 v[20:23], v[204:207], v[188:191], v[20:23]
	v_mfma_f32_16x16x32_bf16 v[16:19], v[212:215], v[188:191], v[16:19]
	v_mfma_f32_16x16x32_bf16 v[4:7], v[204:207], v[196:199], v[4:7]
	v_mfma_f32_16x16x32_bf16 v[0:3], v[212:215], v[196:199], v[0:3]
	s_setprio 0
	s_add_i32 s58, 0, 0x18000
	v_add_u32_e32 v158, s58, v145
	s_barrier
	ds_read_b128 v[140:143], v158
	ds_read_b128 v[150:153], v158 offset:1024
	ds_read_b128 v[154:157], v158 offset:2048
	ds_read_b128 v[158:161], v158 offset:3072
	s_add_u32 s22, s28, 0x100000
	s_addc_u32 s23, s29, 0
	s_mov_b32 m0, s36
	v_lshl_add_u64 v[200:201], s[22:23], 0, v[128:129]
	ds_read_b128 v[162:165], v148 offset:32768
	ds_read_b128 v[166:169], v148 offset:33792
	ds_read_b128 v[170:173], v148 offset:34816
	ds_read_b128 v[180:183], v148 offset:35840
	ds_read_b128 v[184:187], v148 offset:36864
	ds_read_b128 v[188:191], v148 offset:37888
	ds_read_b128 v[192:195], v148 offset:38912
	ds_read_b128 v[196:199], v148 offset:39936
	global_load_lds_dwordx4 v[200:201], off
	v_lshl_add_u64 v[200:201], s[22:23], 0, v[130:131]
	s_mov_b32 m0, s37
	s_nop 0
	global_load_lds_dwordx4 v[200:201], off
	s_waitcnt lgkmcnt(8)
	s_barrier
	s_waitcnt lgkmcnt(0)
	s_setprio 1
	s_waitcnt lgkmcnt(0)
	v_mfma_f32_16x16x32_bf16 v[124:127], v[140:143], v[162:165], v[124:127]
	v_mfma_f32_16x16x32_bf16 v[120:123], v[154:157], v[162:165], v[120:123]
	v_mfma_f32_16x16x32_bf16 v[108:111], v[140:143], v[170:173], v[108:111]
	v_mfma_f32_16x16x32_bf16 v[104:107], v[154:157], v[170:173], v[104:107]
	v_mfma_f32_16x16x32_bf16 v[92:95], v[140:143], v[184:187], v[92:95]
	v_mfma_f32_16x16x32_bf16 v[88:91], v[154:157], v[184:187], v[88:91]
	v_mfma_f32_16x16x32_bf16 v[76:79], v[140:143], v[192:195], v[76:79]
	v_mfma_f32_16x16x32_bf16 v[72:75], v[154:157], v[192:195], v[72:75]
	v_mfma_f32_16x16x32_bf16 v[124:127], v[150:153], v[166:169], v[124:127]
	v_mfma_f32_16x16x32_bf16 v[120:123], v[158:161], v[166:169], v[120:123]
	v_mfma_f32_16x16x32_bf16 v[108:111], v[150:153], v[180:183], v[108:111]
	v_mfma_f32_16x16x32_bf16 v[104:107], v[158:161], v[180:183], v[104:107]
	v_mfma_f32_16x16x32_bf16 v[92:95], v[150:153], v[188:191], v[92:95]
	v_mfma_f32_16x16x32_bf16 v[88:91], v[158:161], v[188:191], v[88:91]
	v_mfma_f32_16x16x32_bf16 v[76:79], v[150:153], v[196:199], v[76:79]
	v_mfma_f32_16x16x32_bf16 v[72:75], v[158:161], v[196:199], v[72:75]
	s_setprio 0
	s_barrier
	s_add_i32 s28, 0, 0x1c000
	s_add_i32 s22, s58, s3
	v_add_u32_e32 v174, s28, v145
	v_lshl_add_u64 v[176:177], v[176:177], 0, s[0:1]
	s_mov_b32 m0, s22
	ds_read_b128 v[200:203], v174
	ds_read_b128 v[204:207], v174 offset:1024
	ds_read_b128 v[208:211], v174 offset:2048
	ds_read_b128 v[212:215], v174 offset:3072
	global_load_lds_dwordx4 v[176:177], off
	v_lshl_add_u64 v[176:177], v[216:217], 0, s[0:1]
	s_add_i32 m0, s22, 0x2000
	s_nop 0
	global_load_lds_dwordx4 v[176:177], off
	s_barrier
	s_waitcnt lgkmcnt(0)
	s_setprio 1
	s_waitcnt lgkmcnt(0)
	v_mfma_f32_16x16x32_bf16 v[116:119], v[200:203], v[162:165], v[116:119]
	v_mfma_f32_16x16x32_bf16 v[112:115], v[208:211], v[162:165], v[112:115]
	v_mfma_f32_16x16x32_bf16 v[100:103], v[200:203], v[170:173], v[100:103]
	v_mfma_f32_16x16x32_bf16 v[96:99], v[208:211], v[170:173], v[96:99]
	v_mfma_f32_16x16x32_bf16 v[84:87], v[200:203], v[184:187], v[84:87]
	v_mfma_f32_16x16x32_bf16 v[80:83], v[208:211], v[184:187], v[80:83]
	v_mfma_f32_16x16x32_bf16 v[68:71], v[200:203], v[192:195], v[68:71]
	v_mfma_f32_16x16x32_bf16 v[64:67], v[208:211], v[192:195], v[64:67]
	v_mfma_f32_16x16x32_bf16 v[116:119], v[204:207], v[166:169], v[116:119]
	v_mfma_f32_16x16x32_bf16 v[112:115], v[212:215], v[166:169], v[112:115]
	v_mfma_f32_16x16x32_bf16 v[100:103], v[204:207], v[180:183], v[100:103]
	v_mfma_f32_16x16x32_bf16 v[96:99], v[212:215], v[180:183], v[96:99]
	v_mfma_f32_16x16x32_bf16 v[84:87], v[204:207], v[188:191], v[84:87]
	v_mfma_f32_16x16x32_bf16 v[80:83], v[212:215], v[188:191], v[80:83]
	v_mfma_f32_16x16x32_bf16 v[68:71], v[204:207], v[196:199], v[68:71]
	v_mfma_f32_16x16x32_bf16 v[64:67], v[212:215], v[196:199], v[64:67]
	s_setprio 0
	s_mov_b32 m0, s39
	v_lshl_add_u64 v[176:177], v[218:219], 0, s[0:1]
	s_barrier
	ds_read_b128 v[162:165], v148 offset:49152
	ds_read_b128 v[166:169], v148 offset:50176
	ds_read_b128 v[170:173], v148 offset:51200
	ds_read_b128 v[180:183], v148 offset:52224
	ds_read_b128 v[184:187], v148 offset:53248
	ds_read_b128 v[188:191], v148 offset:54272
	ds_read_b128 v[192:195], v148 offset:55296
	ds_read_b128 v[196:199], v148 offset:56320
	global_load_lds_dwordx4 v[176:177], off
	v_lshl_add_u64 v[176:177], v[220:221], 0, s[0:1]
	s_mov_b32 m0, s42
	s_nop 0
	global_load_lds_dwordx4 v[176:177], off
	s_barrier
; DI unsigned pk2(float a, float b) { f32x2 v = {a, b}; hbf2 r = __builtin_convertvector(v, hbf2); return __builtin_bit_cast(unsigned, r); }
; DI float sum_x16_x32(float x) { return sum_x32(sum_x16(x)); }
; #define PG8_STAGE(bufoff, gbase, voff) do { _Pragma("unroll") for (int _i = 0; _i < 2; ++_i) \
;         __builtin_amdgcn_global_load_lds((const unsigned*)((const char*)(gbase) + (voff)[_i]), (LAS unsigned*)(lds + (bufoff) + ldsw + _i * 8192), 16, 0, 0); } while (0)
; #define PG8_WAIT_V(n) asm volatile("s_waitcnt vmcnt(" #n ")" ::: "memory")
; #define PG8_BAR __builtin_amdgcn_s_barrier()
; template <class Epi>
; __device__ __forceinline__ void gemm_phase(LAS unsigned char* lds, const Gemm g, const StaticOrder& S, const Epi& E) {
;     ...
;             PG8_STAGE(PG8_SB(1, 1), b3 + hstep, voffB);
;             PG8_WAIT_V(6); PG8_BAR; PG8_MMA(1, 1, At, B1); PG8_BAR;
;         }
;     DI void operator()(const f32x4 (&acc)[2][2][4][2], const Unit& u, int wr, int wc, int fr, int fq) const {
;         const int row0 = u.pm * 256 + wr * 64 + fr, col0 = u.pn * 256 + wc * 32 + 4 * fq;
; #pragma unroll
;         for (int ai = 0; ai < 2; ++ai)
; #pragma unroll
;             for (int m = 0; m < 4; ++m) {
;                 const int r = row0 + ai * 128 + m * 16;
;                 const float* rp;
;                 if (MODE == 0) rp = x + (size_t)r * 1024;
;                 else rp = h + (size_t)r * 1024;
;                 float sq = 0.f;
; #pragma unroll
;                 for (int bj = 0; bj < 2; ++bj)
; #pragma unroll
;                     for (int n = 0; n < 2; ++n) {
;                         const int c = col0 + bj * 128 + n * 16;
;                         f32x4 rv = rp ? *(const f32x4*)(rp + c) : (f32x4){0.f, 0.f, 0.f, 0.f};
;                         f32x4 v = acc[ai][bj][m][n] + rv;
;                         *(f32x4*)(h + (size_t)r * 1024 + c) = v;
;                         if (WRITE_HB) {
;                             u32x2 w; w.x = pk2(v[0], v[1]); w.y = pk2(v[2], v[3]);
;                             *(u32x2*)(hb + (size_t)r * 1024 + c) = w;
;                         }
;                         sq += v[0] * v[0] + v[1] * v[1] + v[2] * v[2] + v[3] * v[3];
;                     }
;                 sq = sum_x16_x32(sq);
;                 if (fq == 0) atomicAdd(ss + r, sq);
	s_waitcnt lgkmcnt(0)
	s_setprio 1
	s_waitcnt lgkmcnt(0)
	v_mfma_f32_16x16x32_bf16 v[60:63], v[140:143], v[162:165], v[60:63]
	v_mfma_f32_16x16x32_bf16 v[56:59], v[154:157], v[162:165], v[56:59]
	v_mfma_f32_16x16x32_bf16 v[44:47], v[140:143], v[170:173], v[44:47]
	v_mfma_f32_16x16x32_bf16 v[40:43], v[154:157], v[170:173], v[40:43]
	v_mfma_f32_16x16x32_bf16 v[28:31], v[140:143], v[184:187], v[28:31]
	v_mfma_f32_16x16x32_bf16 v[24:27], v[154:157], v[184:187], v[24:27]
	v_mfma_f32_16x16x32_bf16 v[12:15], v[140:143], v[192:195], v[12:15]
	v_mfma_f32_16x16x32_bf16 v[8:11], v[154:157], v[192:195], v[8:11]
	v_mfma_f32_16x16x32_bf16 v[60:63], v[150:153], v[166:169], v[60:63]
	v_mfma_f32_16x16x32_bf16 v[56:59], v[158:161], v[166:169], v[56:59]
	v_mfma_f32_16x16x32_bf16 v[44:47], v[150:153], v[180:183], v[44:47]
	v_mfma_f32_16x16x32_bf16 v[40:43], v[158:161], v[180:183], v[40:43]
	v_mfma_f32_16x16x32_bf16 v[28:31], v[150:153], v[188:191], v[28:31]
	v_mfma_f32_16x16x32_bf16 v[24:27], v[158:161], v[188:191], v[24:27]
	v_mfma_f32_16x16x32_bf16 v[12:15], v[150:153], v[196:199], v[12:15]
	v_mfma_f32_16x16x32_bf16 v[8:11], v[158:161], v[196:199], v[8:11]
	s_setprio 0
	s_barrier
	s_add_u32 s22, s26, 0x100080
	s_addc_u32 s23, s27, 0
	s_add_i32 s26, s28, s3
	v_lshl_add_u64 v[140:141], s[22:23], 0, v[128:129]
	s_mov_b32 m0, s26
	s_nop 0
	global_load_lds_dwordx4 v[140:141], off
	v_lshl_add_u64 v[140:141], s[22:23], 0, v[130:131]
	s_add_i32 m0, s26, 0x2000
	s_nop 0
	global_load_lds_dwordx4 v[140:141], off
	s_waitcnt vmcnt(6)
	s_barrier
	s_setprio 1
	v_mfma_f32_16x16x32_bf16 v[52:55], v[200:203], v[162:165], v[52:55]
	v_mfma_f32_16x16x32_bf16 v[48:51], v[208:211], v[162:165], v[48:51]
	v_mfma_f32_16x16x32_bf16 v[36:39], v[200:203], v[170:173], v[36:39]
	v_mfma_f32_16x16x32_bf16 v[32:35], v[208:211], v[170:173], v[32:35]
	v_mfma_f32_16x16x32_bf16 v[20:23], v[200:203], v[184:187], v[20:23]
	v_mfma_f32_16x16x32_bf16 v[16:19], v[208:211], v[184:187], v[16:19]
	v_mfma_f32_16x16x32_bf16 v[4:7], v[200:203], v[192:195], v[4:7]
	v_mfma_f32_16x16x32_bf16 v[0:3], v[208:211], v[192:195], v[0:3]
	v_mfma_f32_16x16x32_bf16 v[52:55], v[204:207], v[166:169], v[52:55]
	v_mfma_f32_16x16x32_bf16 v[48:51], v[212:215], v[166:169], v[48:51]
	v_mfma_f32_16x16x32_bf16 v[36:39], v[204:207], v[180:183], v[36:39]
	v_mfma_f32_16x16x32_bf16 v[32:35], v[212:215], v[180:183], v[32:35]
	v_mfma_f32_16x16x32_bf16 v[20:23], v[204:207], v[188:191], v[20:23]
	v_mfma_f32_16x16x32_bf16 v[16:19], v[212:215], v[188:191], v[16:19]
	v_mfma_f32_16x16x32_bf16 v[4:7], v[204:207], v[196:199], v[4:7]
	v_mfma_f32_16x16x32_bf16 v[0:3], v[212:215], v[196:199], v[0:3]
	s_setprio 0
	s_add_i32 s57, s57, 2
	s_add_u32 s51, s51, 0x100
	s_addc_u32 s56, s56, 0
	s_cmp_gt_u32 s57, 61
	s_mov_b64 s[22:23], s[24:25]
	s_barrier
	s_cbranch_scc0 .LBB0_1008
	v_lshl_add_u32 v142, s18, 8, v144
	v_ashrrev_i32_e32 v143, 31, v142
	v_lshl_or_b32 v140, s20, 8, v146
	v_lshlrev_b64 v[150:151], 12, v[142:143]
	v_lshl_add_u64 v[150:151], s[66:67], 0, v[150:151]
	v_ashrrev_i32_e32 v141, 31, v140
	v_lshl_add_u64 v[154:155], v[140:141], 2, v[150:151]
	global_load_dwordx4 v[180:183], v[154:155], off
	global_load_dwordx4 v[184:187], v[154:155], off offset:64
	global_load_dwordx4 v[188:191], v[154:155], off offset:512
	global_load_dwordx4 v[192:195], v[154:155], off offset:576
	v_lshlrev_b64 v[156:157], 11, v[142:143]
	v_lshl_add_u64 v[156:157], s[68:69], 0, v[156:157]
	v_lshl_add_u64 v[156:157], v[140:141], 1, v[156:157]
	s_waitcnt vmcnt(3)
	v_pk_add_f32 v[126:127], v[126:127], v[182:183]
	v_pk_add_f32 v[124:125], v[124:125], v[180:181]
	v_cvt_pk_bf16_f32 v151, v126, v127
	v_cvt_pk_bf16_f32 v150, v124, v125
	global_store_dwordx4 v[154:155], v[124:127], off
	global_store_dwordx2 v[156:157], v[150:151], off
	s_nop 0
	v_mul_f32_e32 v125, v125, v125
	v_fmac_f32_e32 v125, v124, v124
	v_fmac_f32_e32 v125, v126, v126
	v_fmac_f32_e32 v125, v127, v127
	s_waitcnt vmcnt(4)
	v_pk_add_f32 v[122:123], v[122:123], v[186:187]
	v_pk_add_f32 v[120:121], v[120:121], v[184:185]
	v_cvt_pk_bf16_f32 v151, v122, v123
	v_cvt_pk_bf16_f32 v150, v120, v121
	global_store_dwordx4 v[154:155], v[120:123], off offset:64
	global_store_dwordx2 v[156:157], v[150:151], off offset:32
	s_nop 0
	v_mul_f32_e32 v121, v121, v121
	v_fmac_f32_e32 v121, v120, v120
	v_fmac_f32_e32 v121, v122, v122
	v_fmac_f32_e32 v121, v123, v123
	v_add_f32_e32 v120, v125, v121
	s_waitcnt vmcnt(5)
	v_pk_add_f32 v[118:119], v[118:119], v[190:191]
	v_pk_add_f32 v[116:117], v[116:117], v[188:189]
	v_cvt_pk_bf16_f32 v151, v118, v119
	v_cvt_pk_bf16_f32 v150, v116, v117
	global_store_dwordx4 v[154:155], v[116:119], off offset:512
	global_store_dwordx2 v[156:157], v[150:151], off offset:256
	s_nop 0
	v_mul_f32_e32 v117, v117, v117
	v_fmac_f32_e32 v117, v116, v116
	v_fmac_f32_e32 v117, v118, v118
	v_fmac_f32_e32 v117, v119, v119
	v_add_f32_e32 v118, v120, v117
	s_waitcnt vmcnt(6)
	v_pk_add_f32 v[114:115], v[114:115], v[194:195]
	v_pk_add_f32 v[112:113], v[112:113], v[192:193]
	global_store_dwordx4 v[154:155], v[112:115], off offset:576
	v_cvt_pk_bf16_f32 v116, v112, v113
	v_cvt_pk_bf16_f32 v117, v114, v115
	v_mul_f32_e32 v113, v113, v113
	v_fmac_f32_e32 v113, v112, v112
	v_fmac_f32_e32 v113, v114, v114
	v_fmac_f32_e32 v113, v115, v115
	v_add_f32_e32 v112, v118, v113
	v_mov_b32_e32 v113, v112
	s_nop 1
	v_permlane16_swap_b32_e32 v112, v113
	v_add_f32_e32 v112, v112, v113
	v_mov_b32_e32 v113, v112
	s_nop 1
	v_permlane32_swap_b32_e32 v112, v113
	global_store_dwordx2 v[156:157], v[116:117], off offset:288
	s_and_saveexec_b64 s[18:19], s[4:5]
	s_cbranch_execz .LBB0_1011
	v_lshl_add_u64 v[114:115], v[142:143], 2, s[44:45]
	v_add_f32_e32 v112, v112, v113
	global_atomic_add_f32 v[114:115], v112, off
; DI unsigned pk2(float a, float b) { f32x2 v = {a, b}; hbf2 r = __builtin_convertvector(v, hbf2); return __builtin_bit_cast(unsigned, r); }
; DI float sum_x16_x32(float x) { return sum_x32(sum_x16(x)); }
;     DI void operator()(const f32x4 (&acc)[2][2][4][2], const Unit& u, int wr, int wc, int fr, int fq) const {
;     ...
;             for (int m = 0; m < 4; ++m) {
;                 const int r = row0 + ai * 128 + m * 16;
;                 const float* rp;
;                 if (MODE == 0) rp = x + (size_t)r * 1024;
;                 else rp = h + (size_t)r * 1024;
;                 float sq = 0.f;
; #pragma unroll
;                 for (int bj = 0; bj < 2; ++bj)
; #pragma unroll
;                     for (int n = 0; n < 2; ++n) {
;                         const int c = col0 + bj * 128 + n * 16;
;                         f32x4 rv = rp ? *(const f32x4*)(rp + c) : (f32x4){0.f, 0.f, 0.f, 0.f};
;                         f32x4 v = acc[ai][bj][m][n] + rv;
;                         *(f32x4*)(h + (size_t)r * 1024 + c) = v;
;                         if (WRITE_HB) {
;                             u32x2 w; w.x = pk2(v[0], v[1]); w.y = pk2(v[2], v[3]);
;                             *(u32x2*)(hb + (size_t)r * 1024 + c) = w;
;                         }
;                         sq += v[0] * v[0] + v[1] * v[1] + v[2] * v[2] + v[3] * v[3];
;                     }
;                 sq = sum_x16_x32(sq);
;                 if (fq == 0) atomicAdd(ss + r, sq);
.LBB0_1011:
	s_or_b64 exec, exec, s[18:19]
	v_or_b32_e32 v112, 16, v142
	v_ashrrev_i32_e32 v113, 31, v112
	v_lshlrev_b64 v[114:115], 12, v[112:113]
	v_lshl_add_u64 v[114:115], s[66:67], 0, v[114:115]
	v_lshl_add_u64 v[118:119], v[140:141], 2, v[114:115]
	global_load_dwordx4 v[180:183], v[118:119], off
	global_load_dwordx4 v[184:187], v[118:119], off offset:64
	global_load_dwordx4 v[188:191], v[118:119], off offset:512
	global_load_dwordx4 v[192:195], v[118:119], off offset:576
	v_lshlrev_b64 v[120:121], 11, v[112:113]
	v_lshl_add_u64 v[120:121], s[68:69], 0, v[120:121]
	v_lshl_add_u64 v[120:121], v[140:141], 1, v[120:121]
	s_waitcnt vmcnt(3)
	v_pk_add_f32 v[110:111], v[110:111], v[182:183]
	v_pk_add_f32 v[108:109], v[108:109], v[180:181]
	v_cvt_pk_bf16_f32 v115, v110, v111
	v_cvt_pk_bf16_f32 v114, v108, v109
	global_store_dwordx4 v[118:119], v[108:111], off
	global_store_dwordx2 v[120:121], v[114:115], off
	s_nop 0
	v_mul_f32_e32 v109, v109, v109
	v_fmac_f32_e32 v109, v108, v108
	v_fmac_f32_e32 v109, v110, v110
	v_fmac_f32_e32 v109, v111, v111
	s_waitcnt vmcnt(4)
	v_pk_add_f32 v[106:107], v[106:107], v[186:187]
	v_pk_add_f32 v[104:105], v[104:105], v[184:185]
	v_cvt_pk_bf16_f32 v115, v106, v107
	v_cvt_pk_bf16_f32 v114, v104, v105
	global_store_dwordx4 v[118:119], v[104:107], off offset:64
	global_store_dwordx2 v[120:121], v[114:115], off offset:32
	s_nop 0
	v_mul_f32_e32 v105, v105, v105
	v_fmac_f32_e32 v105, v104, v104
	v_fmac_f32_e32 v105, v106, v106
	v_fmac_f32_e32 v105, v107, v107
	v_add_f32_e32 v104, v109, v105
	s_waitcnt vmcnt(5)
	v_pk_add_f32 v[102:103], v[102:103], v[190:191]
	v_pk_add_f32 v[100:101], v[100:101], v[188:189]
	v_cvt_pk_bf16_f32 v115, v102, v103
	v_cvt_pk_bf16_f32 v114, v100, v101
	global_store_dwordx4 v[118:119], v[100:103], off offset:512
	global_store_dwordx2 v[120:121], v[114:115], off offset:256
	s_nop 0
	v_mul_f32_e32 v101, v101, v101
	v_fmac_f32_e32 v101, v100, v100
	v_fmac_f32_e32 v101, v102, v102
	v_fmac_f32_e32 v101, v103, v103
	v_add_f32_e32 v102, v104, v101
	s_waitcnt vmcnt(6)
	v_pk_add_f32 v[98:99], v[98:99], v[194:195]
	v_pk_add_f32 v[96:97], v[96:97], v[192:193]
	global_store_dwordx4 v[118:119], v[96:99], off offset:576
	v_cvt_pk_bf16_f32 v100, v96, v97
	v_cvt_pk_bf16_f32 v101, v98, v99
	v_mul_f32_e32 v97, v97, v97
	v_fmac_f32_e32 v97, v96, v96
	v_fmac_f32_e32 v97, v98, v98
	v_fmac_f32_e32 v97, v99, v99
	v_add_f32_e32 v96, v102, v97
	v_mov_b32_e32 v97, v96
	s_nop 1
	v_permlane16_swap_b32_e32 v96, v97
	v_add_f32_e32 v96, v96, v97
	v_mov_b32_e32 v97, v96
	s_nop 1
	v_permlane32_swap_b32_e32 v96, v97
	global_store_dwordx2 v[120:121], v[100:101], off offset:288
	s_and_saveexec_b64 s[18:19], s[4:5]
	s_cbranch_execz .LBB0_1013
	v_lshl_add_u64 v[98:99], v[112:113], 2, s[44:45]
	v_add_f32_e32 v96, v96, v97
	global_atomic_add_f32 v[98:99], v96, off
.LBB0_1013:
	s_or_b64 exec, exec, s[18:19]
	v_or_b32_e32 v96, 32, v142
	v_ashrrev_i32_e32 v97, 31, v96
	v_lshlrev_b64 v[98:99], 12, v[96:97]
	v_lshl_add_u64 v[98:99], s[66:67], 0, v[98:99]
	v_lshl_add_u64 v[102:103], v[140:141], 2, v[98:99]
	global_load_dwordx4 v[180:183], v[102:103], off
	global_load_dwordx4 v[184:187], v[102:103], off offset:64
	global_load_dwordx4 v[188:191], v[102:103], off offset:512
	global_load_dwordx4 v[192:195], v[102:103], off offset:576
	v_lshlrev_b64 v[104:105], 11, v[96:97]
	v_lshl_add_u64 v[104:105], s[68:69], 0, v[104:105]
	v_lshl_add_u64 v[104:105], v[140:141], 1, v[104:105]
	s_waitcnt vmcnt(3)
	v_pk_add_f32 v[94:95], v[94:95], v[182:183]
	v_pk_add_f32 v[92:93], v[92:93], v[180:181]
	v_cvt_pk_bf16_f32 v99, v94, v95
	v_cvt_pk_bf16_f32 v98, v92, v93
	global_store_dwordx4 v[102:103], v[92:95], off
	global_store_dwordx2 v[104:105], v[98:99], off
	s_nop 0
	v_mul_f32_e32 v93, v93, v93
	v_fmac_f32_e32 v93, v92, v92
	v_fmac_f32_e32 v93, v94, v94
	v_fmac_f32_e32 v93, v95, v95
	s_waitcnt vmcnt(4)
	v_pk_add_f32 v[90:91], v[90:91], v[186:187]
	v_pk_add_f32 v[88:89], v[88:89], v[184:185]
	v_cvt_pk_bf16_f32 v99, v90, v91
	v_cvt_pk_bf16_f32 v98, v88, v89
	global_store_dwordx4 v[102:103], v[88:91], off offset:64
	global_store_dwordx2 v[104:105], v[98:99], off offset:32
	s_nop 0
	v_mul_f32_e32 v89, v89, v89
	v_fmac_f32_e32 v89, v88, v88
	v_fmac_f32_e32 v89, v90, v90
	v_fmac_f32_e32 v89, v91, v91
	v_add_f32_e32 v88, v93, v89
	s_waitcnt vmcnt(5)
	v_pk_add_f32 v[86:87], v[86:87], v[190:191]
	v_pk_add_f32 v[84:85], v[84:85], v[188:189]
	v_cvt_pk_bf16_f32 v99, v86, v87
	v_cvt_pk_bf16_f32 v98, v84, v85
	global_store_dwordx4 v[102:103], v[84:87], off offset:512
	global_store_dwordx2 v[104:105], v[98:99], off offset:256
	s_nop 0
	v_mul_f32_e32 v85, v85, v85
	v_fmac_f32_e32 v85, v84, v84
	v_fmac_f32_e32 v85, v86, v86
	v_fmac_f32_e32 v85, v87, v87
	v_add_f32_e32 v86, v88, v85
	s_waitcnt vmcnt(6)
	v_pk_add_f32 v[82:83], v[82:83], v[194:195]
	v_pk_add_f32 v[80:81], v[80:81], v[192:193]
	global_store_dwordx4 v[102:103], v[80:83], off offset:576
	v_cvt_pk_bf16_f32 v84, v80, v81
	v_cvt_pk_bf16_f32 v85, v82, v83
	v_mul_f32_e32 v81, v81, v81
	v_fmac_f32_e32 v81, v80, v80
	v_fmac_f32_e32 v81, v82, v82
	v_fmac_f32_e32 v81, v83, v83
	v_add_f32_e32 v80, v86, v81
	v_mov_b32_e32 v81, v80
	s_nop 1
	v_permlane16_swap_b32_e32 v80, v81
	v_add_f32_e32 v80, v80, v81
	v_mov_b32_e32 v81, v80
	s_nop 1
	v_permlane32_swap_b32_e32 v80, v81
	global_store_dwordx2 v[104:105], v[84:85], off offset:288
	s_and_saveexec_b64 s[18:19], s[4:5]
	s_cbranch_execz .LBB0_1015
	v_lshl_add_u64 v[82:83], v[96:97], 2, s[44:45]
	v_add_f32_e32 v80, v80, v81
	global_atomic_add_f32 v[82:83], v80, off
; DI unsigned pk2(float a, float b) { f32x2 v = {a, b}; hbf2 r = __builtin_convertvector(v, hbf2); return __builtin_bit_cast(unsigned, r); }
; DI float sum_x16_x32(float x) { return sum_x32(sum_x16(x)); }
;     DI void operator()(const f32x4 (&acc)[2][2][4][2], const Unit& u, int wr, int wc, int fr, int fq) const {
;     ...
;             for (int m = 0; m < 4; ++m) {
;                 const int r = row0 + ai * 128 + m * 16;
;                 const float* rp;
;                 if (MODE == 0) rp = x + (size_t)r * 1024;
;                 else rp = h + (size_t)r * 1024;
;                 float sq = 0.f;
; #pragma unroll
;                 for (int bj = 0; bj < 2; ++bj)
; #pragma unroll
;                     for (int n = 0; n < 2; ++n) {
;                         const int c = col0 + bj * 128 + n * 16;
;                         f32x4 rv = rp ? *(const f32x4*)(rp + c) : (f32x4){0.f, 0.f, 0.f, 0.f};
;                         f32x4 v = acc[ai][bj][m][n] + rv;
;                         *(f32x4*)(h + (size_t)r * 1024 + c) = v;
;                         if (WRITE_HB) {
;                             u32x2 w; w.x = pk2(v[0], v[1]); w.y = pk2(v[2], v[3]);
;                             *(u32x2*)(hb + (size_t)r * 1024 + c) = w;
;                         }
;                         sq += v[0] * v[0] + v[1] * v[1] + v[2] * v[2] + v[3] * v[3];
;                     }
;                 sq = sum_x16_x32(sq);
;                 if (fq == 0) atomicAdd(ss + r, sq);
.LBB0_1015:
	s_or_b64 exec, exec, s[18:19]
	v_or_b32_e32 v80, 48, v142
	v_ashrrev_i32_e32 v81, 31, v80
	v_lshlrev_b64 v[82:83], 12, v[80:81]
	v_lshl_add_u64 v[82:83], s[66:67], 0, v[82:83]
	v_lshl_add_u64 v[86:87], v[140:141], 2, v[82:83]
	global_load_dwordx4 v[180:183], v[86:87], off
	global_load_dwordx4 v[184:187], v[86:87], off offset:64
	global_load_dwordx4 v[188:191], v[86:87], off offset:512
	global_load_dwordx4 v[192:195], v[86:87], off offset:576
	v_lshlrev_b64 v[88:89], 11, v[80:81]
	v_lshl_add_u64 v[88:89], s[68:69], 0, v[88:89]
	v_lshl_add_u64 v[88:89], v[140:141], 1, v[88:89]
	s_waitcnt vmcnt(3)
	v_pk_add_f32 v[78:79], v[78:79], v[182:183]
	v_pk_add_f32 v[76:77], v[76:77], v[180:181]
	v_cvt_pk_bf16_f32 v83, v78, v79
	v_cvt_pk_bf16_f32 v82, v76, v77
	global_store_dwordx4 v[86:87], v[76:79], off
	global_store_dwordx2 v[88:89], v[82:83], off
	s_nop 0
	v_mul_f32_e32 v77, v77, v77
	v_fmac_f32_e32 v77, v76, v76
	v_fmac_f32_e32 v77, v78, v78
	v_fmac_f32_e32 v77, v79, v79
	s_waitcnt vmcnt(4)
	v_pk_add_f32 v[74:75], v[74:75], v[186:187]
	v_pk_add_f32 v[72:73], v[72:73], v[184:185]
	v_cvt_pk_bf16_f32 v83, v74, v75
	v_cvt_pk_bf16_f32 v82, v72, v73
	global_store_dwordx4 v[86:87], v[72:75], off offset:64
	global_store_dwordx2 v[88:89], v[82:83], off offset:32
	s_nop 0
	v_mul_f32_e32 v73, v73, v73
	v_fmac_f32_e32 v73, v72, v72
	v_fmac_f32_e32 v73, v74, v74
	v_fmac_f32_e32 v73, v75, v75
	v_add_f32_e32 v72, v77, v73
	s_waitcnt vmcnt(5)
	v_pk_add_f32 v[70:71], v[70:71], v[190:191]
	v_pk_add_f32 v[68:69], v[68:69], v[188:189]
	v_cvt_pk_bf16_f32 v83, v70, v71
	v_cvt_pk_bf16_f32 v82, v68, v69
	global_store_dwordx4 v[86:87], v[68:71], off offset:512
	global_store_dwordx2 v[88:89], v[82:83], off offset:256
	s_nop 0
	v_mul_f32_e32 v69, v69, v69
	v_fmac_f32_e32 v69, v68, v68
	v_fmac_f32_e32 v69, v70, v70
	v_fmac_f32_e32 v69, v71, v71
	v_add_f32_e32 v70, v72, v69
	s_waitcnt vmcnt(6)
	v_pk_add_f32 v[66:67], v[66:67], v[194:195]
	v_pk_add_f32 v[64:65], v[64:65], v[192:193]
	global_store_dwordx4 v[86:87], v[64:67], off offset:576
	v_cvt_pk_bf16_f32 v68, v64, v65
	v_cvt_pk_bf16_f32 v69, v66, v67
	v_mul_f32_e32 v65, v65, v65
	v_fmac_f32_e32 v65, v64, v64
	v_fmac_f32_e32 v65, v66, v66
	v_fmac_f32_e32 v65, v67, v67
	v_add_f32_e32 v64, v70, v65
	v_mov_b32_e32 v65, v64
	s_nop 1
	v_permlane16_swap_b32_e32 v64, v65
	v_add_f32_e32 v64, v64, v65
	v_mov_b32_e32 v65, v64
	s_nop 1
	v_permlane32_swap_b32_e32 v64, v65
	global_store_dwordx2 v[88:89], v[68:69], off offset:288
	s_and_saveexec_b64 s[18:19], s[4:5]
	s_cbranch_execz .LBB0_1017
	v_lshl_add_u64 v[66:67], v[80:81], 2, s[44:45]
	v_add_f32_e32 v64, v64, v65
	global_atomic_add_f32 v[66:67], v64, off
.LBB0_1017:
	s_or_b64 exec, exec, s[18:19]
	v_add_u32_e32 v64, 0x80, v142
	v_ashrrev_i32_e32 v65, 31, v64
	v_lshlrev_b64 v[66:67], 12, v[64:65]
	v_lshl_add_u64 v[66:67], s[66:67], 0, v[66:67]
	v_lshl_add_u64 v[70:71], v[140:141], 2, v[66:67]
	global_load_dwordx4 v[180:183], v[70:71], off
	global_load_dwordx4 v[184:187], v[70:71], off offset:64
	global_load_dwordx4 v[188:191], v[70:71], off offset:512
	global_load_dwordx4 v[192:195], v[70:71], off offset:576
	v_lshlrev_b64 v[72:73], 11, v[64:65]
	v_lshl_add_u64 v[72:73], s[68:69], 0, v[72:73]
	v_lshl_add_u64 v[72:73], v[140:141], 1, v[72:73]
	s_waitcnt vmcnt(3)
	v_pk_add_f32 v[62:63], v[62:63], v[182:183]
	v_pk_add_f32 v[60:61], v[60:61], v[180:181]
	v_cvt_pk_bf16_f32 v67, v62, v63
	v_cvt_pk_bf16_f32 v66, v60, v61
	global_store_dwordx4 v[70:71], v[60:63], off
	global_store_dwordx2 v[72:73], v[66:67], off
	s_nop 0
	v_mul_f32_e32 v61, v61, v61
	v_fmac_f32_e32 v61, v60, v60
	v_fmac_f32_e32 v61, v62, v62
	v_fmac_f32_e32 v61, v63, v63
	s_waitcnt vmcnt(4)
	v_pk_add_f32 v[58:59], v[58:59], v[186:187]
	v_pk_add_f32 v[56:57], v[56:57], v[184:185]
	v_cvt_pk_bf16_f32 v67, v58, v59
	v_cvt_pk_bf16_f32 v66, v56, v57
	global_store_dwordx4 v[70:71], v[56:59], off offset:64
	global_store_dwordx2 v[72:73], v[66:67], off offset:32
	s_nop 0
	v_mul_f32_e32 v57, v57, v57
	v_fmac_f32_e32 v57, v56, v56
	v_fmac_f32_e32 v57, v58, v58
	v_fmac_f32_e32 v57, v59, v59
	v_add_f32_e32 v56, v61, v57
	s_waitcnt vmcnt(5)
	v_pk_add_f32 v[54:55], v[54:55], v[190:191]
	v_pk_add_f32 v[52:53], v[52:53], v[188:189]
	v_cvt_pk_bf16_f32 v67, v54, v55
	v_cvt_pk_bf16_f32 v66, v52, v53
	global_store_dwordx4 v[70:71], v[52:55], off offset:512
	global_store_dwordx2 v[72:73], v[66:67], off offset:256
	s_nop 0
	v_mul_f32_e32 v53, v53, v53
	v_fmac_f32_e32 v53, v52, v52
	v_fmac_f32_e32 v53, v54, v54
	v_fmac_f32_e32 v53, v55, v55
	v_add_f32_e32 v54, v56, v53
	s_waitcnt vmcnt(6)
	v_pk_add_f32 v[50:51], v[50:51], v[194:195]
	v_pk_add_f32 v[48:49], v[48:49], v[192:193]
	global_store_dwordx4 v[70:71], v[48:51], off offset:576
	v_cvt_pk_bf16_f32 v52, v48, v49
	v_cvt_pk_bf16_f32 v53, v50, v51
	v_mul_f32_e32 v49, v49, v49
	v_fmac_f32_e32 v49, v48, v48
	v_fmac_f32_e32 v49, v50, v50
	v_fmac_f32_e32 v49, v51, v51
	v_add_f32_e32 v48, v54, v49
	v_mov_b32_e32 v49, v48
	s_nop 1
	v_permlane16_swap_b32_e32 v48, v49
	v_add_f32_e32 v48, v48, v49
	v_mov_b32_e32 v49, v48
	s_nop 1
	v_permlane32_swap_b32_e32 v48, v49
	global_store_dwordx2 v[72:73], v[52:53], off offset:288
	s_and_saveexec_b64 s[18:19], s[4:5]
	s_cbranch_execz .LBB0_1019
	v_lshl_add_u64 v[50:51], v[64:65], 2, s[44:45]
	v_add_f32_e32 v48, v48, v49
	global_atomic_add_f32 v[50:51], v48, off
; DI unsigned pk2(float a, float b) { f32x2 v = {a, b}; hbf2 r = __builtin_convertvector(v, hbf2); return __builtin_bit_cast(unsigned, r); }
; DI float sum_x16_x32(float x) { return sum_x32(sum_x16(x)); }
;     DI void operator()(const f32x4 (&acc)[2][2][4][2], const Unit& u, int wr, int wc, int fr, int fq) const {
;     ...
;             for (int m = 0; m < 4; ++m) {
;                 const int r = row0 + ai * 128 + m * 16;
;                 const float* rp;
;                 if (MODE == 0) rp = x + (size_t)r * 1024;
;                 else rp = h + (size_t)r * 1024;
;                 float sq = 0.f;
; #pragma unroll
;                 for (int bj = 0; bj < 2; ++bj)
; #pragma unroll
;                     for (int n = 0; n < 2; ++n) {
;                         const int c = col0 + bj * 128 + n * 16;
;                         f32x4 rv = rp ? *(const f32x4*)(rp + c) : (f32x4){0.f, 0.f, 0.f, 0.f};
;                         f32x4 v = acc[ai][bj][m][n] + rv;
;                         *(f32x4*)(h + (size_t)r * 1024 + c) = v;
;                         if (WRITE_HB) {
;                             u32x2 w; w.x = pk2(v[0], v[1]); w.y = pk2(v[2], v[3]);
;                             *(u32x2*)(hb + (size_t)r * 1024 + c) = w;
;                         }
;                         sq += v[0] * v[0] + v[1] * v[1] + v[2] * v[2] + v[3] * v[3];
;                     }
;                 sq = sum_x16_x32(sq);
;                 if (fq == 0) atomicAdd(ss + r, sq);
.LBB0_1019:
	s_or_b64 exec, exec, s[18:19]
	v_add_u32_e32 v48, 0x90, v142
	v_ashrrev_i32_e32 v49, 31, v48
	v_lshlrev_b64 v[50:51], 12, v[48:49]
	v_lshl_add_u64 v[50:51], s[66:67], 0, v[50:51]
	v_lshl_add_u64 v[54:55], v[140:141], 2, v[50:51]
	global_load_dwordx4 v[180:183], v[54:55], off
	global_load_dwordx4 v[184:187], v[54:55], off offset:64
	global_load_dwordx4 v[188:191], v[54:55], off offset:512
	global_load_dwordx4 v[192:195], v[54:55], off offset:576
	v_lshlrev_b64 v[56:57], 11, v[48:49]
	v_lshl_add_u64 v[56:57], s[68:69], 0, v[56:57]
	v_lshl_add_u64 v[56:57], v[140:141], 1, v[56:57]
	s_waitcnt vmcnt(3)
	v_pk_add_f32 v[46:47], v[46:47], v[182:183]
	v_pk_add_f32 v[44:45], v[44:45], v[180:181]
	v_cvt_pk_bf16_f32 v51, v46, v47
	v_cvt_pk_bf16_f32 v50, v44, v45
	global_store_dwordx4 v[54:55], v[44:47], off
	global_store_dwordx2 v[56:57], v[50:51], off
	s_nop 0
	v_mul_f32_e32 v45, v45, v45
	v_fmac_f32_e32 v45, v44, v44
	v_fmac_f32_e32 v45, v46, v46
	v_fmac_f32_e32 v45, v47, v47
	s_waitcnt vmcnt(4)
	v_pk_add_f32 v[42:43], v[42:43], v[186:187]
	v_pk_add_f32 v[40:41], v[40:41], v[184:185]
	v_cvt_pk_bf16_f32 v51, v42, v43
	v_cvt_pk_bf16_f32 v50, v40, v41
	global_store_dwordx4 v[54:55], v[40:43], off offset:64
	global_store_dwordx2 v[56:57], v[50:51], off offset:32
	s_nop 0
	v_mul_f32_e32 v41, v41, v41
	v_fmac_f32_e32 v41, v40, v40
	v_fmac_f32_e32 v41, v42, v42
	v_fmac_f32_e32 v41, v43, v43
	v_add_f32_e32 v40, v45, v41
	s_waitcnt vmcnt(5)
	v_pk_add_f32 v[38:39], v[38:39], v[190:191]
	v_pk_add_f32 v[36:37], v[36:37], v[188:189]
	v_cvt_pk_bf16_f32 v51, v38, v39
	v_cvt_pk_bf16_f32 v50, v36, v37
	global_store_dwordx4 v[54:55], v[36:39], off offset:512
	global_store_dwordx2 v[56:57], v[50:51], off offset:256
	s_nop 0
	v_mul_f32_e32 v37, v37, v37
	v_fmac_f32_e32 v37, v36, v36
	v_fmac_f32_e32 v37, v38, v38
	v_fmac_f32_e32 v37, v39, v39
	v_add_f32_e32 v38, v40, v37
	s_waitcnt vmcnt(6)
	v_pk_add_f32 v[34:35], v[34:35], v[194:195]
	v_pk_add_f32 v[32:33], v[32:33], v[192:193]
	global_store_dwordx4 v[54:55], v[32:35], off offset:576
	v_cvt_pk_bf16_f32 v36, v32, v33
	v_cvt_pk_bf16_f32 v37, v34, v35
	v_mul_f32_e32 v33, v33, v33
	v_fmac_f32_e32 v33, v32, v32
	v_fmac_f32_e32 v33, v34, v34
	v_fmac_f32_e32 v33, v35, v35
	v_add_f32_e32 v32, v38, v33
	v_mov_b32_e32 v33, v32
	s_nop 1
	v_permlane16_swap_b32_e32 v32, v33
	v_add_f32_e32 v32, v32, v33
	v_mov_b32_e32 v33, v32
	s_nop 1
	v_permlane32_swap_b32_e32 v32, v33
	global_store_dwordx2 v[56:57], v[36:37], off offset:288
	s_and_saveexec_b64 s[18:19], s[4:5]
	s_cbranch_execz .LBB0_1021
	v_lshl_add_u64 v[34:35], v[48:49], 2, s[44:45]
	v_add_f32_e32 v32, v32, v33
	global_atomic_add_f32 v[34:35], v32, off
; DI unsigned pk2(float a, float b) { f32x2 v = {a, b}; hbf2 r = __builtin_convertvector(v, hbf2); return __builtin_bit_cast(unsigned, r); }
; DI float sum_x16_x32(float x) { return sum_x32(sum_x16(x)); }
;     DI void operator()(const f32x4 (&acc)[2][2][4][2], const Unit& u, int wr, int wc, int fr, int fq) const {
;     ...
;             for (int m = 0; m < 4; ++m) {
;                 const int r = row0 + ai * 128 + m * 16;
;                 const float* rp;
;                 if (MODE == 0) rp = x + (size_t)r * 1024;
;                 else rp = h + (size_t)r * 1024;
;                 float sq = 0.f;
; #pragma unroll
;                 for (int bj = 0; bj < 2; ++bj)
; #pragma unroll
;                     for (int n = 0; n < 2; ++n) {
;                         const int c = col0 + bj * 128 + n * 16;
;                         f32x4 rv = rp ? *(const f32x4*)(rp + c) : (f32x4){0.f, 0.f, 0.f, 0.f};
;                         f32x4 v = acc[ai][bj][m][n] + rv;
;                         *(f32x4*)(h + (size_t)r * 1024 + c) = v;
;                         if (WRITE_HB) {
;                             u32x2 w; w.x = pk2(v[0], v[1]); w.y = pk2(v[2], v[3]);
;                             *(u32x2*)(hb + (size_t)r * 1024 + c) = w;
;                         }
;                         sq += v[0] * v[0] + v[1] * v[1] + v[2] * v[2] + v[3] * v[3];
;                     }
;                 sq = sum_x16_x32(sq);
;                 if (fq == 0) atomicAdd(ss + r, sq);
.LBB0_1021:
	s_or_b64 exec, exec, s[18:19]
	v_add_u32_e32 v32, 0xa0, v142
	v_ashrrev_i32_e32 v33, 31, v32
	v_lshlrev_b64 v[34:35], 12, v[32:33]
	v_lshl_add_u64 v[34:35], s[66:67], 0, v[34:35]
	v_lshl_add_u64 v[38:39], v[140:141], 2, v[34:35]
	global_load_dwordx4 v[180:183], v[38:39], off
	global_load_dwordx4 v[184:187], v[38:39], off offset:64
	global_load_dwordx4 v[188:191], v[38:39], off offset:512
	global_load_dwordx4 v[192:195], v[38:39], off offset:576
	v_lshlrev_b64 v[40:41], 11, v[32:33]
	v_lshl_add_u64 v[40:41], s[68:69], 0, v[40:41]
	v_lshl_add_u64 v[40:41], v[140:141], 1, v[40:41]
	s_waitcnt vmcnt(3)
	v_pk_add_f32 v[30:31], v[30:31], v[182:183]
	v_pk_add_f32 v[28:29], v[28:29], v[180:181]
	v_cvt_pk_bf16_f32 v35, v30, v31
	v_cvt_pk_bf16_f32 v34, v28, v29
	global_store_dwordx4 v[38:39], v[28:31], off
	global_store_dwordx2 v[40:41], v[34:35], off
	s_nop 0
	v_mul_f32_e32 v29, v29, v29
	v_fmac_f32_e32 v29, v28, v28
	v_fmac_f32_e32 v29, v30, v30
	v_fmac_f32_e32 v29, v31, v31
	s_waitcnt vmcnt(4)
	v_pk_add_f32 v[26:27], v[26:27], v[186:187]
	v_pk_add_f32 v[24:25], v[24:25], v[184:185]
	v_cvt_pk_bf16_f32 v35, v26, v27
	v_cvt_pk_bf16_f32 v34, v24, v25
	global_store_dwordx4 v[38:39], v[24:27], off offset:64
	global_store_dwordx2 v[40:41], v[34:35], off offset:32
	s_nop 0
	v_mul_f32_e32 v25, v25, v25
	v_fmac_f32_e32 v25, v24, v24
	v_fmac_f32_e32 v25, v26, v26
	v_fmac_f32_e32 v25, v27, v27
	v_add_f32_e32 v24, v29, v25
	s_waitcnt vmcnt(5)
	v_pk_add_f32 v[22:23], v[22:23], v[190:191]
	v_pk_add_f32 v[20:21], v[20:21], v[188:189]
	v_cvt_pk_bf16_f32 v35, v22, v23
	v_cvt_pk_bf16_f32 v34, v20, v21
	global_store_dwordx4 v[38:39], v[20:23], off offset:512
	global_store_dwordx2 v[40:41], v[34:35], off offset:256
	s_nop 0
	v_mul_f32_e32 v21, v21, v21
	v_fmac_f32_e32 v21, v20, v20
	v_fmac_f32_e32 v21, v22, v22
	v_fmac_f32_e32 v21, v23, v23
	v_add_f32_e32 v22, v24, v21
	s_waitcnt vmcnt(6)
	v_pk_add_f32 v[18:19], v[18:19], v[194:195]
	v_pk_add_f32 v[16:17], v[16:17], v[192:193]
	global_store_dwordx4 v[38:39], v[16:19], off offset:576
	v_cvt_pk_bf16_f32 v20, v16, v17
	v_cvt_pk_bf16_f32 v21, v18, v19
	v_mul_f32_e32 v17, v17, v17
	v_fmac_f32_e32 v17, v16, v16
	v_fmac_f32_e32 v17, v18, v18
	v_fmac_f32_e32 v17, v19, v19
	v_add_f32_e32 v16, v22, v17
	v_mov_b32_e32 v17, v16
	s_nop 1
	v_permlane16_swap_b32_e32 v16, v17
	v_add_f32_e32 v16, v16, v17
	v_mov_b32_e32 v17, v16
	s_nop 1
	v_permlane32_swap_b32_e32 v16, v17
	global_store_dwordx2 v[40:41], v[20:21], off offset:288
	s_and_saveexec_b64 s[18:19], s[4:5]
	s_cbranch_execz .LBB0_1023
	v_lshl_add_u64 v[18:19], v[32:33], 2, s[44:45]
	v_add_f32_e32 v16, v16, v17
	global_atomic_add_f32 v[18:19], v16, off
.LBB0_1023:
	s_or_b64 exec, exec, s[18:19]
	v_add_u32_e32 v16, 0xb0, v142
	v_ashrrev_i32_e32 v17, 31, v16
	v_lshlrev_b64 v[18:19], 12, v[16:17]
	v_lshl_add_u64 v[18:19], s[66:67], 0, v[18:19]
	v_lshl_add_u64 v[22:23], v[140:141], 2, v[18:19]
	global_load_dwordx4 v[180:183], v[22:23], off
	global_load_dwordx4 v[184:187], v[22:23], off offset:64
	global_load_dwordx4 v[188:191], v[22:23], off offset:512
	global_load_dwordx4 v[192:195], v[22:23], off offset:576
	v_lshlrev_b64 v[24:25], 11, v[16:17]
	v_lshl_add_u64 v[24:25], s[68:69], 0, v[24:25]
	v_lshl_add_u64 v[24:25], v[140:141], 1, v[24:25]
	s_waitcnt vmcnt(3)
	v_pk_add_f32 v[14:15], v[14:15], v[182:183]
	v_pk_add_f32 v[12:13], v[12:13], v[180:181]
	v_cvt_pk_bf16_f32 v19, v14, v15
	v_cvt_pk_bf16_f32 v18, v12, v13
	global_store_dwordx4 v[22:23], v[12:15], off
	global_store_dwordx2 v[24:25], v[18:19], off
	s_nop 0
	v_mul_f32_e32 v13, v13, v13
	v_fmac_f32_e32 v13, v12, v12
	v_fmac_f32_e32 v13, v14, v14
	v_fmac_f32_e32 v13, v15, v15
	s_waitcnt vmcnt(4)
	v_pk_add_f32 v[10:11], v[10:11], v[186:187]
	v_pk_add_f32 v[8:9], v[8:9], v[184:185]
	v_cvt_pk_bf16_f32 v19, v10, v11
	v_cvt_pk_bf16_f32 v18, v8, v9
	global_store_dwordx4 v[22:23], v[8:11], off offset:64
	global_store_dwordx2 v[24:25], v[18:19], off offset:32
	s_nop 0
	v_mul_f32_e32 v9, v9, v9
	v_fmac_f32_e32 v9, v8, v8
	v_fmac_f32_e32 v9, v10, v10
	v_fmac_f32_e32 v9, v11, v11
	v_add_f32_e32 v8, v13, v9
	s_waitcnt vmcnt(5)
	v_pk_add_f32 v[6:7], v[6:7], v[190:191]
	v_pk_add_f32 v[4:5], v[4:5], v[188:189]
	v_cvt_pk_bf16_f32 v19, v6, v7
	v_cvt_pk_bf16_f32 v18, v4, v5
	global_store_dwordx4 v[22:23], v[4:7], off offset:512
	global_store_dwordx2 v[24:25], v[18:19], off offset:256
	s_nop 0
	v_mul_f32_e32 v5, v5, v5
	v_fmac_f32_e32 v5, v4, v4
	v_fmac_f32_e32 v5, v6, v6
	v_fmac_f32_e32 v5, v7, v7
	v_add_f32_e32 v6, v8, v5
	s_waitcnt vmcnt(6)
	v_pk_add_f32 v[2:3], v[2:3], v[194:195]
	v_pk_add_f32 v[0:1], v[0:1], v[192:193]
	global_store_dwordx4 v[22:23], v[0:3], off offset:576
	v_cvt_pk_bf16_f32 v4, v0, v1
	v_cvt_pk_bf16_f32 v5, v2, v3
	v_mul_f32_e32 v1, v1, v1
	v_fmac_f32_e32 v1, v0, v0
	v_fmac_f32_e32 v1, v2, v2
	v_fmac_f32_e32 v1, v3, v3
	v_add_f32_e32 v0, v6, v1
	v_mov_b32_e32 v1, v0
	s_nop 1
	v_permlane16_swap_b32_e32 v0, v1
	v_add_f32_e32 v0, v0, v1
	v_mov_b32_e32 v1, v0
	s_nop 1
	v_permlane32_swap_b32_e32 v0, v1
	global_store_dwordx2 v[24:25], v[4:5], off offset:288
	s_and_saveexec_b64 s[18:19], s[4:5]
	s_cbranch_execz .LBB0_1000
	v_lshl_add_u64 v[2:3], v[16:17], 2, s[44:45]
	v_add_f32_e32 v0, v0, v1
	global_atomic_add_f32 v[2:3], v0, off
	s_branch .LBB0_1000

; #define PG8_STAGE(bufoff, gbase, voff) do { _Pragma("unroll") for (int _i = 0; _i < 2; ++_i) \
;         __builtin_amdgcn_global_load_lds((const unsigned*)((const char*)(gbase) + (voff)[_i]), (LAS unsigned*)(lds + (bufoff) + ldsw + _i * 8192), 16, 0, 0); } while (0)
; #define PG8_LDA(dst, b, h) do { _Pragma("unroll") for (int m = 0; m < 4; ++m) _Pragma("unroll") for (int k = 0; k < 2; ++k) dst[m][k] = *(const LAS bf16x8*)(lds + PG8_SA(b, h) + aoff + m * 2048 + k * 1024); } while (0)
; #define PG8_WAIT_V(n) asm volatile("s_waitcnt vmcnt(" #n ")" ::: "memory")
; #define PG8_WAIT_L(n) asm volatile("s_waitcnt lgkmcnt(" #n ")" ::: "memory")
; template <class Epi>
; __device__ __forceinline__ void gemm_phase(LAS unsigned char* lds, const Gemm g, const StaticOrder& S, const Epi& E) {
;     ...
;         for (int t = 0; t < nt; t += 2) {
;             const bool last = (t == nt - 2);
;             const char* a1 = cA + (size_t)(t + 1) * kstep;
;             const char* a2 = last ? nA : cA + (size_t)(t + 2) * kstep; const char* b2 = last ? nB : cB + (size_t)(t + 2) * kstep;
;             const char* a3 = a2 + kstep; const char* b3 = b2 + kstep;
;             PG8_LDB(B0, 0, 0); PG8_SCHED; PG8_LDA(At, 0, 0); PG8_STAGE(PG8_SA(1, 1), a1 + hstep, voffA);
;             PG8_WAIT_L(8); PG8_BAR; PG8_WAIT_L(0); PG8_MMA(0, 0, At, B0); PG8_BAR; PG8_SCHED;
;             PG8_LDB(B1, 0, 1); PG8_STAGE(PG8_SB(0, 0), b2, voffB);
;             PG8_BAR; PG8_WAIT_L(0); PG8_MMA(0, 1, At, B1); PG8_BAR;
;             PG8_LDA(At, 0, 1); PG8_STAGE(PG8_SA(0, 0), a2, voffA);
;             PG8_BAR; PG8_WAIT_L(0); PG8_MMA(1, 0, At, B0); PG8_BAR; PG8_SCHED;
;             PG8_STAGE(PG8_SB(0, 1), b2 + hstep, voffB);
;             PG8_WAIT_V(6); PG8_BAR; PG8_MMA(1, 1, At, B1); PG8_BAR;
;             PG8_LDB(B0, 1, 0); PG8_SCHED; PG8_LDA(At, 1, 0); PG8_STAGE(PG8_SA(0, 1), a2 + hstep, voffA);
;             PG8_WAIT_L(8); PG8_BAR; PG8_WAIT_L(0); PG8_MMA(0, 0, At, B0); PG8_BAR; PG8_SCHED;
;             PG8_LDB(B1, 1, 1); PG8_STAGE(PG8_SB(1, 0), b3, voffB);
;             PG8_BAR; PG8_WAIT_L(0); PG8_MMA(0, 1, At, B1); PG8_BAR;
;             PG8_LDA(At, 1, 1); PG8_STAGE(PG8_SA(1, 0), a3, voffA);
;             PG8_BAR; PG8_WAIT_L(0); PG8_MMA(1, 0, At, B0); PG8_BAR; PG8_SCHED;
;             PG8_STAGE(PG8_SB(1, 1), b3 + hstep, voffB);
;             PG8_WAIT_V(6); PG8_BAR; PG8_MMA(1, 1, At, B1); PG8_BAR;
.LBB0_1377:
	ds_read_b128 v[140:143], v147
	ds_read_b128 v[150:153], v147 offset:1024
	ds_read_b128 v[154:157], v147 offset:2048
	ds_read_b128 v[158:161], v147 offset:3072
	s_add_u32 s30, s28, 0x100
	s_addc_u32 s31, s29, 0
	s_cmp_eq_u32 s59, 12
	s_cselect_b32 s39, s19, s31
	s_cselect_b32 s38, s25, s30
	s_cselect_b32 s37, s15, s58
	s_cselect_b32 s36, s56, s57
	v_lshl_add_u64 v[196:197], s[28:29], 0, v[132:133]
	s_add_i32 m0, s27, 0xc000
	ds_read_b128 v[162:165], v148
	ds_read_b128 v[166:169], v148 offset:1024
	ds_read_b128 v[170:173], v148 offset:2048
	ds_read_b128 v[174:177], v148 offset:3072
	ds_read_b128 v[180:183], v148 offset:4096
	ds_read_b128 v[184:187], v148 offset:5120
	ds_read_b128 v[188:191], v148 offset:6144
	ds_read_b128 v[192:195], v148 offset:7168
	global_load_lds_dwordx4 v[196:197], off
	v_lshl_add_u64 v[196:197], s[28:29], 0, v[134:135]
	s_add_i32 m0, s27, 0xe000
	s_nop 0
	global_load_lds_dwordx4 v[196:197], off
	s_waitcnt lgkmcnt(8)
	s_barrier
	s_waitcnt lgkmcnt(0)
	s_setprio 1
	s_waitcnt lgkmcnt(0)
	v_mfma_f32_16x16x32_bf16 v[124:127], v[140:143], v[162:165], v[124:127]
	v_mfma_f32_16x16x32_bf16 v[120:123], v[154:157], v[162:165], v[120:123]
	v_mfma_f32_16x16x32_bf16 v[108:111], v[140:143], v[170:173], v[108:111]
	v_mfma_f32_16x16x32_bf16 v[104:107], v[154:157], v[170:173], v[104:107]
	v_mfma_f32_16x16x32_bf16 v[92:95], v[140:143], v[180:183], v[92:95]
	v_mfma_f32_16x16x32_bf16 v[88:91], v[154:157], v[180:183], v[88:91]
	v_mfma_f32_16x16x32_bf16 v[76:79], v[140:143], v[188:191], v[76:79]
	v_mfma_f32_16x16x32_bf16 v[72:75], v[154:157], v[188:191], v[72:75]
	v_mfma_f32_16x16x32_bf16 v[124:127], v[150:153], v[166:169], v[124:127]
	v_mfma_f32_16x16x32_bf16 v[120:123], v[158:161], v[166:169], v[120:123]
	v_mfma_f32_16x16x32_bf16 v[108:111], v[150:153], v[174:177], v[108:111]
	v_mfma_f32_16x16x32_bf16 v[104:107], v[158:161], v[174:177], v[104:107]
	v_mfma_f32_16x16x32_bf16 v[92:95], v[150:153], v[184:187], v[92:95]
	v_mfma_f32_16x16x32_bf16 v[88:91], v[158:161], v[184:187], v[88:91]
	v_mfma_f32_16x16x32_bf16 v[76:79], v[150:153], v[192:195], v[76:79]
	v_mfma_f32_16x16x32_bf16 v[72:75], v[158:161], v[192:195], v[72:75]
	s_setprio 0
	s_barrier
	s_add_i32 s28, s50, s40
	v_lshl_add_u64 v[212:213], s[36:37], 0, v[128:129]
	s_mov_b32 m0, s28
	ds_read_b128 v[196:199], v149
	ds_read_b128 v[200:203], v149 offset:1024
	ds_read_b128 v[204:207], v149 offset:2048
	ds_read_b128 v[208:211], v149 offset:3072
	global_load_lds_dwordx4 v[212:213], off
	v_lshl_add_u64 v[214:215], s[36:37], 0, v[130:131]
	s_add_i32 m0, s28, 0x2000
	s_nop 0
	global_load_lds_dwordx4 v[214:215], off
	s_barrier
	s_waitcnt lgkmcnt(0)
	s_setprio 1
	s_waitcnt lgkmcnt(0)
	v_mfma_f32_16x16x32_bf16 v[116:119], v[196:199], v[162:165], v[116:119]
	v_mfma_f32_16x16x32_bf16 v[112:115], v[204:207], v[162:165], v[112:115]
	v_mfma_f32_16x16x32_bf16 v[100:103], v[196:199], v[170:173], v[100:103]
	v_mfma_f32_16x16x32_bf16 v[96:99], v[204:207], v[170:173], v[96:99]
	v_mfma_f32_16x16x32_bf16 v[84:87], v[196:199], v[180:183], v[84:87]
	v_mfma_f32_16x16x32_bf16 v[80:83], v[204:207], v[180:183], v[80:83]
	v_mfma_f32_16x16x32_bf16 v[68:71], v[196:199], v[188:191], v[68:71]
	v_mfma_f32_16x16x32_bf16 v[64:67], v[204:207], v[188:191], v[64:67]
	v_mfma_f32_16x16x32_bf16 v[116:119], v[200:203], v[166:169], v[116:119]
	v_mfma_f32_16x16x32_bf16 v[112:115], v[208:211], v[166:169], v[112:115]
	v_mfma_f32_16x16x32_bf16 v[100:103], v[200:203], v[174:177], v[100:103]
	v_mfma_f32_16x16x32_bf16 v[96:99], v[208:211], v[174:177], v[96:99]
	v_mfma_f32_16x16x32_bf16 v[84:87], v[200:203], v[184:187], v[84:87]
	v_mfma_f32_16x16x32_bf16 v[80:83], v[208:211], v[184:187], v[80:83]
	v_mfma_f32_16x16x32_bf16 v[68:71], v[200:203], v[192:195], v[68:71]
	v_mfma_f32_16x16x32_bf16 v[64:67], v[208:211], v[192:195], v[64:67]
	s_setprio 0
	s_mov_b32 m0, s27
	v_lshl_add_u64 v[216:217], s[38:39], 0, v[128:129]
	s_barrier
	ds_read_b128 v[162:165], v148 offset:16384
	ds_read_b128 v[166:169], v148 offset:17408
	ds_read_b128 v[170:173], v148 offset:18432
	ds_read_b128 v[174:177], v148 offset:19456
	ds_read_b128 v[180:183], v148 offset:20480
	ds_read_b128 v[184:187], v148 offset:21504
	ds_read_b128 v[188:191], v148 offset:22528
	ds_read_b128 v[192:195], v148 offset:23552
	global_load_lds_dwordx4 v[216:217], off
	v_lshl_add_u64 v[218:219], s[38:39], 0, v[130:131]
	s_mov_b32 m0, s41
	s_nop 0
	global_load_lds_dwordx4 v[218:219], off
	s_barrier
	s_waitcnt lgkmcnt(0)
	s_setprio 1
	s_waitcnt lgkmcnt(0)
	v_mfma_f32_16x16x32_bf16 v[60:63], v[140:143], v[162:165], v[60:63]
	v_mfma_f32_16x16x32_bf16 v[56:59], v[154:157], v[162:165], v[56:59]
	v_mfma_f32_16x16x32_bf16 v[44:47], v[140:143], v[170:173], v[44:47]
	v_mfma_f32_16x16x32_bf16 v[40:43], v[154:157], v[170:173], v[40:43]
	v_mfma_f32_16x16x32_bf16 v[28:31], v[140:143], v[180:183], v[28:31]
	v_mfma_f32_16x16x32_bf16 v[24:27], v[154:157], v[180:183], v[24:27]
	v_mfma_f32_16x16x32_bf16 v[12:15], v[140:143], v[188:191], v[12:15]
	v_mfma_f32_16x16x32_bf16 v[8:11], v[154:157], v[188:191], v[8:11]
	v_mfma_f32_16x16x32_bf16 v[60:63], v[150:153], v[166:169], v[60:63]
	v_mfma_f32_16x16x32_bf16 v[56:59], v[158:161], v[166:169], v[56:59]
	v_mfma_f32_16x16x32_bf16 v[44:47], v[150:153], v[174:177], v[44:47]
	v_mfma_f32_16x16x32_bf16 v[40:43], v[158:161], v[174:177], v[40:43]
	v_mfma_f32_16x16x32_bf16 v[28:31], v[150:153], v[184:187], v[28:31]
	v_mfma_f32_16x16x32_bf16 v[24:27], v[158:161], v[184:187], v[24:27]
	v_mfma_f32_16x16x32_bf16 v[12:15], v[150:153], v[192:195], v[12:15]
	v_mfma_f32_16x16x32_bf16 v[8:11], v[158:161], v[192:195], v[8:11]
	s_setprio 0
	s_barrier
; #define PG8_STAGE(bufoff, gbase, voff) do { _Pragma("unroll") for (int _i = 0; _i < 2; ++_i) \
;         __builtin_amdgcn_global_load_lds((const unsigned*)((const char*)(gbase) + (voff)[_i]), (LAS unsigned*)(lds + (bufoff) + ldsw + _i * 8192), 16, 0, 0); } while (0)
; #define PG8_LDA(dst, b, h) do { _Pragma("unroll") for (int m = 0; m < 4; ++m) _Pragma("unroll") for (int k = 0; k < 2; ++k) dst[m][k] = *(const LAS bf16x8*)(lds + PG8_SA(b, h) + aoff + m * 2048 + k * 1024); } while (0)
; #define PG8_WAIT_V(n) asm volatile("s_waitcnt vmcnt(" #n ")" ::: "memory")
; #define PG8_WAIT_L(n) asm volatile("s_waitcnt lgkmcnt(" #n ")" ::: "memory")
; template <class Epi>
; __device__ __forceinline__ void gemm_phase(LAS unsigned char* lds, const Gemm g, const StaticOrder& S, const Epi& E) {
;     ...
;         for (int t = 0; t < nt; t += 2) {
;             const bool last = (t == nt - 2);
;             const char* a1 = cA + (size_t)(t + 1) * kstep;
;             const char* a2 = last ? nA : cA + (size_t)(t + 2) * kstep; const char* b2 = last ? nB : cB + (size_t)(t + 2) * kstep;
;             const char* a3 = a2 + kstep; const char* b3 = b2 + kstep;
;             PG8_LDB(B0, 0, 0); PG8_SCHED; PG8_LDA(At, 0, 0); PG8_STAGE(PG8_SA(1, 1), a1 + hstep, voffA);
;             PG8_WAIT_L(8); PG8_BAR; PG8_WAIT_L(0); PG8_MMA(0, 0, At, B0); PG8_BAR; PG8_SCHED;
;             PG8_LDB(B1, 0, 1); PG8_STAGE(PG8_SB(0, 0), b2, voffB);
;             PG8_BAR; PG8_WAIT_L(0); PG8_MMA(0, 1, At, B1); PG8_BAR;
;             PG8_LDA(At, 0, 1); PG8_STAGE(PG8_SA(0, 0), a2, voffA);
;             PG8_BAR; PG8_WAIT_L(0); PG8_MMA(1, 0, At, B0); PG8_BAR; PG8_SCHED;
;             PG8_STAGE(PG8_SB(0, 1), b2 + hstep, voffB);
;             PG8_WAIT_V(6); PG8_BAR; PG8_MMA(1, 1, At, B1); PG8_BAR;
;             PG8_LDB(B0, 1, 0); PG8_SCHED; PG8_LDA(At, 1, 0); PG8_STAGE(PG8_SA(0, 1), a2 + hstep, voffA);
;             PG8_WAIT_L(8); PG8_BAR; PG8_WAIT_L(0); PG8_MMA(0, 0, At, B0); PG8_BAR; PG8_SCHED;
;             PG8_LDB(B1, 1, 1); PG8_STAGE(PG8_SB(1, 0), b3, voffB);
;             PG8_BAR; PG8_WAIT_L(0); PG8_MMA(0, 1, At, B1); PG8_BAR;
;             PG8_LDA(At, 1, 1); PG8_STAGE(PG8_SA(1, 0), a3, voffA);
;             PG8_BAR; PG8_WAIT_L(0); PG8_MMA(1, 0, At, B0); PG8_BAR; PG8_SCHED;
;             PG8_STAGE(PG8_SB(1, 1), b3 + hstep, voffB);
;             PG8_WAIT_V(6); PG8_BAR; PG8_MMA(1, 1, At, B1); PG8_BAR;
	s_add_u32 s28, s36, 0x40000
	s_addc_u32 s29, s37, 0
	s_add_i32 s60, s51, s40
	v_lshl_add_u64 v[140:141], s[28:29], 0, v[128:129]
	s_mov_b32 m0, s60
	s_nop 0
	global_load_lds_dwordx4 v[140:141], off
	v_lshl_add_u64 v[140:141], s[28:29], 0, v[130:131]
	s_add_i32 m0, s60, 0x2000
	s_nop 0
	global_load_lds_dwordx4 v[140:141], off
	s_waitcnt vmcnt(6)
	s_barrier
	s_setprio 1
	v_mfma_f32_16x16x32_bf16 v[52:55], v[196:199], v[162:165], v[52:55]
	v_mfma_f32_16x16x32_bf16 v[48:51], v[204:207], v[162:165], v[48:51]
	v_mfma_f32_16x16x32_bf16 v[36:39], v[196:199], v[170:173], v[36:39]
	v_mfma_f32_16x16x32_bf16 v[32:35], v[204:207], v[170:173], v[32:35]
	v_mfma_f32_16x16x32_bf16 v[20:23], v[196:199], v[180:183], v[20:23]
	v_mfma_f32_16x16x32_bf16 v[16:19], v[204:207], v[180:183], v[16:19]
	v_mfma_f32_16x16x32_bf16 v[4:7], v[196:199], v[188:191], v[4:7]
	v_mfma_f32_16x16x32_bf16 v[0:3], v[204:207], v[188:191], v[0:3]
	v_mfma_f32_16x16x32_bf16 v[52:55], v[200:203], v[166:169], v[52:55]
	v_mfma_f32_16x16x32_bf16 v[48:51], v[208:211], v[166:169], v[48:51]
	v_mfma_f32_16x16x32_bf16 v[36:39], v[200:203], v[174:177], v[36:39]
	v_mfma_f32_16x16x32_bf16 v[32:35], v[208:211], v[174:177], v[32:35]
	v_mfma_f32_16x16x32_bf16 v[20:23], v[200:203], v[184:187], v[20:23]
	v_mfma_f32_16x16x32_bf16 v[16:19], v[208:211], v[184:187], v[16:19]
	v_mfma_f32_16x16x32_bf16 v[4:7], v[200:203], v[192:195], v[4:7]
	v_mfma_f32_16x16x32_bf16 v[0:3], v[208:211], v[192:195], v[0:3]
	s_setprio 0
	s_add_i32 s60, 0, 0x18000
	v_add_u32_e32 v158, s60, v145
	s_barrier
	ds_read_b128 v[140:143], v158
	ds_read_b128 v[150:153], v158 offset:1024
	ds_read_b128 v[154:157], v158 offset:2048
	ds_read_b128 v[158:161], v158 offset:3072
	s_add_u32 s28, s38, 0x40000
	s_addc_u32 s29, s39, 0
	s_mov_b32 m0, s42
	v_lshl_add_u64 v[196:197], s[28:29], 0, v[128:129]
	ds_read_b128 v[162:165], v148 offset:32768
	ds_read_b128 v[166:169], v148 offset:33792
	ds_read_b128 v[170:173], v148 offset:34816
	ds_read_b128 v[174:177], v148 offset:35840
	ds_read_b128 v[180:183], v148 offset:36864
	ds_read_b128 v[184:187], v148 offset:37888
	ds_read_b128 v[188:191], v148 offset:38912
	ds_read_b128 v[192:195], v148 offset:39936
	global_load_lds_dwordx4 v[196:197], off
	v_lshl_add_u64 v[196:197], s[28:29], 0, v[130:131]
	s_mov_b32 m0, s43
	s_nop 0
	global_load_lds_dwordx4 v[196:197], off
	s_waitcnt lgkmcnt(8)
	s_barrier
	s_waitcnt lgkmcnt(0)
	s_setprio 1
	s_waitcnt lgkmcnt(0)
	v_mfma_f32_16x16x32_bf16 v[124:127], v[140:143], v[162:165], v[124:127]
	v_mfma_f32_16x16x32_bf16 v[120:123], v[154:157], v[162:165], v[120:123]
	v_mfma_f32_16x16x32_bf16 v[108:111], v[140:143], v[170:173], v[108:111]
	v_mfma_f32_16x16x32_bf16 v[104:107], v[154:157], v[170:173], v[104:107]
	v_mfma_f32_16x16x32_bf16 v[92:95], v[140:143], v[180:183], v[92:95]
	v_mfma_f32_16x16x32_bf16 v[88:91], v[154:157], v[180:183], v[88:91]
	v_mfma_f32_16x16x32_bf16 v[76:79], v[140:143], v[188:191], v[76:79]
	v_mfma_f32_16x16x32_bf16 v[72:75], v[154:157], v[188:191], v[72:75]
	v_mfma_f32_16x16x32_bf16 v[124:127], v[150:153], v[166:169], v[124:127]
	v_mfma_f32_16x16x32_bf16 v[120:123], v[158:161], v[166:169], v[120:123]
	v_mfma_f32_16x16x32_bf16 v[108:111], v[150:153], v[174:177], v[108:111]
	v_mfma_f32_16x16x32_bf16 v[104:107], v[158:161], v[174:177], v[104:107]
	v_mfma_f32_16x16x32_bf16 v[92:95], v[150:153], v[184:187], v[92:95]
	v_mfma_f32_16x16x32_bf16 v[88:91], v[158:161], v[184:187], v[88:91]
	v_mfma_f32_16x16x32_bf16 v[76:79], v[150:153], v[192:195], v[76:79]
	v_mfma_f32_16x16x32_bf16 v[72:75], v[158:161], v[192:195], v[72:75]
	s_setprio 0
	s_barrier
	s_add_i32 s38, 0, 0x1c000
	s_add_i32 s28, s60, s40
	v_add_u32_e32 v179, s38, v145
	v_lshl_add_u64 v[212:213], v[212:213], 0, s[12:13]
	s_mov_b32 m0, s28
	ds_read_b128 v[196:199], v179
	ds_read_b128 v[200:203], v179 offset:1024
	ds_read_b128 v[204:207], v179 offset:2048
	ds_read_b128 v[208:211], v179 offset:3072
	global_load_lds_dwordx4 v[212:213], off
	v_lshl_add_u64 v[212:213], v[214:215], 0, s[12:13]
	s_add_i32 m0, s28, 0x2000
	s_nop 0
	global_load_lds_dwordx4 v[212:213], off
	s_barrier
	s_waitcnt lgkmcnt(0)
	s_setprio 1
	s_waitcnt lgkmcnt(0)
	v_mfma_f32_16x16x32_bf16 v[116:119], v[196:199], v[162:165], v[116:119]
	v_mfma_f32_16x16x32_bf16 v[112:115], v[204:207], v[162:165], v[112:115]
	v_mfma_f32_16x16x32_bf16 v[100:103], v[196:199], v[170:173], v[100:103]
	v_mfma_f32_16x16x32_bf16 v[96:99], v[204:207], v[170:173], v[96:99]
	v_mfma_f32_16x16x32_bf16 v[84:87], v[196:199], v[180:183], v[84:87]
	v_mfma_f32_16x16x32_bf16 v[80:83], v[204:207], v[180:183], v[80:83]
	v_mfma_f32_16x16x32_bf16 v[68:71], v[196:199], v[188:191], v[68:71]
	v_mfma_f32_16x16x32_bf16 v[64:67], v[204:207], v[188:191], v[64:67]
	v_mfma_f32_16x16x32_bf16 v[116:119], v[200:203], v[166:169], v[116:119]
	v_mfma_f32_16x16x32_bf16 v[112:115], v[208:211], v[166:169], v[112:115]
	v_mfma_f32_16x16x32_bf16 v[100:103], v[200:203], v[174:177], v[100:103]
	v_mfma_f32_16x16x32_bf16 v[96:99], v[208:211], v[174:177], v[96:99]
	v_mfma_f32_16x16x32_bf16 v[84:87], v[200:203], v[184:187], v[84:87]
	v_mfma_f32_16x16x32_bf16 v[80:83], v[208:211], v[184:187], v[80:83]
	v_mfma_f32_16x16x32_bf16 v[68:71], v[200:203], v[192:195], v[68:71]
	v_mfma_f32_16x16x32_bf16 v[64:67], v[208:211], v[192:195], v[64:67]
	s_setprio 0
	s_mov_b32 m0, s45
	v_lshl_add_u64 v[212:213], v[216:217], 0, s[12:13]
	s_barrier
	ds_read_b128 v[162:165], v148 offset:49152
	ds_read_b128 v[166:169], v148 offset:50176
	ds_read_b128 v[170:173], v148 offset:51200
	ds_read_b128 v[174:177], v148 offset:52224
	ds_read_b128 v[180:183], v148 offset:53248
	ds_read_b128 v[184:187], v148 offset:54272
	ds_read_b128 v[188:191], v148 offset:55296
	ds_read_b128 v[192:195], v148 offset:56320
	global_load_lds_dwordx4 v[212:213], off
	v_lshl_add_u64 v[212:213], v[218:219], 0, s[12:13]
	s_mov_b32 m0, s46
	s_nop 0
	global_load_lds_dwordx4 v[212:213], off
	s_barrier
; DI unsigned pk2(float a, float b) { f32x2 v = {a, b}; hbf2 r = __builtin_convertvector(v, hbf2); return __builtin_bit_cast(unsigned, r); }
; template <class Epi>
; __device__ __forceinline__ void gemm_phase(LAS unsigned char* lds, const Gemm g, const StaticOrder& S, const Epi& E) {
;     ...
;             PG8_WAIT_V(6); PG8_BAR; PG8_MMA(1, 1, At, B1); PG8_BAR;
;             PG8_LDB(B0, 1, 0); PG8_SCHED; PG8_LDA(At, 1, 0); PG8_STAGE(PG8_SA(0, 1), a2 + hstep, voffA);
;             PG8_WAIT_L(8); PG8_BAR; PG8_WAIT_L(0); PG8_MMA(0, 0, At, B0); PG8_BAR; PG8_SCHED;
;             PG8_LDB(B1, 1, 1); PG8_STAGE(PG8_SB(1, 0), b3, voffB);
;             PG8_BAR; PG8_WAIT_L(0); PG8_MMA(0, 1, At, B1); PG8_BAR;
;             PG8_LDA(At, 1, 1); PG8_STAGE(PG8_SA(1, 0), a3, voffA);
;             PG8_BAR; PG8_WAIT_L(0); PG8_MMA(1, 0, At, B0); PG8_BAR; PG8_SCHED;
;             PG8_STAGE(PG8_SB(1, 1), b3 + hstep, voffB);
;             PG8_WAIT_V(6); PG8_BAR; PG8_MMA(1, 1, At, B1); PG8_BAR;
;     DI void operator()(const f32x4 (&acc)[2][2][4][2], const Unit& u, int wr, int wc, int fr, int fq) const {
;         const int row0 = u.pm * 256 + wr * 64 + fr, col0 = u.pn * 256 + wc * 32 + 4 * fq;
; #pragma unroll
;         for (int ai = 0; ai < 2; ++ai)
; #pragma unroll
;             for (int m = 0; m < 4; ++m) {
;                 const int r = row0 + ai * 128 + m * 16;
;                 const float* rp;
;                 if (MODE == 0) rp = x + (size_t)r * 1024;
;                 else rp = h + (size_t)r * 1024;
;                 float sq = 0.f;
; #pragma unroll
;                 for (int bj = 0; bj < 2; ++bj)
; #pragma unroll
;                     for (int n = 0; n < 2; ++n) {
;                         const int c = col0 + bj * 128 + n * 16;
;                         f32x4 rv = rp ? *(const f32x4*)(rp + c) : (f32x4){0.f, 0.f, 0.f, 0.f};
;                         f32x4 v = acc[ai][bj][m][n] + rv;
;                         *(f32x4*)(h + (size_t)r * 1024 + c) = v;
;                         if (WRITE_HB) {
;                             u32x2 w; w.x = pk2(v[0], v[1]); w.y = pk2(v[2], v[3]);
;                             *(u32x2*)(hb + (size_t)r * 1024 + c) = w;
;                         }
;                         sq += v[0] * v[0] + v[1] * v[1] + v[2] * v[2] + v[3] * v[3];
;                     }
;                 sq = sum_x16_x32(sq);
;                 if (fq == 0) atomicAdd(ss + r, sq);
	s_waitcnt lgkmcnt(0)
	s_setprio 1
	s_waitcnt lgkmcnt(0)
	v_mfma_f32_16x16x32_bf16 v[60:63], v[140:143], v[162:165], v[60:63]
	v_mfma_f32_16x16x32_bf16 v[56:59], v[154:157], v[162:165], v[56:59]
	v_mfma_f32_16x16x32_bf16 v[44:47], v[140:143], v[170:173], v[44:47]
	v_mfma_f32_16x16x32_bf16 v[40:43], v[154:157], v[170:173], v[40:43]
	v_mfma_f32_16x16x32_bf16 v[28:31], v[140:143], v[180:183], v[28:31]
	v_mfma_f32_16x16x32_bf16 v[24:27], v[154:157], v[180:183], v[24:27]
	v_mfma_f32_16x16x32_bf16 v[12:15], v[140:143], v[188:191], v[12:15]
	v_mfma_f32_16x16x32_bf16 v[8:11], v[154:157], v[188:191], v[8:11]
	v_mfma_f32_16x16x32_bf16 v[60:63], v[150:153], v[166:169], v[60:63]
	v_mfma_f32_16x16x32_bf16 v[56:59], v[158:161], v[166:169], v[56:59]
	v_mfma_f32_16x16x32_bf16 v[44:47], v[150:153], v[174:177], v[44:47]
	v_mfma_f32_16x16x32_bf16 v[40:43], v[158:161], v[174:177], v[40:43]
	v_mfma_f32_16x16x32_bf16 v[28:31], v[150:153], v[184:187], v[28:31]
	v_mfma_f32_16x16x32_bf16 v[24:27], v[158:161], v[184:187], v[24:27]
	v_mfma_f32_16x16x32_bf16 v[12:15], v[150:153], v[192:195], v[12:15]
	v_mfma_f32_16x16x32_bf16 v[8:11], v[158:161], v[192:195], v[8:11]
	s_setprio 0
	s_barrier
	s_add_u32 s28, s36, 0x40080
	s_addc_u32 s29, s37, 0
	s_add_i32 s36, s38, s40
	v_lshl_add_u64 v[140:141], s[28:29], 0, v[128:129]
	s_mov_b32 m0, s36
	s_nop 0
	global_load_lds_dwordx4 v[140:141], off
	v_lshl_add_u64 v[140:141], s[28:29], 0, v[130:131]
	s_add_i32 m0, s36, 0x2000
	s_nop 0
	global_load_lds_dwordx4 v[140:141], off
	s_waitcnt vmcnt(6)
	s_barrier
	s_setprio 1
	v_mfma_f32_16x16x32_bf16 v[52:55], v[196:199], v[162:165], v[52:55]
	v_mfma_f32_16x16x32_bf16 v[48:51], v[204:207], v[162:165], v[48:51]
	v_mfma_f32_16x16x32_bf16 v[36:39], v[196:199], v[170:173], v[36:39]
	v_mfma_f32_16x16x32_bf16 v[32:35], v[204:207], v[170:173], v[32:35]
	v_mfma_f32_16x16x32_bf16 v[20:23], v[196:199], v[180:183], v[20:23]
	v_mfma_f32_16x16x32_bf16 v[16:19], v[204:207], v[180:183], v[16:19]
	v_mfma_f32_16x16x32_bf16 v[4:7], v[196:199], v[188:191], v[4:7]
	v_mfma_f32_16x16x32_bf16 v[0:3], v[204:207], v[188:191], v[0:3]
	v_mfma_f32_16x16x32_bf16 v[52:55], v[200:203], v[166:169], v[52:55]
	v_mfma_f32_16x16x32_bf16 v[48:51], v[208:211], v[166:169], v[48:51]
	v_mfma_f32_16x16x32_bf16 v[36:39], v[200:203], v[174:177], v[36:39]
	v_mfma_f32_16x16x32_bf16 v[32:35], v[208:211], v[174:177], v[32:35]
	v_mfma_f32_16x16x32_bf16 v[20:23], v[200:203], v[184:187], v[20:23]
	v_mfma_f32_16x16x32_bf16 v[16:19], v[208:211], v[184:187], v[16:19]
	v_mfma_f32_16x16x32_bf16 v[4:7], v[200:203], v[192:195], v[4:7]
	v_mfma_f32_16x16x32_bf16 v[0:3], v[208:211], v[192:195], v[0:3]
	s_setprio 0
	s_add_i32 s59, s59, 2
	s_add_u32 s57, s57, 0x100
	s_addc_u32 s58, s58, 0
	s_cmp_gt_u32 s59, 13
	s_mov_b64 s[28:29], s[30:31]
	s_barrier
	s_cbranch_scc0 .LBB0_1377
	v_lshl_add_u32 v142, s24, 8, v144
	v_ashrrev_i32_e32 v143, 31, v142
	v_lshl_or_b32 v140, s26, 8, v146
	v_lshlrev_b64 v[150:151], 12, v[142:143]
	v_lshl_add_u64 v[150:151], s[66:67], 0, v[150:151]
	v_ashrrev_i32_e32 v141, 31, v140
	v_lshl_add_u64 v[154:155], v[140:141], 2, v[150:151]
	global_load_dwordx4 v[180:183], v[154:155], off
	global_load_dwordx4 v[184:187], v[154:155], off offset:64
	global_load_dwordx4 v[188:191], v[154:155], off offset:512
	global_load_dwordx4 v[192:195], v[154:155], off offset:576
	v_lshlrev_b64 v[156:157], 11, v[142:143]
	v_lshl_add_u64 v[156:157], s[68:69], 0, v[156:157]
	v_lshl_add_u64 v[156:157], v[140:141], 1, v[156:157]
	s_waitcnt vmcnt(3)
	v_pk_add_f32 v[126:127], v[126:127], v[182:183]
	v_pk_add_f32 v[124:125], v[124:125], v[180:181]
	v_cvt_pk_bf16_f32 v151, v126, v127
	v_cvt_pk_bf16_f32 v150, v124, v125
	global_store_dwordx4 v[154:155], v[124:127], off
	global_store_dwordx2 v[156:157], v[150:151], off
	s_nop 0
	v_mul_f32_e32 v125, v125, v125
	v_fmac_f32_e32 v125, v124, v124
	v_fmac_f32_e32 v125, v126, v126
	v_fmac_f32_e32 v125, v127, v127
	s_waitcnt vmcnt(4)
	v_pk_add_f32 v[122:123], v[122:123], v[186:187]
	v_pk_add_f32 v[120:121], v[120:121], v[184:185]
	v_cvt_pk_bf16_f32 v151, v122, v123
	v_cvt_pk_bf16_f32 v150, v120, v121
	global_store_dwordx4 v[154:155], v[120:123], off offset:64
	global_store_dwordx2 v[156:157], v[150:151], off offset:32
	s_nop 0
	v_mul_f32_e32 v121, v121, v121
	v_fmac_f32_e32 v121, v120, v120
	v_fmac_f32_e32 v121, v122, v122
	v_fmac_f32_e32 v121, v123, v123
	v_add_f32_e32 v120, v125, v121
	s_waitcnt vmcnt(5)
	v_pk_add_f32 v[118:119], v[118:119], v[190:191]
	v_pk_add_f32 v[116:117], v[116:117], v[188:189]
	v_cvt_pk_bf16_f32 v151, v118, v119
	v_cvt_pk_bf16_f32 v150, v116, v117
	global_store_dwordx4 v[154:155], v[116:119], off offset:512
	global_store_dwordx2 v[156:157], v[150:151], off offset:256
	s_nop 0
	v_mul_f32_e32 v117, v117, v117
	v_fmac_f32_e32 v117, v116, v116
	v_fmac_f32_e32 v117, v118, v118
	v_fmac_f32_e32 v117, v119, v119
	v_add_f32_e32 v118, v120, v117
	s_waitcnt vmcnt(6)
	v_pk_add_f32 v[114:115], v[114:115], v[194:195]
	v_pk_add_f32 v[112:113], v[112:113], v[192:193]
	global_store_dwordx4 v[154:155], v[112:115], off offset:576
	v_cvt_pk_bf16_f32 v116, v112, v113
	v_cvt_pk_bf16_f32 v117, v114, v115
	v_mul_f32_e32 v113, v113, v113
	v_fmac_f32_e32 v113, v112, v112
	v_fmac_f32_e32 v113, v114, v114
	v_fmac_f32_e32 v113, v115, v115
	v_add_f32_e32 v112, v118, v113
	v_mov_b32_e32 v113, v112
	s_nop 1
	v_permlane16_swap_b32_e32 v112, v113
	v_add_f32_e32 v112, v112, v113
	v_mov_b32_e32 v113, v112
	s_nop 1
	v_permlane32_swap_b32_e32 v112, v113
	global_store_dwordx2 v[156:157], v[116:117], off offset:288
	s_and_saveexec_b64 s[24:25], s[6:7]
	s_cbranch_execz .LBB0_1380
	v_lshl_add_u64 v[114:115], v[142:143], 2, s[10:11]
	v_add_f32_e32 v112, v112, v113
	global_atomic_add_f32 v[114:115], v112, off
; DI unsigned pk2(float a, float b) { f32x2 v = {a, b}; hbf2 r = __builtin_convertvector(v, hbf2); return __builtin_bit_cast(unsigned, r); }
; DI float sum_x16_x32(float x) { return sum_x32(sum_x16(x)); }
;     DI void operator()(const f32x4 (&acc)[2][2][4][2], const Unit& u, int wr, int wc, int fr, int fq) const {
;         const int row0 = u.pm * 256 + wr * 64 + fr, col0 = u.pn * 256 + wc * 32 + 4 * fq;
; #pragma unroll
;         for (int ai = 0; ai < 2; ++ai)
; #pragma unroll
;             for (int m = 0; m < 4; ++m) {
;                 const int r = row0 + ai * 128 + m * 16;
;                 const float* rp;
;                 if (MODE == 0) rp = x + (size_t)r * 1024;
;                 else rp = h + (size_t)r * 1024;
;                 float sq = 0.f;
; #pragma unroll
;                 for (int bj = 0; bj < 2; ++bj)
; #pragma unroll
;                     for (int n = 0; n < 2; ++n) {
;                         const int c = col0 + bj * 128 + n * 16;
;                         f32x4 rv = rp ? *(const f32x4*)(rp + c) : (f32x4){0.f, 0.f, 0.f, 0.f};
;                         f32x4 v = acc[ai][bj][m][n] + rv;
;                         *(f32x4*)(h + (size_t)r * 1024 + c) = v;
;                         if (WRITE_HB) {
;                             u32x2 w; w.x = pk2(v[0], v[1]); w.y = pk2(v[2], v[3]);
;                             *(u32x2*)(hb + (size_t)r * 1024 + c) = w;
;                         }
;                         sq += v[0] * v[0] + v[1] * v[1] + v[2] * v[2] + v[3] * v[3];
;                     }
;                 sq = sum_x16_x32(sq);
;                 if (fq == 0) atomicAdd(ss + r, sq);
.LBB0_1380:
	s_or_b64 exec, exec, s[24:25]
	v_or_b32_e32 v112, 16, v142
	v_ashrrev_i32_e32 v113, 31, v112
	v_lshlrev_b64 v[114:115], 12, v[112:113]
	v_lshl_add_u64 v[114:115], s[66:67], 0, v[114:115]
	v_lshl_add_u64 v[118:119], v[140:141], 2, v[114:115]
	global_load_dwordx4 v[180:183], v[118:119], off
	global_load_dwordx4 v[184:187], v[118:119], off offset:64
	global_load_dwordx4 v[188:191], v[118:119], off offset:512
	global_load_dwordx4 v[192:195], v[118:119], off offset:576
	v_lshlrev_b64 v[120:121], 11, v[112:113]
	v_lshl_add_u64 v[120:121], s[68:69], 0, v[120:121]
	v_lshl_add_u64 v[120:121], v[140:141], 1, v[120:121]
	s_waitcnt vmcnt(3)
	v_pk_add_f32 v[110:111], v[110:111], v[182:183]
	v_pk_add_f32 v[108:109], v[108:109], v[180:181]
	v_cvt_pk_bf16_f32 v115, v110, v111
	v_cvt_pk_bf16_f32 v114, v108, v109
	global_store_dwordx4 v[118:119], v[108:111], off
	global_store_dwordx2 v[120:121], v[114:115], off
	s_nop 0
	v_mul_f32_e32 v109, v109, v109
	v_fmac_f32_e32 v109, v108, v108
	v_fmac_f32_e32 v109, v110, v110
	v_fmac_f32_e32 v109, v111, v111
	s_waitcnt vmcnt(4)
	v_pk_add_f32 v[106:107], v[106:107], v[186:187]
	v_pk_add_f32 v[104:105], v[104:105], v[184:185]
	v_cvt_pk_bf16_f32 v115, v106, v107
	v_cvt_pk_bf16_f32 v114, v104, v105
	global_store_dwordx4 v[118:119], v[104:107], off offset:64
	global_store_dwordx2 v[120:121], v[114:115], off offset:32
	s_nop 0
	v_mul_f32_e32 v105, v105, v105
	v_fmac_f32_e32 v105, v104, v104
	v_fmac_f32_e32 v105, v106, v106
	v_fmac_f32_e32 v105, v107, v107
	v_add_f32_e32 v104, v109, v105
	s_waitcnt vmcnt(5)
	v_pk_add_f32 v[102:103], v[102:103], v[190:191]
	v_pk_add_f32 v[100:101], v[100:101], v[188:189]
	v_cvt_pk_bf16_f32 v115, v102, v103
	v_cvt_pk_bf16_f32 v114, v100, v101
	global_store_dwordx4 v[118:119], v[100:103], off offset:512
	global_store_dwordx2 v[120:121], v[114:115], off offset:256
	s_nop 0
	v_mul_f32_e32 v101, v101, v101
	v_fmac_f32_e32 v101, v100, v100
	v_fmac_f32_e32 v101, v102, v102
	v_fmac_f32_e32 v101, v103, v103
	v_add_f32_e32 v102, v104, v101
	s_waitcnt vmcnt(6)
	v_pk_add_f32 v[98:99], v[98:99], v[194:195]
	v_pk_add_f32 v[96:97], v[96:97], v[192:193]
	global_store_dwordx4 v[118:119], v[96:99], off offset:576
	v_cvt_pk_bf16_f32 v100, v96, v97
	v_cvt_pk_bf16_f32 v101, v98, v99
	v_mul_f32_e32 v97, v97, v97
	v_fmac_f32_e32 v97, v96, v96
	v_fmac_f32_e32 v97, v98, v98
	v_fmac_f32_e32 v97, v99, v99
	v_add_f32_e32 v96, v102, v97
	v_mov_b32_e32 v97, v96
	s_nop 1
	v_permlane16_swap_b32_e32 v96, v97
	v_add_f32_e32 v96, v96, v97
	v_mov_b32_e32 v97, v96
	s_nop 1
	v_permlane32_swap_b32_e32 v96, v97
	global_store_dwordx2 v[120:121], v[100:101], off offset:288
	s_and_saveexec_b64 s[24:25], s[6:7]
	s_cbranch_execz .LBB0_1382
	v_lshl_add_u64 v[98:99], v[112:113], 2, s[10:11]
	v_add_f32_e32 v96, v96, v97
	global_atomic_add_f32 v[98:99], v96, off
.LBB0_1382:
	s_or_b64 exec, exec, s[24:25]
	v_or_b32_e32 v96, 32, v142
	v_ashrrev_i32_e32 v97, 31, v96
	v_lshlrev_b64 v[98:99], 12, v[96:97]
	v_lshl_add_u64 v[98:99], s[66:67], 0, v[98:99]
	v_lshl_add_u64 v[102:103], v[140:141], 2, v[98:99]
	global_load_dwordx4 v[180:183], v[102:103], off
	global_load_dwordx4 v[184:187], v[102:103], off offset:64
	global_load_dwordx4 v[188:191], v[102:103], off offset:512
	global_load_dwordx4 v[192:195], v[102:103], off offset:576
	v_lshlrev_b64 v[104:105], 11, v[96:97]
	v_lshl_add_u64 v[104:105], s[68:69], 0, v[104:105]
	v_lshl_add_u64 v[104:105], v[140:141], 1, v[104:105]
	s_waitcnt vmcnt(3)
	v_pk_add_f32 v[94:95], v[94:95], v[182:183]
	v_pk_add_f32 v[92:93], v[92:93], v[180:181]
	v_cvt_pk_bf16_f32 v99, v94, v95
	v_cvt_pk_bf16_f32 v98, v92, v93
	global_store_dwordx4 v[102:103], v[92:95], off
	global_store_dwordx2 v[104:105], v[98:99], off
	s_nop 0
	v_mul_f32_e32 v93, v93, v93
	v_fmac_f32_e32 v93, v92, v92
	v_fmac_f32_e32 v93, v94, v94
	v_fmac_f32_e32 v93, v95, v95
	s_waitcnt vmcnt(4)
	v_pk_add_f32 v[90:91], v[90:91], v[186:187]
	v_pk_add_f32 v[88:89], v[88:89], v[184:185]
	v_cvt_pk_bf16_f32 v99, v90, v91
	v_cvt_pk_bf16_f32 v98, v88, v89
	global_store_dwordx4 v[102:103], v[88:91], off offset:64
	global_store_dwordx2 v[104:105], v[98:99], off offset:32
	s_nop 0
	v_mul_f32_e32 v89, v89, v89
	v_fmac_f32_e32 v89, v88, v88
	v_fmac_f32_e32 v89, v90, v90
	v_fmac_f32_e32 v89, v91, v91
	v_add_f32_e32 v88, v93, v89
	s_waitcnt vmcnt(5)
	v_pk_add_f32 v[86:87], v[86:87], v[190:191]
	v_pk_add_f32 v[84:85], v[84:85], v[188:189]
	v_cvt_pk_bf16_f32 v99, v86, v87
	v_cvt_pk_bf16_f32 v98, v84, v85
	global_store_dwordx4 v[102:103], v[84:87], off offset:512
	global_store_dwordx2 v[104:105], v[98:99], off offset:256
	s_nop 0
	v_mul_f32_e32 v85, v85, v85
	v_fmac_f32_e32 v85, v84, v84
	v_fmac_f32_e32 v85, v86, v86
	v_fmac_f32_e32 v85, v87, v87
	v_add_f32_e32 v86, v88, v85
	s_waitcnt vmcnt(6)
	v_pk_add_f32 v[82:83], v[82:83], v[194:195]
	v_pk_add_f32 v[80:81], v[80:81], v[192:193]
	global_store_dwordx4 v[102:103], v[80:83], off offset:576
	v_cvt_pk_bf16_f32 v84, v80, v81
	v_cvt_pk_bf16_f32 v85, v82, v83
	v_mul_f32_e32 v81, v81, v81
	v_fmac_f32_e32 v81, v80, v80
	v_fmac_f32_e32 v81, v82, v82
	v_fmac_f32_e32 v81, v83, v83
	v_add_f32_e32 v80, v86, v81
	v_mov_b32_e32 v81, v80
	s_nop 1
	v_permlane16_swap_b32_e32 v80, v81
	v_add_f32_e32 v80, v80, v81
	v_mov_b32_e32 v81, v80
	s_nop 1
	v_permlane32_swap_b32_e32 v80, v81
	global_store_dwordx2 v[104:105], v[84:85], off offset:288
	s_and_saveexec_b64 s[24:25], s[6:7]
	s_cbranch_execz .LBB0_1384
	v_lshl_add_u64 v[82:83], v[96:97], 2, s[10:11]
	v_add_f32_e32 v80, v80, v81
	global_atomic_add_f32 v[82:83], v80, off
; DI unsigned pk2(float a, float b) { f32x2 v = {a, b}; hbf2 r = __builtin_convertvector(v, hbf2); return __builtin_bit_cast(unsigned, r); }
; DI float sum_x16_x32(float x) { return sum_x32(sum_x16(x)); }
;     DI void operator()(const f32x4 (&acc)[2][2][4][2], const Unit& u, int wr, int wc, int fr, int fq) const {
;         const int row0 = u.pm * 256 + wr * 64 + fr, col0 = u.pn * 256 + wc * 32 + 4 * fq;
; #pragma unroll
;         for (int ai = 0; ai < 2; ++ai)
; #pragma unroll
;             for (int m = 0; m < 4; ++m) {
;                 const int r = row0 + ai * 128 + m * 16;
;                 const float* rp;
;                 if (MODE == 0) rp = x + (size_t)r * 1024;
;                 else rp = h + (size_t)r * 1024;
;                 float sq = 0.f;
; #pragma unroll
;                 for (int bj = 0; bj < 2; ++bj)
; #pragma unroll
;                     for (int n = 0; n < 2; ++n) {
;                         const int c = col0 + bj * 128 + n * 16;
;                         f32x4 rv = rp ? *(const f32x4*)(rp + c) : (f32x4){0.f, 0.f, 0.f, 0.f};
;                         f32x4 v = acc[ai][bj][m][n] + rv;
;                         *(f32x4*)(h + (size_t)r * 1024 + c) = v;
;                         if (WRITE_HB) {
;                             u32x2 w; w.x = pk2(v[0], v[1]); w.y = pk2(v[2], v[3]);
;                             *(u32x2*)(hb + (size_t)r * 1024 + c) = w;
;                         }
;                         sq += v[0] * v[0] + v[1] * v[1] + v[2] * v[2] + v[3] * v[3];
;                     }
;                 sq = sum_x16_x32(sq);
;                 if (fq == 0) atomicAdd(ss + r, sq);
.LBB0_1384:
	s_or_b64 exec, exec, s[24:25]
	v_or_b32_e32 v80, 48, v142
	v_ashrrev_i32_e32 v81, 31, v80
	v_lshlrev_b64 v[82:83], 12, v[80:81]
	v_lshl_add_u64 v[82:83], s[66:67], 0, v[82:83]
	v_lshl_add_u64 v[86:87], v[140:141], 2, v[82:83]
	global_load_dwordx4 v[180:183], v[86:87], off
	global_load_dwordx4 v[184:187], v[86:87], off offset:64
	global_load_dwordx4 v[188:191], v[86:87], off offset:512
	global_load_dwordx4 v[192:195], v[86:87], off offset:576
	v_lshlrev_b64 v[88:89], 11, v[80:81]
	v_lshl_add_u64 v[88:89], s[68:69], 0, v[88:89]
	v_lshl_add_u64 v[88:89], v[140:141], 1, v[88:89]
	s_waitcnt vmcnt(3)
	v_pk_add_f32 v[78:79], v[78:79], v[182:183]
	v_pk_add_f32 v[76:77], v[76:77], v[180:181]
	v_cvt_pk_bf16_f32 v83, v78, v79
	v_cvt_pk_bf16_f32 v82, v76, v77
	global_store_dwordx4 v[86:87], v[76:79], off
	global_store_dwordx2 v[88:89], v[82:83], off
	s_nop 0
	v_mul_f32_e32 v77, v77, v77
	v_fmac_f32_e32 v77, v76, v76
	v_fmac_f32_e32 v77, v78, v78
	v_fmac_f32_e32 v77, v79, v79
	s_waitcnt vmcnt(4)
	v_pk_add_f32 v[74:75], v[74:75], v[186:187]
	v_pk_add_f32 v[72:73], v[72:73], v[184:185]
	v_cvt_pk_bf16_f32 v83, v74, v75
	v_cvt_pk_bf16_f32 v82, v72, v73
	global_store_dwordx4 v[86:87], v[72:75], off offset:64
	global_store_dwordx2 v[88:89], v[82:83], off offset:32
	s_nop 0
	v_mul_f32_e32 v73, v73, v73
	v_fmac_f32_e32 v73, v72, v72
	v_fmac_f32_e32 v73, v74, v74
	v_fmac_f32_e32 v73, v75, v75
	v_add_f32_e32 v72, v77, v73
	s_waitcnt vmcnt(5)
	v_pk_add_f32 v[70:71], v[70:71], v[190:191]
	v_pk_add_f32 v[68:69], v[68:69], v[188:189]
	v_cvt_pk_bf16_f32 v83, v70, v71
	v_cvt_pk_bf16_f32 v82, v68, v69
	global_store_dwordx4 v[86:87], v[68:71], off offset:512
	global_store_dwordx2 v[88:89], v[82:83], off offset:256
	s_nop 0
	v_mul_f32_e32 v69, v69, v69
	v_fmac_f32_e32 v69, v68, v68
	v_fmac_f32_e32 v69, v70, v70
	v_fmac_f32_e32 v69, v71, v71
	v_add_f32_e32 v70, v72, v69
	s_waitcnt vmcnt(6)
	v_pk_add_f32 v[66:67], v[66:67], v[194:195]
	v_pk_add_f32 v[64:65], v[64:65], v[192:193]
	global_store_dwordx4 v[86:87], v[64:67], off offset:576
	v_cvt_pk_bf16_f32 v68, v64, v65
	v_cvt_pk_bf16_f32 v69, v66, v67
	v_mul_f32_e32 v65, v65, v65
	v_fmac_f32_e32 v65, v64, v64
	v_fmac_f32_e32 v65, v66, v66
	v_fmac_f32_e32 v65, v67, v67
	v_add_f32_e32 v64, v70, v65
	v_mov_b32_e32 v65, v64
	s_nop 1
	v_permlane16_swap_b32_e32 v64, v65
	v_add_f32_e32 v64, v64, v65
	v_mov_b32_e32 v65, v64
	s_nop 1
	v_permlane32_swap_b32_e32 v64, v65
	global_store_dwordx2 v[88:89], v[68:69], off offset:288
	s_and_saveexec_b64 s[24:25], s[6:7]
	s_cbranch_execz .LBB0_1386
	v_lshl_add_u64 v[66:67], v[80:81], 2, s[10:11]
	v_add_f32_e32 v64, v64, v65
	global_atomic_add_f32 v[66:67], v64, off
.LBB0_1386:
	s_or_b64 exec, exec, s[24:25]
	v_add_u32_e32 v64, 0x80, v142
	v_ashrrev_i32_e32 v65, 31, v64
	v_lshlrev_b64 v[66:67], 12, v[64:65]
	v_lshl_add_u64 v[66:67], s[66:67], 0, v[66:67]
	v_lshl_add_u64 v[70:71], v[140:141], 2, v[66:67]
	global_load_dwordx4 v[180:183], v[70:71], off
	global_load_dwordx4 v[184:187], v[70:71], off offset:64
	global_load_dwordx4 v[188:191], v[70:71], off offset:512
	global_load_dwordx4 v[192:195], v[70:71], off offset:576
	v_lshlrev_b64 v[72:73], 11, v[64:65]
	v_lshl_add_u64 v[72:73], s[68:69], 0, v[72:73]
	v_lshl_add_u64 v[72:73], v[140:141], 1, v[72:73]
	s_waitcnt vmcnt(3)
	v_pk_add_f32 v[62:63], v[62:63], v[182:183]
	v_pk_add_f32 v[60:61], v[60:61], v[180:181]
	v_cvt_pk_bf16_f32 v67, v62, v63
	v_cvt_pk_bf16_f32 v66, v60, v61
	global_store_dwordx4 v[70:71], v[60:63], off
	global_store_dwordx2 v[72:73], v[66:67], off
	s_nop 0
	v_mul_f32_e32 v61, v61, v61
	v_fmac_f32_e32 v61, v60, v60
	v_fmac_f32_e32 v61, v62, v62
	v_fmac_f32_e32 v61, v63, v63
	s_waitcnt vmcnt(4)
	v_pk_add_f32 v[58:59], v[58:59], v[186:187]
	v_pk_add_f32 v[56:57], v[56:57], v[184:185]
	v_cvt_pk_bf16_f32 v67, v58, v59
	v_cvt_pk_bf16_f32 v66, v56, v57
	global_store_dwordx4 v[70:71], v[56:59], off offset:64
	global_store_dwordx2 v[72:73], v[66:67], off offset:32
	s_nop 0
	v_mul_f32_e32 v57, v57, v57
	v_fmac_f32_e32 v57, v56, v56
	v_fmac_f32_e32 v57, v58, v58
	v_fmac_f32_e32 v57, v59, v59
	v_add_f32_e32 v56, v61, v57
	s_waitcnt vmcnt(5)
	v_pk_add_f32 v[54:55], v[54:55], v[190:191]
	v_pk_add_f32 v[52:53], v[52:53], v[188:189]
	v_cvt_pk_bf16_f32 v67, v54, v55
	v_cvt_pk_bf16_f32 v66, v52, v53
	global_store_dwordx4 v[70:71], v[52:55], off offset:512
	global_store_dwordx2 v[72:73], v[66:67], off offset:256
	s_nop 0
	v_mul_f32_e32 v53, v53, v53
	v_fmac_f32_e32 v53, v52, v52
	v_fmac_f32_e32 v53, v54, v54
	v_fmac_f32_e32 v53, v55, v55
	v_add_f32_e32 v54, v56, v53
	s_waitcnt vmcnt(6)
	v_pk_add_f32 v[50:51], v[50:51], v[194:195]
	v_pk_add_f32 v[48:49], v[48:49], v[192:193]
	global_store_dwordx4 v[70:71], v[48:51], off offset:576
	v_cvt_pk_bf16_f32 v52, v48, v49
	v_cvt_pk_bf16_f32 v53, v50, v51
	v_mul_f32_e32 v49, v49, v49
	v_fmac_f32_e32 v49, v48, v48
	v_fmac_f32_e32 v49, v50, v50
	v_fmac_f32_e32 v49, v51, v51
	v_add_f32_e32 v48, v54, v49
	v_mov_b32_e32 v49, v48
	s_nop 1
	v_permlane16_swap_b32_e32 v48, v49
	v_add_f32_e32 v48, v48, v49
	v_mov_b32_e32 v49, v48
	s_nop 1
	v_permlane32_swap_b32_e32 v48, v49
	global_store_dwordx2 v[72:73], v[52:53], off offset:288
	s_and_saveexec_b64 s[24:25], s[6:7]
	s_cbranch_execz .LBB0_1388
	v_lshl_add_u64 v[50:51], v[64:65], 2, s[10:11]
	v_add_f32_e32 v48, v48, v49
	global_atomic_add_f32 v[50:51], v48, off
; DI unsigned pk2(float a, float b) { f32x2 v = {a, b}; hbf2 r = __builtin_convertvector(v, hbf2); return __builtin_bit_cast(unsigned, r); }
; DI float sum_x16_x32(float x) { return sum_x32(sum_x16(x)); }
;     DI void operator()(const f32x4 (&acc)[2][2][4][2], const Unit& u, int wr, int wc, int fr, int fq) const {
;         const int row0 = u.pm * 256 + wr * 64 + fr, col0 = u.pn * 256 + wc * 32 + 4 * fq;
; #pragma unroll
;         for (int ai = 0; ai < 2; ++ai)
; #pragma unroll
;             for (int m = 0; m < 4; ++m) {
;                 const int r = row0 + ai * 128 + m * 16;
;                 const float* rp;
;                 if (MODE == 0) rp = x + (size_t)r * 1024;
;                 else rp = h + (size_t)r * 1024;
;                 float sq = 0.f;
; #pragma unroll
;                 for (int bj = 0; bj < 2; ++bj)
; #pragma unroll
;                     for (int n = 0; n < 2; ++n) {
;                         const int c = col0 + bj * 128 + n * 16;
;                         f32x4 rv = rp ? *(const f32x4*)(rp + c) : (f32x4){0.f, 0.f, 0.f, 0.f};
;                         f32x4 v = acc[ai][bj][m][n] + rv;
;                         *(f32x4*)(h + (size_t)r * 1024 + c) = v;
;                         if (WRITE_HB) {
;                             u32x2 w; w.x = pk2(v[0], v[1]); w.y = pk2(v[2], v[3]);
;                             *(u32x2*)(hb + (size_t)r * 1024 + c) = w;
;                         }
;                         sq += v[0] * v[0] + v[1] * v[1] + v[2] * v[2] + v[3] * v[3];
;                     }
;                 sq = sum_x16_x32(sq);
;                 if (fq == 0) atomicAdd(ss + r, sq);
.LBB0_1388:
	s_or_b64 exec, exec, s[24:25]
	v_add_u32_e32 v48, 0x90, v142
	v_ashrrev_i32_e32 v49, 31, v48
	v_lshlrev_b64 v[50:51], 12, v[48:49]
	v_lshl_add_u64 v[50:51], s[66:67], 0, v[50:51]
	v_lshl_add_u64 v[54:55], v[140:141], 2, v[50:51]
	global_load_dwordx4 v[180:183], v[54:55], off
	global_load_dwordx4 v[184:187], v[54:55], off offset:64
	global_load_dwordx4 v[188:191], v[54:55], off offset:512
	global_load_dwordx4 v[192:195], v[54:55], off offset:576
	v_lshlrev_b64 v[56:57], 11, v[48:49]
	v_lshl_add_u64 v[56:57], s[68:69], 0, v[56:57]
	v_lshl_add_u64 v[56:57], v[140:141], 1, v[56:57]
	s_waitcnt vmcnt(3)
	v_pk_add_f32 v[46:47], v[46:47], v[182:183]
	v_pk_add_f32 v[44:45], v[44:45], v[180:181]
	v_cvt_pk_bf16_f32 v51, v46, v47
	v_cvt_pk_bf16_f32 v50, v44, v45
	global_store_dwordx4 v[54:55], v[44:47], off
	global_store_dwordx2 v[56:57], v[50:51], off
	s_nop 0
	v_mul_f32_e32 v45, v45, v45
	v_fmac_f32_e32 v45, v44, v44
	v_fmac_f32_e32 v45, v46, v46
	v_fmac_f32_e32 v45, v47, v47
	s_waitcnt vmcnt(4)
	v_pk_add_f32 v[42:43], v[42:43], v[186:187]
	v_pk_add_f32 v[40:41], v[40:41], v[184:185]
	v_cvt_pk_bf16_f32 v51, v42, v43
	v_cvt_pk_bf16_f32 v50, v40, v41
	global_store_dwordx4 v[54:55], v[40:43], off offset:64
	global_store_dwordx2 v[56:57], v[50:51], off offset:32
	s_nop 0
	v_mul_f32_e32 v41, v41, v41
	v_fmac_f32_e32 v41, v40, v40
	v_fmac_f32_e32 v41, v42, v42
	v_fmac_f32_e32 v41, v43, v43
	v_add_f32_e32 v40, v45, v41
	s_waitcnt vmcnt(5)
	v_pk_add_f32 v[38:39], v[38:39], v[190:191]
	v_pk_add_f32 v[36:37], v[36:37], v[188:189]
	v_cvt_pk_bf16_f32 v51, v38, v39
	v_cvt_pk_bf16_f32 v50, v36, v37
	global_store_dwordx4 v[54:55], v[36:39], off offset:512
	global_store_dwordx2 v[56:57], v[50:51], off offset:256
	s_nop 0
	v_mul_f32_e32 v37, v37, v37
	v_fmac_f32_e32 v37, v36, v36
	v_fmac_f32_e32 v37, v38, v38
	v_fmac_f32_e32 v37, v39, v39
	v_add_f32_e32 v38, v40, v37
	s_waitcnt vmcnt(6)
	v_pk_add_f32 v[34:35], v[34:35], v[194:195]
	v_pk_add_f32 v[32:33], v[32:33], v[192:193]
	global_store_dwordx4 v[54:55], v[32:35], off offset:576
	v_cvt_pk_bf16_f32 v36, v32, v33
	v_cvt_pk_bf16_f32 v37, v34, v35
	v_mul_f32_e32 v33, v33, v33
	v_fmac_f32_e32 v33, v32, v32
	v_fmac_f32_e32 v33, v34, v34
	v_fmac_f32_e32 v33, v35, v35
	v_add_f32_e32 v32, v38, v33
	v_mov_b32_e32 v33, v32
	s_nop 1
	v_permlane16_swap_b32_e32 v32, v33
	v_add_f32_e32 v32, v32, v33
	v_mov_b32_e32 v33, v32
	s_nop 1
	v_permlane32_swap_b32_e32 v32, v33
	global_store_dwordx2 v[56:57], v[36:37], off offset:288
	s_and_saveexec_b64 s[24:25], s[6:7]
	s_cbranch_execz .LBB0_1390
	v_lshl_add_u64 v[34:35], v[48:49], 2, s[10:11]
	v_add_f32_e32 v32, v32, v33
	global_atomic_add_f32 v[34:35], v32, off
; DI unsigned pk2(float a, float b) { f32x2 v = {a, b}; hbf2 r = __builtin_convertvector(v, hbf2); return __builtin_bit_cast(unsigned, r); }
; DI float sum_x16_x32(float x) { return sum_x32(sum_x16(x)); }
;     DI void operator()(const f32x4 (&acc)[2][2][4][2], const Unit& u, int wr, int wc, int fr, int fq) const {
;         const int row0 = u.pm * 256 + wr * 64 + fr, col0 = u.pn * 256 + wc * 32 + 4 * fq;
; #pragma unroll
;         for (int ai = 0; ai < 2; ++ai)
; #pragma unroll
;             for (int m = 0; m < 4; ++m) {
;                 const int r = row0 + ai * 128 + m * 16;
;                 const float* rp;
;                 if (MODE == 0) rp = x + (size_t)r * 1024;
;                 else rp = h + (size_t)r * 1024;
;                 float sq = 0.f;
; #pragma unroll
;                 for (int bj = 0; bj < 2; ++bj)
; #pragma unroll
;                     for (int n = 0; n < 2; ++n) {
;                         const int c = col0 + bj * 128 + n * 16;
;                         f32x4 rv = rp ? *(const f32x4*)(rp + c) : (f32x4){0.f, 0.f, 0.f, 0.f};
;                         f32x4 v = acc[ai][bj][m][n] + rv;
;                         *(f32x4*)(h + (size_t)r * 1024 + c) = v;
;                         if (WRITE_HB) {
;                             u32x2 w; w.x = pk2(v[0], v[1]); w.y = pk2(v[2], v[3]);
;                             *(u32x2*)(hb + (size_t)r * 1024 + c) = w;
;                         }
;                         sq += v[0] * v[0] + v[1] * v[1] + v[2] * v[2] + v[3] * v[3];
;                     }
;                 sq = sum_x16_x32(sq);
;                 if (fq == 0) atomicAdd(ss + r, sq);
.LBB0_1390:
	s_or_b64 exec, exec, s[24:25]
	v_add_u32_e32 v32, 0xa0, v142
	v_ashrrev_i32_e32 v33, 31, v32
	v_lshlrev_b64 v[34:35], 12, v[32:33]
	v_lshl_add_u64 v[34:35], s[66:67], 0, v[34:35]
	v_lshl_add_u64 v[38:39], v[140:141], 2, v[34:35]
	global_load_dwordx4 v[180:183], v[38:39], off
	global_load_dwordx4 v[184:187], v[38:39], off offset:64
	global_load_dwordx4 v[188:191], v[38:39], off offset:512
	global_load_dwordx4 v[192:195], v[38:39], off offset:576
	v_lshlrev_b64 v[40:41], 11, v[32:33]
	v_lshl_add_u64 v[40:41], s[68:69], 0, v[40:41]
	v_lshl_add_u64 v[40:41], v[140:141], 1, v[40:41]
	s_waitcnt vmcnt(3)
	v_pk_add_f32 v[30:31], v[30:31], v[182:183]
	v_pk_add_f32 v[28:29], v[28:29], v[180:181]
	v_cvt_pk_bf16_f32 v35, v30, v31
	v_cvt_pk_bf16_f32 v34, v28, v29
	global_store_dwordx4 v[38:39], v[28:31], off
	global_store_dwordx2 v[40:41], v[34:35], off
	s_nop 0
	v_mul_f32_e32 v29, v29, v29
	v_fmac_f32_e32 v29, v28, v28
	v_fmac_f32_e32 v29, v30, v30
	v_fmac_f32_e32 v29, v31, v31
	s_waitcnt vmcnt(4)
	v_pk_add_f32 v[26:27], v[26:27], v[186:187]
	v_pk_add_f32 v[24:25], v[24:25], v[184:185]
	v_cvt_pk_bf16_f32 v35, v26, v27
	v_cvt_pk_bf16_f32 v34, v24, v25
	global_store_dwordx4 v[38:39], v[24:27], off offset:64
	global_store_dwordx2 v[40:41], v[34:35], off offset:32
	s_nop 0
	v_mul_f32_e32 v25, v25, v25
	v_fmac_f32_e32 v25, v24, v24
	v_fmac_f32_e32 v25, v26, v26
	v_fmac_f32_e32 v25, v27, v27
	v_add_f32_e32 v24, v29, v25
	s_waitcnt vmcnt(5)
	v_pk_add_f32 v[22:23], v[22:23], v[190:191]
	v_pk_add_f32 v[20:21], v[20:21], v[188:189]
	v_cvt_pk_bf16_f32 v35, v22, v23
	v_cvt_pk_bf16_f32 v34, v20, v21
	global_store_dwordx4 v[38:39], v[20:23], off offset:512
	global_store_dwordx2 v[40:41], v[34:35], off offset:256
	s_nop 0
	v_mul_f32_e32 v21, v21, v21
	v_fmac_f32_e32 v21, v20, v20
	v_fmac_f32_e32 v21, v22, v22
	v_fmac_f32_e32 v21, v23, v23
	v_add_f32_e32 v22, v24, v21
	s_waitcnt vmcnt(6)
	v_pk_add_f32 v[18:19], v[18:19], v[194:195]
	v_pk_add_f32 v[16:17], v[16:17], v[192:193]
	global_store_dwordx4 v[38:39], v[16:19], off offset:576
	v_cvt_pk_bf16_f32 v20, v16, v17
	v_cvt_pk_bf16_f32 v21, v18, v19
	v_mul_f32_e32 v17, v17, v17
	v_fmac_f32_e32 v17, v16, v16
	v_fmac_f32_e32 v17, v18, v18
	v_fmac_f32_e32 v17, v19, v19
	v_add_f32_e32 v16, v22, v17
	v_mov_b32_e32 v17, v16
	s_nop 1
	v_permlane16_swap_b32_e32 v16, v17
	v_add_f32_e32 v16, v16, v17
	v_mov_b32_e32 v17, v16
	s_nop 1
	v_permlane32_swap_b32_e32 v16, v17
	global_store_dwordx2 v[40:41], v[20:21], off offset:288
	s_and_saveexec_b64 s[24:25], s[6:7]
	s_cbranch_execz .LBB0_1392
	v_lshl_add_u64 v[18:19], v[32:33], 2, s[10:11]
	v_add_f32_e32 v16, v16, v17
	global_atomic_add_f32 v[18:19], v16, off
.LBB0_1392:
	s_or_b64 exec, exec, s[24:25]
	v_add_u32_e32 v16, 0xb0, v142
	v_ashrrev_i32_e32 v17, 31, v16
	v_lshlrev_b64 v[18:19], 12, v[16:17]
	v_lshl_add_u64 v[18:19], s[66:67], 0, v[18:19]
	v_lshl_add_u64 v[22:23], v[140:141], 2, v[18:19]
	global_load_dwordx4 v[180:183], v[22:23], off
	global_load_dwordx4 v[184:187], v[22:23], off offset:64
	global_load_dwordx4 v[188:191], v[22:23], off offset:512
	global_load_dwordx4 v[192:195], v[22:23], off offset:576
	v_lshlrev_b64 v[24:25], 11, v[16:17]
	v_lshl_add_u64 v[24:25], s[68:69], 0, v[24:25]
	v_lshl_add_u64 v[24:25], v[140:141], 1, v[24:25]
	s_waitcnt vmcnt(3)
	v_pk_add_f32 v[14:15], v[14:15], v[182:183]
	v_pk_add_f32 v[12:13], v[12:13], v[180:181]
	v_cvt_pk_bf16_f32 v19, v14, v15
	v_cvt_pk_bf16_f32 v18, v12, v13
	global_store_dwordx4 v[22:23], v[12:15], off
	global_store_dwordx2 v[24:25], v[18:19], off
	s_nop 0
	v_mul_f32_e32 v13, v13, v13
	v_fmac_f32_e32 v13, v12, v12
	v_fmac_f32_e32 v13, v14, v14
	v_fmac_f32_e32 v13, v15, v15
	s_waitcnt vmcnt(4)
	v_pk_add_f32 v[10:11], v[10:11], v[186:187]
	v_pk_add_f32 v[8:9], v[8:9], v[184:185]
	v_cvt_pk_bf16_f32 v19, v10, v11
	v_cvt_pk_bf16_f32 v18, v8, v9
	global_store_dwordx4 v[22:23], v[8:11], off offset:64
	global_store_dwordx2 v[24:25], v[18:19], off offset:32
	s_nop 0
	v_mul_f32_e32 v9, v9, v9
	v_fmac_f32_e32 v9, v8, v8
	v_fmac_f32_e32 v9, v10, v10
	v_fmac_f32_e32 v9, v11, v11
	v_add_f32_e32 v8, v13, v9
	s_waitcnt vmcnt(5)
	v_pk_add_f32 v[6:7], v[6:7], v[190:191]
	v_pk_add_f32 v[4:5], v[4:5], v[188:189]
	v_cvt_pk_bf16_f32 v19, v6, v7
	v_cvt_pk_bf16_f32 v18, v4, v5
	global_store_dwordx4 v[22:23], v[4:7], off offset:512
	global_store_dwordx2 v[24:25], v[18:19], off offset:256
	s_nop 0
	v_mul_f32_e32 v5, v5, v5
	v_fmac_f32_e32 v5, v4, v4
	v_fmac_f32_e32 v5, v6, v6
	v_fmac_f32_e32 v5, v7, v7
	v_add_f32_e32 v6, v8, v5
	s_waitcnt vmcnt(6)
	v_pk_add_f32 v[2:3], v[2:3], v[194:195]
	v_pk_add_f32 v[0:1], v[0:1], v[192:193]
	global_store_dwordx4 v[22:23], v[0:3], off offset:576
	v_cvt_pk_bf16_f32 v4, v0, v1
	v_cvt_pk_bf16_f32 v5, v2, v3
	v_mul_f32_e32 v1, v1, v1
	v_fmac_f32_e32 v1, v0, v0
	v_fmac_f32_e32 v1, v2, v2
	v_fmac_f32_e32 v1, v3, v3
	v_add_f32_e32 v0, v6, v1
	v_mov_b32_e32 v1, v0
	s_nop 1
	v_permlane16_swap_b32_e32 v0, v1
	v_add_f32_e32 v0, v0, v1
	v_mov_b32_e32 v1, v0
	s_nop 1
	v_permlane32_swap_b32_e32 v0, v1
	global_store_dwordx2 v[24:25], v[4:5], off offset:288
	s_and_saveexec_b64 s[24:25], s[6:7]
	s_cbranch_execz .LBB0_1369
	v_lshl_add_u64 v[2:3], v[16:17], 2, s[10:11]
	v_add_f32_e32 v0, v0, v1
	global_atomic_add_f32 v[2:3], v0, off
	s_branch .LBB0_1369

; #define PG8_STAGE(bufoff, gbase, voff) do { _Pragma("unroll") for (int _i = 0; _i < 2; ++_i) \
;         __builtin_amdgcn_global_load_lds((const unsigned*)((const char*)(gbase) + (voff)[_i]), (LAS unsigned*)(lds + (bufoff) + ldsw + _i * 8192), 16, 0, 0); } while (0)
; #define PG8_LDA(dst, b, h) do { _Pragma("unroll") for (int m = 0; m < 4; ++m) _Pragma("unroll") for (int k = 0; k < 2; ++k) dst[m][k] = *(const LAS bf16x8*)(lds + PG8_SA(b, h) + aoff + m * 2048 + k * 1024); } while (0)
; #define PG8_WAIT_V(n) asm volatile("s_waitcnt vmcnt(" #n ")" ::: "memory")
; #define PG8_WAIT_L(n) asm volatile("s_waitcnt lgkmcnt(" #n ")" ::: "memory")
; template <class Epi>
; __device__ __forceinline__ void gemm_phase(LAS unsigned char* lds, const Gemm g, const StaticOrder& S, const Epi& E) {
;     ...
;         for (int t = 0; t < nt; t += 2) {
;             const bool last = (t == nt - 2);
;             const char* a1 = cA + (size_t)(t + 1) * kstep;
;             const char* a2 = last ? nA : cA + (size_t)(t + 2) * kstep; const char* b2 = last ? nB : cB + (size_t)(t + 2) * kstep;
;             const char* a3 = a2 + kstep; const char* b3 = b2 + kstep;
;             PG8_LDB(B0, 0, 0); PG8_SCHED; PG8_LDA(At, 0, 0); PG8_STAGE(PG8_SA(1, 1), a1 + hstep, voffA);
;             PG8_WAIT_L(8); PG8_BAR; PG8_WAIT_L(0); PG8_MMA(0, 0, At, B0); PG8_BAR; PG8_SCHED;
;             PG8_LDB(B1, 0, 1); PG8_STAGE(PG8_SB(0, 0), b2, voffB);
;             PG8_BAR; PG8_WAIT_L(0); PG8_MMA(0, 1, At, B1); PG8_BAR;
;             PG8_LDA(At, 0, 1); PG8_STAGE(PG8_SA(0, 0), a2, voffA);
;             PG8_BAR; PG8_WAIT_L(0); PG8_MMA(1, 0, At, B0); PG8_BAR; PG8_SCHED;
;             PG8_STAGE(PG8_SB(0, 1), b2 + hstep, voffB);
;             PG8_WAIT_V(6); PG8_BAR; PG8_MMA(1, 1, At, B1); PG8_BAR;
;             PG8_LDB(B0, 1, 0); PG8_SCHED; PG8_LDA(At, 1, 0); PG8_STAGE(PG8_SA(0, 1), a2 + hstep, voffA);
;             PG8_WAIT_L(8); PG8_BAR; PG8_WAIT_L(0); PG8_MMA(0, 0, At, B0); PG8_BAR; PG8_SCHED;
;             PG8_LDB(B1, 1, 1); PG8_STAGE(PG8_SB(1, 0), b3, voffB);
;             PG8_BAR; PG8_WAIT_L(0); PG8_MMA(0, 1, At, B1); PG8_BAR;
;             PG8_LDA(At, 1, 1); PG8_STAGE(PG8_SA(1, 0), a3, voffA);
;             PG8_BAR; PG8_WAIT_L(0); PG8_MMA(1, 0, At, B0); PG8_BAR; PG8_SCHED;
;             PG8_STAGE(PG8_SB(1, 1), b3 + hstep, voffB);
;             PG8_WAIT_V(6); PG8_BAR; PG8_MMA(1, 1, At, B1); PG8_BAR;
.LBB0_1464:
	ds_read_b128 v[144:147], v155
	ds_read_b128 v[148:151], v155 offset:1024
	ds_read_b128 v[160:163], v155 offset:2048
	ds_read_b128 v[164:167], v155 offset:3072
	s_add_u32 s30, s0, 0xfffc0080
	s_addc_u32 s31, s1, -1
	s_cmp_eq_u32 s70, 12
	s_cselect_b32 s37, s23, s31
	s_cselect_b32 s36, s60, s30
	s_cselect_b32 s31, s21, s63
	s_cselect_b32 s30, s61, s62
	v_lshl_add_u64 v[176:177], s[0:1], 0, v[136:137]
	s_add_i32 m0, s29, 0xc000
	ds_read_b128 v[168:171], v156
	ds_read_b128 v[172:175], v156 offset:1024
	ds_read_b128 v[180:183], v156 offset:2048
	ds_read_b128 v[184:187], v156 offset:3072
	ds_read_b128 v[188:191], v156 offset:4096
	ds_read_b128 v[192:195], v156 offset:5120
	ds_read_b128 v[196:199], v156 offset:6144
	ds_read_b128 v[200:203], v156 offset:7168
	global_load_lds_dwordx4 v[176:177], off
	v_lshl_add_u64 v[176:177], s[0:1], 0, v[138:139]
	s_add_i32 m0, s29, 0xe000
	s_nop 0
	global_load_lds_dwordx4 v[176:177], off
	s_waitcnt lgkmcnt(8)
	s_barrier
	s_waitcnt lgkmcnt(0)
	s_setprio 1
	s_waitcnt lgkmcnt(0)
	v_mfma_f32_16x16x32_bf16 v[124:127], v[144:147], v[168:171], v[124:127]
	v_mfma_f32_16x16x32_bf16 v[120:123], v[160:163], v[168:171], v[120:123]
	v_mfma_f32_16x16x32_bf16 v[108:111], v[144:147], v[180:183], v[108:111]
	v_mfma_f32_16x16x32_bf16 v[104:107], v[160:163], v[180:183], v[104:107]
	v_mfma_f32_16x16x32_bf16 v[92:95], v[144:147], v[188:191], v[92:95]
	v_mfma_f32_16x16x32_bf16 v[88:91], v[160:163], v[188:191], v[88:91]
	v_mfma_f32_16x16x32_bf16 v[76:79], v[144:147], v[196:199], v[76:79]
	v_mfma_f32_16x16x32_bf16 v[72:75], v[160:163], v[196:199], v[72:75]
	v_mfma_f32_16x16x32_bf16 v[124:127], v[148:151], v[172:175], v[124:127]
	v_mfma_f32_16x16x32_bf16 v[120:123], v[164:167], v[172:175], v[120:123]
	v_mfma_f32_16x16x32_bf16 v[108:111], v[148:151], v[184:187], v[108:111]
	v_mfma_f32_16x16x32_bf16 v[104:107], v[164:167], v[184:187], v[104:107]
	v_mfma_f32_16x16x32_bf16 v[92:95], v[148:151], v[192:195], v[92:95]
	v_mfma_f32_16x16x32_bf16 v[88:91], v[164:167], v[192:195], v[88:91]
	v_mfma_f32_16x16x32_bf16 v[76:79], v[148:151], v[200:203], v[76:79]
	v_mfma_f32_16x16x32_bf16 v[72:75], v[164:167], v[200:203], v[72:75]
	s_setprio 0
	s_barrier
	s_add_i32 s71, s48, s39
	v_lshl_add_u64 v[176:177], s[30:31], 0, v[130:131]
	s_mov_b32 m0, s71
	ds_read_b128 v[204:207], v157
	ds_read_b128 v[208:211], v157 offset:1024
	ds_read_b128 v[212:215], v157 offset:2048
	ds_read_b128 v[216:219], v157 offset:3072
	global_load_lds_dwordx4 v[176:177], off
	v_lshl_add_u64 v[220:221], s[30:31], 0, v[134:135]
	s_add_i32 m0, s71, 0x2000
	s_nop 0
	global_load_lds_dwordx4 v[220:221], off
	s_barrier
	s_waitcnt lgkmcnt(0)
	s_setprio 1
	s_waitcnt lgkmcnt(0)
	v_mfma_f32_16x16x32_bf16 v[116:119], v[204:207], v[168:171], v[116:119]
	v_mfma_f32_16x16x32_bf16 v[112:115], v[212:215], v[168:171], v[112:115]
	v_mfma_f32_16x16x32_bf16 v[100:103], v[204:207], v[180:183], v[100:103]
	v_mfma_f32_16x16x32_bf16 v[96:99], v[212:215], v[180:183], v[96:99]
	v_mfma_f32_16x16x32_bf16 v[84:87], v[204:207], v[188:191], v[84:87]
	v_mfma_f32_16x16x32_bf16 v[80:83], v[212:215], v[188:191], v[80:83]
	v_mfma_f32_16x16x32_bf16 v[68:71], v[204:207], v[196:199], v[68:71]
	v_mfma_f32_16x16x32_bf16 v[64:67], v[212:215], v[196:199], v[64:67]
	v_mfma_f32_16x16x32_bf16 v[116:119], v[208:211], v[172:175], v[116:119]
	v_mfma_f32_16x16x32_bf16 v[112:115], v[216:219], v[172:175], v[112:115]
	v_mfma_f32_16x16x32_bf16 v[100:103], v[208:211], v[184:187], v[100:103]
	v_mfma_f32_16x16x32_bf16 v[96:99], v[216:219], v[184:187], v[96:99]
	v_mfma_f32_16x16x32_bf16 v[84:87], v[208:211], v[192:195], v[84:87]
	v_mfma_f32_16x16x32_bf16 v[80:83], v[216:219], v[192:195], v[80:83]
	v_mfma_f32_16x16x32_bf16 v[68:71], v[208:211], v[200:203], v[68:71]
	v_mfma_f32_16x16x32_bf16 v[64:67], v[216:219], v[200:203], v[64:67]
	s_setprio 0
	s_mov_b32 m0, s29
	v_lshl_add_u64 v[222:223], s[36:37], 0, v[128:129]
	s_barrier
	ds_read_b128 v[168:171], v156 offset:16384
	ds_read_b128 v[172:175], v156 offset:17408
	ds_read_b128 v[180:183], v156 offset:18432
	ds_read_b128 v[184:187], v156 offset:19456
	ds_read_b128 v[188:191], v156 offset:20480
	ds_read_b128 v[192:195], v156 offset:21504
	ds_read_b128 v[196:199], v156 offset:22528
	ds_read_b128 v[200:203], v156 offset:23552
	global_load_lds_dwordx4 v[222:223], off
	v_lshl_add_u64 v[224:225], s[36:37], 0, v[132:133]
	s_mov_b32 m0, s40
	s_nop 0
	global_load_lds_dwordx4 v[224:225], off
	s_barrier
	s_waitcnt lgkmcnt(0)
	s_setprio 1
	s_waitcnt lgkmcnt(0)
	v_mfma_f32_16x16x32_bf16 v[60:63], v[144:147], v[168:171], v[60:63]
	v_mfma_f32_16x16x32_bf16 v[56:59], v[160:163], v[168:171], v[56:59]
	v_mfma_f32_16x16x32_bf16 v[44:47], v[144:147], v[180:183], v[44:47]
	v_mfma_f32_16x16x32_bf16 v[40:43], v[160:163], v[180:183], v[40:43]
	v_mfma_f32_16x16x32_bf16 v[28:31], v[144:147], v[188:191], v[28:31]
	v_mfma_f32_16x16x32_bf16 v[24:27], v[160:163], v[188:191], v[24:27]
	v_mfma_f32_16x16x32_bf16 v[12:15], v[144:147], v[196:199], v[12:15]
	v_mfma_f32_16x16x32_bf16 v[8:11], v[160:163], v[196:199], v[8:11]
	v_mfma_f32_16x16x32_bf16 v[60:63], v[148:151], v[172:175], v[60:63]
	v_mfma_f32_16x16x32_bf16 v[56:59], v[164:167], v[172:175], v[56:59]
	v_mfma_f32_16x16x32_bf16 v[44:47], v[148:151], v[184:187], v[44:47]
	v_mfma_f32_16x16x32_bf16 v[40:43], v[164:167], v[184:187], v[40:43]
	v_mfma_f32_16x16x32_bf16 v[28:31], v[148:151], v[192:195], v[28:31]
	v_mfma_f32_16x16x32_bf16 v[24:27], v[164:167], v[192:195], v[24:27]
	v_mfma_f32_16x16x32_bf16 v[12:15], v[148:151], v[200:203], v[12:15]
	v_mfma_f32_16x16x32_bf16 v[8:11], v[164:167], v[200:203], v[8:11]
	s_setprio 0
	s_barrier
; #define PG8_STAGE(bufoff, gbase, voff) do { _Pragma("unroll") for (int _i = 0; _i < 2; ++_i) \
;         __builtin_amdgcn_global_load_lds((const unsigned*)((const char*)(gbase) + (voff)[_i]), (LAS unsigned*)(lds + (bufoff) + ldsw + _i * 8192), 16, 0, 0); } while (0)
; #define PG8_LDA(dst, b, h) do { _Pragma("unroll") for (int m = 0; m < 4; ++m) _Pragma("unroll") for (int k = 0; k < 2; ++k) dst[m][k] = *(const LAS bf16x8*)(lds + PG8_SA(b, h) + aoff + m * 2048 + k * 1024); } while (0)
; #define PG8_WAIT_V(n) asm volatile("s_waitcnt vmcnt(" #n ")" ::: "memory")
; #define PG8_WAIT_L(n) asm volatile("s_waitcnt lgkmcnt(" #n ")" ::: "memory")
; template <class Epi>
; __device__ __forceinline__ void gemm_phase(LAS unsigned char* lds, const Gemm g, const StaticOrder& S, const Epi& E) {
;     ...
;         for (int t = 0; t < nt; t += 2) {
;             const bool last = (t == nt - 2);
;             const char* a1 = cA + (size_t)(t + 1) * kstep;
;             const char* a2 = last ? nA : cA + (size_t)(t + 2) * kstep; const char* b2 = last ? nB : cB + (size_t)(t + 2) * kstep;
;             const char* a3 = a2 + kstep; const char* b3 = b2 + kstep;
;             PG8_LDB(B0, 0, 0); PG8_SCHED; PG8_LDA(At, 0, 0); PG8_STAGE(PG8_SA(1, 1), a1 + hstep, voffA);
;             PG8_WAIT_L(8); PG8_BAR; PG8_WAIT_L(0); PG8_MMA(0, 0, At, B0); PG8_BAR; PG8_SCHED;
;             PG8_LDB(B1, 0, 1); PG8_STAGE(PG8_SB(0, 0), b2, voffB);
;             PG8_BAR; PG8_WAIT_L(0); PG8_MMA(0, 1, At, B1); PG8_BAR;
;             PG8_LDA(At, 0, 1); PG8_STAGE(PG8_SA(0, 0), a2, voffA);
;             PG8_BAR; PG8_WAIT_L(0); PG8_MMA(1, 0, At, B0); PG8_BAR; PG8_SCHED;
;             PG8_STAGE(PG8_SB(0, 1), b2 + hstep, voffB);
;             PG8_WAIT_V(6); PG8_BAR; PG8_MMA(1, 1, At, B1); PG8_BAR;
;             PG8_LDB(B0, 1, 0); PG8_SCHED; PG8_LDA(At, 1, 0); PG8_STAGE(PG8_SA(0, 1), a2 + hstep, voffA);
;             PG8_WAIT_L(8); PG8_BAR; PG8_WAIT_L(0); PG8_MMA(0, 0, At, B0); PG8_BAR; PG8_SCHED;
;             PG8_LDB(B1, 1, 1); PG8_STAGE(PG8_SB(1, 0), b3, voffB);
;             PG8_BAR; PG8_WAIT_L(0); PG8_MMA(0, 1, At, B1); PG8_BAR;
;             PG8_LDA(At, 1, 1); PG8_STAGE(PG8_SA(1, 0), a3, voffA);
;             PG8_BAR; PG8_WAIT_L(0); PG8_MMA(1, 0, At, B0); PG8_BAR; PG8_SCHED;
;             PG8_STAGE(PG8_SB(1, 1), b3 + hstep, voffB);
;             PG8_WAIT_V(6); PG8_BAR; PG8_MMA(1, 1, At, B1); PG8_BAR;
	s_add_u32 s72, s30, 0x40000
	s_addc_u32 s73, s31, 0
	s_add_i32 s71, s49, s39
	v_lshl_add_u64 v[144:145], s[72:73], 0, v[130:131]
	s_mov_b32 m0, s71
	s_nop 0
	global_load_lds_dwordx4 v[144:145], off
	v_lshl_add_u64 v[144:145], s[72:73], 0, v[134:135]
	s_add_i32 m0, s71, 0x2000
	s_nop 0
	global_load_lds_dwordx4 v[144:145], off
	s_waitcnt vmcnt(6)
	s_barrier
	s_setprio 1
	v_mfma_f32_16x16x32_bf16 v[52:55], v[204:207], v[168:171], v[52:55]
	v_mfma_f32_16x16x32_bf16 v[48:51], v[212:215], v[168:171], v[48:51]
	v_mfma_f32_16x16x32_bf16 v[36:39], v[204:207], v[180:183], v[36:39]
	v_mfma_f32_16x16x32_bf16 v[32:35], v[212:215], v[180:183], v[32:35]
	v_mfma_f32_16x16x32_bf16 v[20:23], v[204:207], v[188:191], v[20:23]
	v_mfma_f32_16x16x32_bf16 v[16:19], v[212:215], v[188:191], v[16:19]
	v_mfma_f32_16x16x32_bf16 v[4:7], v[204:207], v[196:199], v[4:7]
	v_mfma_f32_16x16x32_bf16 v[0:3], v[212:215], v[196:199], v[0:3]
	v_mfma_f32_16x16x32_bf16 v[52:55], v[208:211], v[172:175], v[52:55]
	v_mfma_f32_16x16x32_bf16 v[48:51], v[216:219], v[172:175], v[48:51]
	v_mfma_f32_16x16x32_bf16 v[36:39], v[208:211], v[184:187], v[36:39]
	v_mfma_f32_16x16x32_bf16 v[32:35], v[216:219], v[184:187], v[32:35]
	v_mfma_f32_16x16x32_bf16 v[20:23], v[208:211], v[192:195], v[20:23]
	v_mfma_f32_16x16x32_bf16 v[16:19], v[216:219], v[192:195], v[16:19]
	v_mfma_f32_16x16x32_bf16 v[4:7], v[208:211], v[200:203], v[4:7]
	v_mfma_f32_16x16x32_bf16 v[0:3], v[216:219], v[200:203], v[0:3]
	s_setprio 0
	s_add_i32 s71, 0, 0x18000
	v_add_u32_e32 v159, s71, v153
	s_barrier
	ds_read_b128 v[144:147], v159
	ds_read_b128 v[148:151], v159 offset:1024
	ds_read_b128 v[160:163], v159 offset:2048
	ds_read_b128 v[164:167], v159 offset:3072
	s_add_u32 s36, s36, 0x40000
	s_addc_u32 s37, s37, 0
	s_mov_b32 m0, s41
	v_lshl_add_u64 v[204:205], s[36:37], 0, v[128:129]
	ds_read_b128 v[168:171], v156 offset:32768
	ds_read_b128 v[172:175], v156 offset:33792
	ds_read_b128 v[180:183], v156 offset:34816
	ds_read_b128 v[184:187], v156 offset:35840
	ds_read_b128 v[188:191], v156 offset:36864
	ds_read_b128 v[192:195], v156 offset:37888
	ds_read_b128 v[196:199], v156 offset:38912
	ds_read_b128 v[200:203], v156 offset:39936
	global_load_lds_dwordx4 v[204:205], off
	v_lshl_add_u64 v[204:205], s[36:37], 0, v[132:133]
	s_mov_b32 m0, s42
	s_nop 0
	global_load_lds_dwordx4 v[204:205], off
	s_waitcnt lgkmcnt(8)
	s_barrier
	s_waitcnt lgkmcnt(0)
	s_setprio 1
	s_waitcnt lgkmcnt(0)
	v_mfma_f32_16x16x32_bf16 v[124:127], v[144:147], v[168:171], v[124:127]
	v_mfma_f32_16x16x32_bf16 v[120:123], v[160:163], v[168:171], v[120:123]
	v_mfma_f32_16x16x32_bf16 v[108:111], v[144:147], v[180:183], v[108:111]
	v_mfma_f32_16x16x32_bf16 v[104:107], v[160:163], v[180:183], v[104:107]
	v_mfma_f32_16x16x32_bf16 v[92:95], v[144:147], v[188:191], v[92:95]
	v_mfma_f32_16x16x32_bf16 v[88:91], v[160:163], v[188:191], v[88:91]
	v_mfma_f32_16x16x32_bf16 v[76:79], v[144:147], v[196:199], v[76:79]
	v_mfma_f32_16x16x32_bf16 v[72:75], v[160:163], v[196:199], v[72:75]
	v_mfma_f32_16x16x32_bf16 v[124:127], v[148:151], v[172:175], v[124:127]
	v_mfma_f32_16x16x32_bf16 v[120:123], v[164:167], v[172:175], v[120:123]
	v_mfma_f32_16x16x32_bf16 v[108:111], v[148:151], v[184:187], v[108:111]
	v_mfma_f32_16x16x32_bf16 v[104:107], v[164:167], v[184:187], v[104:107]
	v_mfma_f32_16x16x32_bf16 v[92:95], v[148:151], v[192:195], v[92:95]
	v_mfma_f32_16x16x32_bf16 v[88:91], v[164:167], v[192:195], v[88:91]
	v_mfma_f32_16x16x32_bf16 v[76:79], v[148:151], v[200:203], v[76:79]
	v_mfma_f32_16x16x32_bf16 v[72:75], v[164:167], v[200:203], v[72:75]
	s_setprio 0
	s_barrier
	s_add_i32 s36, 0, 0x1c000
	s_add_i32 s37, s71, s39
	v_add_u32_e32 v159, s36, v153
	v_lshl_add_u64 v[176:177], v[176:177], 0, s[6:7]
	s_mov_b32 m0, s37
	ds_read_b128 v[204:207], v159
	ds_read_b128 v[208:211], v159 offset:1024
	ds_read_b128 v[212:215], v159 offset:2048
	ds_read_b128 v[216:219], v159 offset:3072
	global_load_lds_dwordx4 v[176:177], off
	v_lshl_add_u64 v[176:177], v[220:221], 0, s[6:7]
	s_add_i32 m0, s37, 0x2000
	s_nop 0
	global_load_lds_dwordx4 v[176:177], off
	s_barrier
	s_waitcnt lgkmcnt(0)
	s_setprio 1
	s_waitcnt lgkmcnt(0)
	v_mfma_f32_16x16x32_bf16 v[116:119], v[204:207], v[168:171], v[116:119]
	v_mfma_f32_16x16x32_bf16 v[112:115], v[212:215], v[168:171], v[112:115]
	v_mfma_f32_16x16x32_bf16 v[100:103], v[204:207], v[180:183], v[100:103]
	v_mfma_f32_16x16x32_bf16 v[96:99], v[212:215], v[180:183], v[96:99]
	v_mfma_f32_16x16x32_bf16 v[84:87], v[204:207], v[188:191], v[84:87]
	v_mfma_f32_16x16x32_bf16 v[80:83], v[212:215], v[188:191], v[80:83]
	v_mfma_f32_16x16x32_bf16 v[68:71], v[204:207], v[196:199], v[68:71]
	v_mfma_f32_16x16x32_bf16 v[64:67], v[212:215], v[196:199], v[64:67]
	v_mfma_f32_16x16x32_bf16 v[116:119], v[208:211], v[172:175], v[116:119]
	v_mfma_f32_16x16x32_bf16 v[112:115], v[216:219], v[172:175], v[112:115]
	v_mfma_f32_16x16x32_bf16 v[100:103], v[208:211], v[184:187], v[100:103]
	v_mfma_f32_16x16x32_bf16 v[96:99], v[216:219], v[184:187], v[96:99]
	v_mfma_f32_16x16x32_bf16 v[84:87], v[208:211], v[192:195], v[84:87]
	v_mfma_f32_16x16x32_bf16 v[80:83], v[216:219], v[192:195], v[80:83]
	v_mfma_f32_16x16x32_bf16 v[68:71], v[208:211], v[200:203], v[68:71]
	v_mfma_f32_16x16x32_bf16 v[64:67], v[216:219], v[200:203], v[64:67]
	s_setprio 0
	s_mov_b32 m0, s44
	v_lshl_add_u64 v[176:177], v[222:223], 0, s[6:7]
	s_barrier
	ds_read_b128 v[168:171], v156 offset:49152
	ds_read_b128 v[172:175], v156 offset:50176
	ds_read_b128 v[180:183], v156 offset:51200
	ds_read_b128 v[184:187], v156 offset:52224
	ds_read_b128 v[188:191], v156 offset:53248
	ds_read_b128 v[192:195], v156 offset:54272
	ds_read_b128 v[196:199], v156 offset:55296
	ds_read_b128 v[200:203], v156 offset:56320
	global_load_lds_dwordx4 v[176:177], off
	v_lshl_add_u64 v[176:177], v[224:225], 0, s[6:7]
	s_mov_b32 m0, s45
	s_nop 0
	global_load_lds_dwordx4 v[176:177], off
	s_barrier
; DI unsigned pk2(float a, float b) { f32x2 v = {a, b}; hbf2 r = __builtin_convertvector(v, hbf2); return __builtin_bit_cast(unsigned, r); }
; #define PG8_STAGE(bufoff, gbase, voff) do { _Pragma("unroll") for (int _i = 0; _i < 2; ++_i) \
;         __builtin_amdgcn_global_load_lds((const unsigned*)((const char*)(gbase) + (voff)[_i]), (LAS unsigned*)(lds + (bufoff) + ldsw + _i * 8192), 16, 0, 0); } while (0)
; #define PG8_WAIT_V(n) asm volatile("s_waitcnt vmcnt(" #n ")" ::: "memory")
; template <class Epi>
; __device__ __forceinline__ void gemm_phase(LAS unsigned char* lds, const Gemm g, const StaticOrder& S, const Epi& E) {
;     ...
;             PG8_WAIT_V(6); PG8_BAR; PG8_MMA(1, 1, At, B1); PG8_BAR;
;             PG8_LDB(B0, 1, 0); PG8_SCHED; PG8_LDA(At, 1, 0); PG8_STAGE(PG8_SA(0, 1), a2 + hstep, voffA);
;             PG8_WAIT_L(8); PG8_BAR; PG8_WAIT_L(0); PG8_MMA(0, 0, At, B0); PG8_BAR; PG8_SCHED;
;             PG8_LDB(B1, 1, 1); PG8_STAGE(PG8_SB(1, 0), b3, voffB);
;             PG8_BAR; PG8_WAIT_L(0); PG8_MMA(0, 1, At, B1); PG8_BAR;
;             PG8_LDA(At, 1, 1); PG8_STAGE(PG8_SA(1, 0), a3, voffA);
;             PG8_BAR; PG8_WAIT_L(0); PG8_MMA(1, 0, At, B0); PG8_BAR; PG8_SCHED;
;             PG8_STAGE(PG8_SB(1, 1), b3 + hstep, voffB);
;             PG8_WAIT_V(6); PG8_BAR; PG8_MMA(1, 1, At, B1); PG8_BAR;
;     DI void operator()(const f32x4 (&acc)[2][2][4][2], const Unit& u, int wr, int wc, int fr, int fq) const {
;         const int row0 = u.pm * 256 + wr * 64 + fr, col0 = u.pn * 256 + wc * 32 + 8 * fq;
; #pragma unroll
;         for (int ai = 0; ai < 2; ++ai)
; #pragma unroll
;             for (int m = 0; m < 4; ++m) {
;                 const int r = row0 + ai * 128 + m * 16;
;                 const float rstd = rsqrtf(ss[r] * (1.0f / 1024.0f) + EPS);
;                 bf16_t* rowp = HID + (size_t)r * 4096 + col0;
; #pragma unroll
;                 for (int bj = 0; bj < 2; ++bj) {
;                     f32x4 v0 = acc[ai][bj][m][0] * rstd, v1 = acc[ai][bj][m][1] * rstd;
; #pragma unroll
;                     for (int j = 0; j < 4; ++j) { float a = fmaxf(v0[j], 0.f), b = fmaxf(v1[j], 0.f); v0[j] = a * a; v1[j] = b * b; }
;                     u32x4 w; w.x = pk2(v0[0], v0[1]); w.y = pk2(v0[2], v0[3]); w.z = pk2(v1[0], v1[1]); w.w = pk2(v1[2], v1[3]);
;                     *(u32x4*)(rowp + bj * 128) = w;
;                 }
	s_waitcnt lgkmcnt(0)
	s_setprio 1
	s_waitcnt lgkmcnt(0)
	v_mfma_f32_16x16x32_bf16 v[60:63], v[144:147], v[168:171], v[60:63]
	v_mfma_f32_16x16x32_bf16 v[56:59], v[160:163], v[168:171], v[56:59]
	v_mfma_f32_16x16x32_bf16 v[44:47], v[144:147], v[180:183], v[44:47]
	v_mfma_f32_16x16x32_bf16 v[40:43], v[160:163], v[180:183], v[40:43]
	v_mfma_f32_16x16x32_bf16 v[28:31], v[144:147], v[188:191], v[28:31]
	v_mfma_f32_16x16x32_bf16 v[24:27], v[160:163], v[188:191], v[24:27]
	v_mfma_f32_16x16x32_bf16 v[12:15], v[144:147], v[196:199], v[12:15]
	v_mfma_f32_16x16x32_bf16 v[8:11], v[160:163], v[196:199], v[8:11]
	v_mfma_f32_16x16x32_bf16 v[60:63], v[148:151], v[172:175], v[60:63]
	v_mfma_f32_16x16x32_bf16 v[56:59], v[164:167], v[172:175], v[56:59]
	v_mfma_f32_16x16x32_bf16 v[44:47], v[148:151], v[184:187], v[44:47]
	v_mfma_f32_16x16x32_bf16 v[40:43], v[164:167], v[184:187], v[40:43]
	v_mfma_f32_16x16x32_bf16 v[28:31], v[148:151], v[192:195], v[28:31]
	v_mfma_f32_16x16x32_bf16 v[24:27], v[164:167], v[192:195], v[24:27]
	v_mfma_f32_16x16x32_bf16 v[12:15], v[148:151], v[200:203], v[12:15]
	v_mfma_f32_16x16x32_bf16 v[8:11], v[164:167], v[200:203], v[8:11]
	s_setprio 0
	s_barrier
	s_add_u32 s30, s30, 0x40080
	s_addc_u32 s31, s31, 0
	s_add_i32 s36, s36, s39
	v_lshl_add_u64 v[144:145], s[30:31], 0, v[130:131]
	s_mov_b32 m0, s36
	s_nop 0
	global_load_lds_dwordx4 v[144:145], off
	v_lshl_add_u64 v[144:145], s[30:31], 0, v[134:135]
	s_add_i32 m0, s36, 0x2000
	s_nop 0
	global_load_lds_dwordx4 v[144:145], off
	s_waitcnt vmcnt(6)
	s_barrier
	s_setprio 1
	v_mfma_f32_16x16x32_bf16 v[52:55], v[204:207], v[168:171], v[52:55]
	v_mfma_f32_16x16x32_bf16 v[48:51], v[212:215], v[168:171], v[48:51]
	v_mfma_f32_16x16x32_bf16 v[36:39], v[204:207], v[180:183], v[36:39]
	v_mfma_f32_16x16x32_bf16 v[32:35], v[212:215], v[180:183], v[32:35]
	v_mfma_f32_16x16x32_bf16 v[20:23], v[204:207], v[188:191], v[20:23]
	v_mfma_f32_16x16x32_bf16 v[16:19], v[212:215], v[188:191], v[16:19]
	v_mfma_f32_16x16x32_bf16 v[4:7], v[204:207], v[196:199], v[4:7]
	v_mfma_f32_16x16x32_bf16 v[0:3], v[212:215], v[196:199], v[0:3]
	v_mfma_f32_16x16x32_bf16 v[52:55], v[208:211], v[172:175], v[52:55]
	v_mfma_f32_16x16x32_bf16 v[48:51], v[216:219], v[172:175], v[48:51]
	v_mfma_f32_16x16x32_bf16 v[36:39], v[208:211], v[184:187], v[36:39]
	v_mfma_f32_16x16x32_bf16 v[32:35], v[216:219], v[184:187], v[32:35]
	v_mfma_f32_16x16x32_bf16 v[20:23], v[208:211], v[192:195], v[20:23]
	v_mfma_f32_16x16x32_bf16 v[16:19], v[216:219], v[192:195], v[16:19]
	v_mfma_f32_16x16x32_bf16 v[4:7], v[208:211], v[200:203], v[4:7]
	v_mfma_f32_16x16x32_bf16 v[0:3], v[216:219], v[200:203], v[0:3]
	s_setprio 0
	s_add_i32 s70, s70, 2
	s_add_u32 s0, s0, 0x100
	s_addc_u32 s1, s1, 0
	s_add_u32 s62, s62, 0x100
	s_addc_u32 s63, s63, 0
	s_cmp_gt_u32 s70, 13
	s_barrier
	s_cbranch_scc0 .LBB0_1464
	v_lshl_add_u32 v148, s28, 8, v152
	v_ashrrev_i32_e32 v149, 31, v148
	v_lshl_add_u64 v[144:145], v[148:149], 2, s[10:11]
	global_load_dword v159, v[144:145], off
	global_load_dword v209, v[144:145], off offset:64
	global_load_dword v210, v[144:145], off offset:128
	global_load_dword v211, v[144:145], off offset:192
	global_load_dword v212, v[144:145], off offset:512
	global_load_dword v213, v[144:145], off offset:576
	global_load_dword v214, v[144:145], off offset:640
	global_load_dword v215, v[144:145], off offset:704
	v_lshl_or_b32 v146, s59, 8, v154
	v_ashrrev_i32_e32 v147, 31, v146
	v_lshlrev_b64 v[150:151], 1, v[146:147]
	v_lshlrev_b64 v[162:163], 13, v[148:149]
	v_or_b32_e32 v160, 16, v148
	v_ashrrev_i32_e32 v161, 31, v160
	s_mov_b32 s59, s20
	s_mov_b32 s28, s22
	s_mov_b64 s[30:31], s[26:27]
	s_mov_b64 s[36:37], s[24:25]
	s_waitcnt vmcnt(0)
	v_fmamk_f32 v146, v159, 0x3a800000, v158
	v_mul_f32_e32 v147, 0x4b800000, v146
	v_cmp_gt_f32_e32 vcc, s50, v146
	s_nop 1
	v_cndmask_b32_e32 v146, v146, v147, vcc
	v_rsq_f32_e32 v149, v146
	v_lshl_add_u64 v[146:147], s[34:35], 0, v[162:163]
	v_lshl_add_u64 v[146:147], v[146:147], 0, v[150:151]
	v_lshl_add_u64 v[162:163], v[160:161], 2, s[10:11]
	v_mul_f32_e32 v159, 0x45800000, v149
	v_cndmask_b32_e32 v164, v149, v159, vcc
	v_pk_mul_f32 v[126:127], v[126:127], v[164:165] op_sel_hi:[1,0]
	v_pk_mul_f32 v[124:125], v[124:125], v[164:165] op_sel_hi:[1,0]
	v_pk_mul_f32 v[122:123], v[122:123], v[164:165] op_sel_hi:[1,0]
	v_pk_mul_f32 v[120:121], v[120:121], v[164:165] op_sel_hi:[1,0]
	v_pk_mul_f32 v[118:119], v[118:119], v[164:165] op_sel_hi:[1,0]
	v_pk_mul_f32 v[116:117], v[116:117], v[164:165] op_sel_hi:[1,0]
	v_pk_mul_f32 v[114:115], v[114:115], v[164:165] op_sel_hi:[1,0]
	v_pk_mul_f32 v[112:113], v[112:113], v[164:165] op_sel_hi:[1,0]
	v_max_f32_e32 v124, 0, v124
	v_max_f32_e32 v120, 0, v120
	v_max_f32_e32 v125, 0, v125
	v_max_f32_e32 v121, 0, v121
	v_max_f32_e32 v126, 0, v126
	v_max_f32_e32 v122, 0, v122
	v_max_f32_e32 v127, 0, v127
	v_max_f32_e32 v123, 0, v123
	v_max_f32_e32 v116, 0, v116
	v_max_f32_e32 v112, 0, v112
	v_max_f32_e32 v117, 0, v117
	v_max_f32_e32 v113, 0, v113
	v_max_f32_e32 v118, 0, v118
	v_max_f32_e32 v114, 0, v114
	v_max_f32_e32 v119, 0, v119
	v_max_f32_e32 v115, 0, v115
	v_pk_mul_f32 v[124:125], v[124:125], v[124:125]
	v_pk_mul_f32 v[120:121], v[120:121], v[120:121]
	v_pk_mul_f32 v[126:127], v[126:127], v[126:127]
	v_pk_mul_f32 v[122:123], v[122:123], v[122:123]
	v_pk_mul_f32 v[116:117], v[116:117], v[116:117]
	v_pk_mul_f32 v[164:165], v[112:113], v[112:113]
	v_pk_mul_f32 v[118:119], v[118:119], v[118:119]
	v_pk_mul_f32 v[166:167], v[114:115], v[114:115]
	v_cvt_pk_bf16_f32 v112, v124, v125
	v_cvt_pk_bf16_f32 v113, v126, v127
	v_cvt_pk_bf16_f32 v114, v120, v121
	v_cvt_pk_bf16_f32 v115, v122, v123
; DI unsigned pk2(float a, float b) { f32x2 v = {a, b}; hbf2 r = __builtin_convertvector(v, hbf2); return __builtin_bit_cast(unsigned, r); }
;     DI void operator()(const f32x4 (&acc)[2][2][4][2], const Unit& u, int wr, int wc, int fr, int fq) const {
;         const int row0 = u.pm * 256 + wr * 64 + fr, col0 = u.pn * 256 + wc * 32 + 8 * fq;
; #pragma unroll
;         for (int ai = 0; ai < 2; ++ai)
; #pragma unroll
;             for (int m = 0; m < 4; ++m) {
;                 const int r = row0 + ai * 128 + m * 16;
;                 const float rstd = rsqrtf(ss[r] * (1.0f / 1024.0f) + EPS);
;                 bf16_t* rowp = HID + (size_t)r * 4096 + col0;
; #pragma unroll
;                 for (int bj = 0; bj < 2; ++bj) {
;                     f32x4 v0 = acc[ai][bj][m][0] * rstd, v1 = acc[ai][bj][m][1] * rstd;
; #pragma unroll
;                     for (int j = 0; j < 4; ++j) { float a = fmaxf(v0[j], 0.f), b = fmaxf(v1[j], 0.f); v0[j] = a * a; v1[j] = b * b; }
;                     u32x4 w; w.x = pk2(v0[0], v0[1]); w.y = pk2(v0[2], v0[3]); w.z = pk2(v1[0], v1[1]); w.w = pk2(v1[2], v1[3]);
;                     *(u32x4*)(rowp + bj * 128) = w;
;                 }
	v_cvt_pk_bf16_f32 v116, v116, v117
	v_cvt_pk_bf16_f32 v117, v118, v119
	v_cvt_pk_bf16_f32 v118, v164, v165
	v_cvt_pk_bf16_f32 v119, v166, v167
	global_store_dwordx4 v[146:147], v[112:115], off
	global_store_dwordx4 v[146:147], v[116:119], off offset:256
	s_nop 0
	v_lshlrev_b64 v[114:115], 13, v[160:161]
	v_or_b32_e32 v112, 32, v148
	v_lshl_add_u64 v[114:115], s[34:35], 0, v[114:115]
	v_ashrrev_i32_e32 v113, 31, v112
	v_lshl_add_u64 v[114:115], v[114:115], 0, v[150:151]
	s_nop 1
	v_mov_b32_e32 v116, v209
	v_fmamk_f32 v116, v116, 0x3a800000, v158
	v_mul_f32_e32 v117, 0x4b800000, v116
	v_cmp_gt_f32_e32 vcc, s50, v116
	s_nop 1
	v_cndmask_b32_e32 v116, v116, v117, vcc
	v_rsq_f32_e32 v118, v116
	v_lshl_add_u64 v[116:117], v[112:113], 2, s[10:11]
	v_mul_f32_e32 v119, 0x45800000, v118
	v_cndmask_b32_e32 v118, v118, v119, vcc
	v_pk_mul_f32 v[110:111], v[110:111], v[118:119] op_sel_hi:[1,0]
	v_pk_mul_f32 v[108:109], v[108:109], v[118:119] op_sel_hi:[1,0]
	v_pk_mul_f32 v[106:107], v[106:107], v[118:119] op_sel_hi:[1,0]
	v_pk_mul_f32 v[104:105], v[104:105], v[118:119] op_sel_hi:[1,0]
	v_pk_mul_f32 v[102:103], v[102:103], v[118:119] op_sel_hi:[1,0]
	v_pk_mul_f32 v[100:101], v[100:101], v[118:119] op_sel_hi:[1,0]
	v_pk_mul_f32 v[98:99], v[98:99], v[118:119] op_sel_hi:[1,0]
	v_pk_mul_f32 v[96:97], v[96:97], v[118:119] op_sel_hi:[1,0]
	v_max_f32_e32 v108, 0, v108
	v_max_f32_e32 v104, 0, v104
	v_max_f32_e32 v109, 0, v109
	v_max_f32_e32 v105, 0, v105
	v_max_f32_e32 v110, 0, v110
	v_max_f32_e32 v106, 0, v106
	v_max_f32_e32 v111, 0, v111
	v_max_f32_e32 v107, 0, v107
	v_max_f32_e32 v100, 0, v100
	v_max_f32_e32 v96, 0, v96
	v_max_f32_e32 v101, 0, v101
	v_max_f32_e32 v97, 0, v97
	v_max_f32_e32 v102, 0, v102
	v_max_f32_e32 v98, 0, v98
	v_max_f32_e32 v103, 0, v103
	v_max_f32_e32 v99, 0, v99
	v_pk_mul_f32 v[108:109], v[108:109], v[108:109]
	v_pk_mul_f32 v[104:105], v[104:105], v[104:105]
	v_pk_mul_f32 v[110:111], v[110:111], v[110:111]
	v_pk_mul_f32 v[106:107], v[106:107], v[106:107]
	v_pk_mul_f32 v[100:101], v[100:101], v[100:101]
	v_pk_mul_f32 v[118:119], v[96:97], v[96:97]
	v_pk_mul_f32 v[102:103], v[102:103], v[102:103]
	v_pk_mul_f32 v[120:121], v[98:99], v[98:99]
	v_cvt_pk_bf16_f32 v96, v108, v109
	v_cvt_pk_bf16_f32 v97, v110, v111
	v_cvt_pk_bf16_f32 v98, v104, v105
	v_cvt_pk_bf16_f32 v99, v106, v107
	v_cvt_pk_bf16_f32 v100, v100, v101
	v_cvt_pk_bf16_f32 v101, v102, v103
	v_cvt_pk_bf16_f32 v102, v118, v119
	v_cvt_pk_bf16_f32 v103, v120, v121
	global_store_dwordx4 v[114:115], v[96:99], off
	global_store_dwordx4 v[114:115], v[100:103], off offset:256
	s_nop 0
	v_lshlrev_b64 v[98:99], 13, v[112:113]
	v_or_b32_e32 v96, 48, v148
	v_lshl_add_u64 v[98:99], s[34:35], 0, v[98:99]
	v_ashrrev_i32_e32 v97, 31, v96
	v_lshl_add_u64 v[98:99], v[98:99], 0, v[150:151]
	s_nop 1
	v_mov_b32_e32 v100, v210
	v_fmamk_f32 v100, v100, 0x3a800000, v158
	v_mul_f32_e32 v101, 0x4b800000, v100
	v_cmp_gt_f32_e32 vcc, s50, v100
	s_nop 1
	v_cndmask_b32_e32 v100, v100, v101, vcc
	v_rsq_f32_e32 v102, v100
	v_lshl_add_u64 v[100:101], v[96:97], 2, s[10:11]
	v_mul_f32_e32 v103, 0x45800000, v102
	v_cndmask_b32_e32 v102, v102, v103, vcc
	v_pk_mul_f32 v[94:95], v[94:95], v[102:103] op_sel_hi:[1,0]
	v_pk_mul_f32 v[92:93], v[92:93], v[102:103] op_sel_hi:[1,0]
	v_pk_mul_f32 v[90:91], v[90:91], v[102:103] op_sel_hi:[1,0]
	v_pk_mul_f32 v[88:89], v[88:89], v[102:103] op_sel_hi:[1,0]
	v_pk_mul_f32 v[86:87], v[86:87], v[102:103] op_sel_hi:[1,0]
	v_pk_mul_f32 v[84:85], v[84:85], v[102:103] op_sel_hi:[1,0]
	v_pk_mul_f32 v[82:83], v[82:83], v[102:103] op_sel_hi:[1,0]
	v_pk_mul_f32 v[80:81], v[80:81], v[102:103] op_sel_hi:[1,0]
	v_max_f32_e32 v92, 0, v92
	v_max_f32_e32 v88, 0, v88
	v_max_f32_e32 v93, 0, v93
	v_max_f32_e32 v89, 0, v89
	v_max_f32_e32 v94, 0, v94
	v_max_f32_e32 v90, 0, v90
	v_max_f32_e32 v95, 0, v95
	v_max_f32_e32 v91, 0, v91
	v_max_f32_e32 v84, 0, v84
	v_max_f32_e32 v80, 0, v80
	v_max_f32_e32 v85, 0, v85
	v_max_f32_e32 v81, 0, v81
	v_max_f32_e32 v86, 0, v86
	v_max_f32_e32 v82, 0, v82
	v_max_f32_e32 v87, 0, v87
	v_max_f32_e32 v83, 0, v83
	v_pk_mul_f32 v[92:93], v[92:93], v[92:93]
	v_pk_mul_f32 v[88:89], v[88:89], v[88:89]
	v_pk_mul_f32 v[94:95], v[94:95], v[94:95]
	v_pk_mul_f32 v[90:91], v[90:91], v[90:91]
	v_pk_mul_f32 v[84:85], v[84:85], v[84:85]
	v_pk_mul_f32 v[102:103], v[80:81], v[80:81]
	v_pk_mul_f32 v[86:87], v[86:87], v[86:87]
	v_pk_mul_f32 v[104:105], v[82:83], v[82:83]
	v_cvt_pk_bf16_f32 v80, v92, v93
	v_cvt_pk_bf16_f32 v81, v94, v95
	v_cvt_pk_bf16_f32 v82, v88, v89
	v_cvt_pk_bf16_f32 v83, v90, v91
	v_cvt_pk_bf16_f32 v84, v84, v85
	v_cvt_pk_bf16_f32 v85, v86, v87
	v_cvt_pk_bf16_f32 v86, v102, v103
	v_cvt_pk_bf16_f32 v87, v104, v105
	global_store_dwordx4 v[98:99], v[80:83], off
	global_store_dwordx4 v[98:99], v[84:87], off offset:256
	s_nop 0
	s_nop 1
	v_mov_b32_e32 v80, v211
	v_fmamk_f32 v80, v80, 0x3a800000, v158
	v_mul_f32_e32 v81, 0x4b800000, v80
	v_cmp_gt_f32_e32 vcc, s50, v80
	s_nop 1
	v_cndmask_b32_e32 v80, v80, v81, vcc
	v_rsq_f32_e32 v82, v80
	v_lshlrev_b64 v[80:81], 13, v[96:97]
	v_lshl_add_u64 v[80:81], s[34:35], 0, v[80:81]
	v_lshl_add_u64 v[80:81], v[80:81], 0, v[150:151]
	v_mul_f32_e32 v83, 0x45800000, v82
	v_cndmask_b32_e32 v82, v82, v83, vcc
	v_pk_mul_f32 v[78:79], v[78:79], v[82:83] op_sel_hi:[1,0]
	v_pk_mul_f32 v[76:77], v[76:77], v[82:83] op_sel_hi:[1,0]
	v_pk_mul_f32 v[74:75], v[74:75], v[82:83] op_sel_hi:[1,0]
	v_pk_mul_f32 v[72:73], v[72:73], v[82:83] op_sel_hi:[1,0]
	v_pk_mul_f32 v[70:71], v[70:71], v[82:83] op_sel_hi:[1,0]
	v_pk_mul_f32 v[68:69], v[68:69], v[82:83] op_sel_hi:[1,0]
	v_pk_mul_f32 v[66:67], v[66:67], v[82:83] op_sel_hi:[1,0]
; DI unsigned pk2(float a, float b) { f32x2 v = {a, b}; hbf2 r = __builtin_convertvector(v, hbf2); return __builtin_bit_cast(unsigned, r); }
;     DI void operator()(const f32x4 (&acc)[2][2][4][2], const Unit& u, int wr, int wc, int fr, int fq) const {
;         const int row0 = u.pm * 256 + wr * 64 + fr, col0 = u.pn * 256 + wc * 32 + 8 * fq;
; #pragma unroll
;         for (int ai = 0; ai < 2; ++ai)
; #pragma unroll
;             for (int m = 0; m < 4; ++m) {
;                 const int r = row0 + ai * 128 + m * 16;
;                 const float rstd = rsqrtf(ss[r] * (1.0f / 1024.0f) + EPS);
;                 bf16_t* rowp = HID + (size_t)r * 4096 + col0;
; #pragma unroll
;                 for (int bj = 0; bj < 2; ++bj) {
;                     f32x4 v0 = acc[ai][bj][m][0] * rstd, v1 = acc[ai][bj][m][1] * rstd;
; #pragma unroll
;                     for (int j = 0; j < 4; ++j) { float a = fmaxf(v0[j], 0.f), b = fmaxf(v1[j], 0.f); v0[j] = a * a; v1[j] = b * b; }
;                     u32x4 w; w.x = pk2(v0[0], v0[1]); w.y = pk2(v0[2], v0[3]); w.z = pk2(v1[0], v1[1]); w.w = pk2(v1[2], v1[3]);
;                     *(u32x4*)(rowp + bj * 128) = w;
;                 }
	v_pk_mul_f32 v[64:65], v[64:65], v[82:83] op_sel_hi:[1,0]
	v_max_f32_e32 v76, 0, v76
	v_max_f32_e32 v72, 0, v72
	v_max_f32_e32 v77, 0, v77
	v_max_f32_e32 v73, 0, v73
	v_max_f32_e32 v78, 0, v78
	v_max_f32_e32 v74, 0, v74
	v_max_f32_e32 v79, 0, v79
	v_max_f32_e32 v75, 0, v75
	v_max_f32_e32 v68, 0, v68
	v_max_f32_e32 v64, 0, v64
	v_max_f32_e32 v69, 0, v69
	v_max_f32_e32 v65, 0, v65
	v_max_f32_e32 v70, 0, v70
	v_max_f32_e32 v66, 0, v66
	v_max_f32_e32 v71, 0, v71
	v_max_f32_e32 v67, 0, v67
	v_pk_mul_f32 v[76:77], v[76:77], v[76:77]
	v_pk_mul_f32 v[72:73], v[72:73], v[72:73]
	v_pk_mul_f32 v[78:79], v[78:79], v[78:79]
	v_pk_mul_f32 v[74:75], v[74:75], v[74:75]
	v_pk_mul_f32 v[68:69], v[68:69], v[68:69]
	v_pk_mul_f32 v[82:83], v[64:65], v[64:65]
	v_pk_mul_f32 v[70:71], v[70:71], v[70:71]
	v_pk_mul_f32 v[84:85], v[66:67], v[66:67]
	v_cvt_pk_bf16_f32 v64, v76, v77
	v_cvt_pk_bf16_f32 v65, v78, v79
	v_cvt_pk_bf16_f32 v66, v72, v73
	v_cvt_pk_bf16_f32 v67, v74, v75
	v_cvt_pk_bf16_f32 v68, v68, v69
	v_cvt_pk_bf16_f32 v69, v70, v71
	v_cvt_pk_bf16_f32 v70, v82, v83
	v_cvt_pk_bf16_f32 v71, v84, v85
	global_store_dwordx4 v[80:81], v[64:67], off
	global_store_dwordx4 v[80:81], v[68:71], off offset:256
	s_nop 0
	v_lshl_add_u64 v[64:65], v[146:147], 0, s[8:9]
	s_nop 1
	v_mov_b32_e32 v66, v212
	v_fmamk_f32 v66, v66, 0x3a800000, v158
	v_mul_f32_e32 v67, 0x4b800000, v66
	v_cmp_gt_f32_e32 vcc, s50, v66
	s_nop 1
	v_cndmask_b32_e32 v66, v66, v67, vcc
	v_rsq_f32_e32 v68, v66
	v_add_co_u32_e64 v66, s[0:1], s51, v146
	v_mul_f32_e32 v69, 0x45800000, v68
	v_cndmask_b32_e32 v68, v68, v69, vcc
	v_pk_mul_f32 v[62:63], v[62:63], v[68:69] op_sel_hi:[1,0]
	v_pk_mul_f32 v[60:61], v[60:61], v[68:69] op_sel_hi:[1,0]
	v_pk_mul_f32 v[58:59], v[58:59], v[68:69] op_sel_hi:[1,0]
	v_pk_mul_f32 v[56:57], v[56:57], v[68:69] op_sel_hi:[1,0]
	v_pk_mul_f32 v[54:55], v[54:55], v[68:69] op_sel_hi:[1,0]
	v_pk_mul_f32 v[52:53], v[52:53], v[68:69] op_sel_hi:[1,0]
	v_pk_mul_f32 v[50:51], v[50:51], v[68:69] op_sel_hi:[1,0]
	v_pk_mul_f32 v[48:49], v[48:49], v[68:69] op_sel_hi:[1,0]
	v_max_f32_e32 v60, 0, v60
	v_max_f32_e32 v56, 0, v56
	v_max_f32_e32 v61, 0, v61
	v_max_f32_e32 v57, 0, v57
	v_max_f32_e32 v62, 0, v62
	v_max_f32_e32 v58, 0, v58
	v_max_f32_e32 v63, 0, v63
	v_max_f32_e32 v59, 0, v59
	v_max_f32_e32 v52, 0, v52
	v_max_f32_e32 v48, 0, v48
	v_max_f32_e32 v53, 0, v53
	v_max_f32_e32 v49, 0, v49
	v_max_f32_e32 v54, 0, v54
	v_max_f32_e32 v50, 0, v50
	v_max_f32_e32 v55, 0, v55
	v_max_f32_e32 v51, 0, v51
	v_pk_mul_f32 v[60:61], v[60:61], v[60:61]
	v_pk_mul_f32 v[56:57], v[56:57], v[56:57]
	v_pk_mul_f32 v[62:63], v[62:63], v[62:63]
	v_pk_mul_f32 v[58:59], v[58:59], v[58:59]
	v_addc_co_u32_e64 v67, s[0:1], 0, v147, s[0:1]
	v_pk_mul_f32 v[52:53], v[52:53], v[52:53]
	v_pk_mul_f32 v[68:69], v[48:49], v[48:49]
	v_pk_mul_f32 v[54:55], v[54:55], v[54:55]
	v_pk_mul_f32 v[70:71], v[50:51], v[50:51]
	v_cvt_pk_bf16_f32 v48, v60, v61
	v_cvt_pk_bf16_f32 v49, v62, v63
	v_cvt_pk_bf16_f32 v50, v56, v57
	v_cvt_pk_bf16_f32 v51, v58, v59
	v_cvt_pk_bf16_f32 v52, v52, v53
	v_cvt_pk_bf16_f32 v53, v54, v55
	v_cvt_pk_bf16_f32 v54, v68, v69
	v_cvt_pk_bf16_f32 v55, v70, v71
	global_store_dwordx4 v[66:67], v[48:51], off
	global_store_dwordx4 v[64:65], v[52:55], off offset:256
	s_nop 0
	v_lshl_add_u64 v[48:49], v[146:147], 0, s[12:13]
	s_nop 1
	v_mov_b32_e32 v50, v213
	v_fmamk_f32 v50, v50, 0x3a800000, v158
	v_mul_f32_e32 v51, 0x4b800000, v50
	v_cmp_gt_f32_e32 vcc, s50, v50
	s_nop 1
	v_cndmask_b32_e32 v50, v50, v51, vcc
	v_rsq_f32_e32 v52, v50
	v_add_co_u32_e64 v50, s[0:1], s56, v146
	v_mul_f32_e32 v53, 0x45800000, v52
	v_cndmask_b32_e32 v52, v52, v53, vcc
	v_pk_mul_f32 v[46:47], v[46:47], v[52:53] op_sel_hi:[1,0]
	v_pk_mul_f32 v[44:45], v[44:45], v[52:53] op_sel_hi:[1,0]
	v_pk_mul_f32 v[42:43], v[42:43], v[52:53] op_sel_hi:[1,0]
	v_pk_mul_f32 v[40:41], v[40:41], v[52:53] op_sel_hi:[1,0]
	v_pk_mul_f32 v[38:39], v[38:39], v[52:53] op_sel_hi:[1,0]
	v_pk_mul_f32 v[36:37], v[36:37], v[52:53] op_sel_hi:[1,0]
	v_pk_mul_f32 v[34:35], v[34:35], v[52:53] op_sel_hi:[1,0]
	v_pk_mul_f32 v[32:33], v[32:33], v[52:53] op_sel_hi:[1,0]
	v_max_f32_e32 v44, 0, v44
	v_max_f32_e32 v40, 0, v40
	v_max_f32_e32 v45, 0, v45
	v_max_f32_e32 v41, 0, v41
	v_max_f32_e32 v46, 0, v46
	v_max_f32_e32 v42, 0, v42
	v_max_f32_e32 v47, 0, v47
	v_max_f32_e32 v43, 0, v43
	v_max_f32_e32 v36, 0, v36
	v_max_f32_e32 v32, 0, v32
	v_max_f32_e32 v37, 0, v37
	v_max_f32_e32 v33, 0, v33
	v_max_f32_e32 v38, 0, v38
	v_max_f32_e32 v34, 0, v34
	v_max_f32_e32 v39, 0, v39
	v_max_f32_e32 v35, 0, v35
	v_pk_mul_f32 v[44:45], v[44:45], v[44:45]
	v_pk_mul_f32 v[40:41], v[40:41], v[40:41]
	v_pk_mul_f32 v[46:47], v[46:47], v[46:47]
	v_pk_mul_f32 v[42:43], v[42:43], v[42:43]
; DI unsigned pk2(float a, float b) { f32x2 v = {a, b}; hbf2 r = __builtin_convertvector(v, hbf2); return __builtin_bit_cast(unsigned, r); }
; #define PG8_WAIT_V(n) asm volatile("s_waitcnt vmcnt(" #n ")" ::: "memory")
; #define PG8_BAR __builtin_amdgcn_s_barrier()
; template <class Epi>
; __device__ __forceinline__ void gemm_phase(LAS unsigned char* lds, const Gemm g, const StaticOrder& S, const Epi& E) {
;     ...
;         cur = nxt; cA = nA; cB = nB; ++ui;
;     }
;     PG8_WAIT_V(0);
;     if (wr == 0) PG8_BAR;
;     PG8_BAR;
;     DI void operator()(const f32x4 (&acc)[2][2][4][2], const Unit& u, int wr, int wc, int fr, int fq) const {
;         const int row0 = u.pm * 256 + wr * 64 + fr, col0 = u.pn * 256 + wc * 32 + 8 * fq;
; #pragma unroll
;         for (int ai = 0; ai < 2; ++ai)
; #pragma unroll
;             for (int m = 0; m < 4; ++m) {
;                 const int r = row0 + ai * 128 + m * 16;
;                 const float rstd = rsqrtf(ss[r] * (1.0f / 1024.0f) + EPS);
;                 bf16_t* rowp = HID + (size_t)r * 4096 + col0;
; #pragma unroll
;                 for (int bj = 0; bj < 2; ++bj) {
;                     f32x4 v0 = acc[ai][bj][m][0] * rstd, v1 = acc[ai][bj][m][1] * rstd;
; #pragma unroll
;                     for (int j = 0; j < 4; ++j) { float a = fmaxf(v0[j], 0.f), b = fmaxf(v1[j], 0.f); v0[j] = a * a; v1[j] = b * b; }
;                     u32x4 w; w.x = pk2(v0[0], v0[1]); w.y = pk2(v0[2], v0[3]); w.z = pk2(v1[0], v1[1]); w.w = pk2(v1[2], v1[3]);
;                     *(u32x4*)(rowp + bj * 128) = w;
;                 }
	v_addc_co_u32_e64 v51, s[0:1], 0, v147, s[0:1]
	v_pk_mul_f32 v[36:37], v[36:37], v[36:37]
	v_pk_mul_f32 v[52:53], v[32:33], v[32:33]
	v_pk_mul_f32 v[38:39], v[38:39], v[38:39]
	v_pk_mul_f32 v[54:55], v[34:35], v[34:35]
	v_cvt_pk_bf16_f32 v32, v44, v45
	v_cvt_pk_bf16_f32 v33, v46, v47
	v_cvt_pk_bf16_f32 v34, v40, v41
	v_cvt_pk_bf16_f32 v35, v42, v43
	v_cvt_pk_bf16_f32 v36, v36, v37
	v_cvt_pk_bf16_f32 v37, v38, v39
	v_cvt_pk_bf16_f32 v38, v52, v53
	v_cvt_pk_bf16_f32 v39, v54, v55
	global_store_dwordx4 v[50:51], v[32:35], off
	global_store_dwordx4 v[48:49], v[36:39], off offset:256
	s_nop 0
	v_lshl_add_u64 v[32:33], v[146:147], 0, s[14:15]
	s_nop 1
	v_mov_b32_e32 v34, v214
	v_fmamk_f32 v34, v34, 0x3a800000, v158
	v_mul_f32_e32 v35, 0x4b800000, v34
	v_cmp_gt_f32_e32 vcc, s50, v34
	s_nop 1
	v_cndmask_b32_e32 v34, v34, v35, vcc
	v_rsq_f32_e32 v36, v34
	v_add_co_u32_e64 v34, s[0:1], s57, v146
	v_mul_f32_e32 v37, 0x45800000, v36
	v_cndmask_b32_e32 v36, v36, v37, vcc
	v_pk_mul_f32 v[30:31], v[30:31], v[36:37] op_sel_hi:[1,0]
	v_pk_mul_f32 v[28:29], v[28:29], v[36:37] op_sel_hi:[1,0]
	v_pk_mul_f32 v[26:27], v[26:27], v[36:37] op_sel_hi:[1,0]
	v_pk_mul_f32 v[24:25], v[24:25], v[36:37] op_sel_hi:[1,0]
	v_pk_mul_f32 v[22:23], v[22:23], v[36:37] op_sel_hi:[1,0]
	v_pk_mul_f32 v[20:21], v[20:21], v[36:37] op_sel_hi:[1,0]
	v_pk_mul_f32 v[18:19], v[18:19], v[36:37] op_sel_hi:[1,0]
	v_pk_mul_f32 v[16:17], v[16:17], v[36:37] op_sel_hi:[1,0]
	v_max_f32_e32 v28, 0, v28
	v_max_f32_e32 v24, 0, v24
	v_max_f32_e32 v29, 0, v29
	v_max_f32_e32 v25, 0, v25
	v_max_f32_e32 v30, 0, v30
	v_max_f32_e32 v26, 0, v26
	v_max_f32_e32 v31, 0, v31
	v_max_f32_e32 v27, 0, v27
	v_max_f32_e32 v20, 0, v20
	v_max_f32_e32 v16, 0, v16
	v_max_f32_e32 v21, 0, v21
	v_max_f32_e32 v17, 0, v17
	v_max_f32_e32 v22, 0, v22
	v_max_f32_e32 v18, 0, v18
	v_max_f32_e32 v23, 0, v23
	v_max_f32_e32 v19, 0, v19
	v_pk_mul_f32 v[28:29], v[28:29], v[28:29]
	v_pk_mul_f32 v[24:25], v[24:25], v[24:25]
	v_pk_mul_f32 v[30:31], v[30:31], v[30:31]
	v_pk_mul_f32 v[26:27], v[26:27], v[26:27]
	v_addc_co_u32_e64 v35, s[0:1], 0, v147, s[0:1]
	v_pk_mul_f32 v[20:21], v[20:21], v[20:21]
	v_pk_mul_f32 v[36:37], v[16:17], v[16:17]
	v_pk_mul_f32 v[22:23], v[22:23], v[22:23]
	v_pk_mul_f32 v[38:39], v[18:19], v[18:19]
	v_cvt_pk_bf16_f32 v16, v28, v29
	v_cvt_pk_bf16_f32 v17, v30, v31
	v_cvt_pk_bf16_f32 v18, v24, v25
	v_cvt_pk_bf16_f32 v19, v26, v27
	v_cvt_pk_bf16_f32 v20, v20, v21
	v_cvt_pk_bf16_f32 v21, v22, v23
	v_cvt_pk_bf16_f32 v22, v36, v37
	v_cvt_pk_bf16_f32 v23, v38, v39
	global_store_dwordx4 v[34:35], v[16:19], off
	global_store_dwordx4 v[32:33], v[20:23], off offset:256
	s_nop 0
	s_and_b64 vcc, exec, s[4:5]
	v_lshl_add_u64 v[16:17], v[146:147], 0, s[18:19]
	s_nop 1
	v_mov_b32_e32 v18, v215
	v_fmamk_f32 v18, v18, 0x3a800000, v158
	v_mul_f32_e32 v19, 0x4b800000, v18
	v_cmp_gt_f32_e64 s[0:1], s50, v18
	s_nop 1
	v_cndmask_b32_e64 v18, v18, v19, s[0:1]
	v_rsq_f32_e32 v20, v18
	v_add_co_u32_e64 v18, s[4:5], s58, v146
	v_mul_f32_e32 v21, 0x45800000, v20
	v_cndmask_b32_e64 v20, v20, v21, s[0:1]
	v_pk_mul_f32 v[14:15], v[14:15], v[20:21] op_sel_hi:[1,0]
	v_pk_mul_f32 v[12:13], v[12:13], v[20:21] op_sel_hi:[1,0]
	v_pk_mul_f32 v[10:11], v[10:11], v[20:21] op_sel_hi:[1,0]
	v_pk_mul_f32 v[8:9], v[8:9], v[20:21] op_sel_hi:[1,0]
	v_pk_mul_f32 v[6:7], v[6:7], v[20:21] op_sel_hi:[1,0]
	v_pk_mul_f32 v[4:5], v[4:5], v[20:21] op_sel_hi:[1,0]
	v_pk_mul_f32 v[2:3], v[2:3], v[20:21] op_sel_hi:[1,0]
	v_pk_mul_f32 v[0:1], v[0:1], v[20:21] op_sel_hi:[1,0]
	v_max_f32_e32 v12, 0, v12
	v_max_f32_e32 v8, 0, v8
	v_max_f32_e32 v13, 0, v13
	v_max_f32_e32 v9, 0, v9
	v_max_f32_e32 v14, 0, v14
	v_max_f32_e32 v10, 0, v10
	v_max_f32_e32 v15, 0, v15
	v_max_f32_e32 v11, 0, v11
	v_max_f32_e32 v4, 0, v4
	v_max_f32_e32 v0, 0, v0
	v_max_f32_e32 v5, 0, v5
	v_max_f32_e32 v1, 0, v1
	v_max_f32_e32 v6, 0, v6
	v_max_f32_e32 v2, 0, v2
	v_max_f32_e32 v7, 0, v7
	v_max_f32_e32 v3, 0, v3
	v_pk_mul_f32 v[12:13], v[12:13], v[12:13]
	v_pk_mul_f32 v[8:9], v[8:9], v[8:9]
	v_pk_mul_f32 v[14:15], v[14:15], v[14:15]
	v_pk_mul_f32 v[10:11], v[10:11], v[10:11]
	v_addc_co_u32_e64 v19, s[4:5], 0, v147, s[4:5]
	v_pk_mul_f32 v[4:5], v[4:5], v[4:5]
	v_pk_mul_f32 v[20:21], v[0:1], v[0:1]
	v_pk_mul_f32 v[6:7], v[6:7], v[6:7]
	v_pk_mul_f32 v[22:23], v[2:3], v[2:3]
	v_cvt_pk_bf16_f32 v0, v12, v13
	v_cvt_pk_bf16_f32 v1, v14, v15
	v_cvt_pk_bf16_f32 v2, v8, v9
	v_cvt_pk_bf16_f32 v3, v10, v11
	v_cvt_pk_bf16_f32 v4, v4, v5
	v_cvt_pk_bf16_f32 v5, v6, v7
	v_cvt_pk_bf16_f32 v6, v20, v21
	v_cvt_pk_bf16_f32 v7, v22, v23
	global_store_dwordx4 v[18:19], v[0:3], off
	global_store_dwordx4 v[16:17], v[4:7], off offset:256
	s_cbranch_vccz .LBB0_1457
	s_waitcnt vmcnt(0)
	s_cmpk_gt_u32 s2, 0xff
	s_cbranch_scc1 .LBB0_1468
	s_barrier
